# PG/PH/PF: A(1,1) stage of the next tile's K-step 1 issued at epilogue start; peeled first iteration has no vmcnt wait until after its last MFMA plus one extra s_barrier, so epilogue stores drain under
# speedup vs baseline: 1.0028x; 1.0014x over previous
; #define PG8_STAGE(bufoff, gbase, voff) do { _Pragma("unroll") for (int _i = 0; _i < 2; ++_i) \
;         __builtin_amdgcn_global_load_lds((const unsigned*)((const char*)(gbase) + (voff)[_i]), (LAS unsigned*)(lds + (bufoff) + ldsw + _i * 8192), 16, 0, 0); } while (0)
; #define PG8_LDA(dst, b, h) do { _Pragma("unroll") for (int m = 0; m < 4; ++m) _Pragma("unroll") for (int k = 0; k < 2; ++k) dst[m][k] = *(const LAS bf16x8*)(lds + PG8_SA(b, h) + aoff + m * 2048 + k * 1024); } while (0)
; #define PG8_LDB(dst, b, h) do { _Pragma("unroll") for (int n = 0; n < 2; ++n) _Pragma("unroll") for (int k = 0; k < 2; ++k) dst[n][k] = *(const LAS bf16x8*)(lds + PG8_SB(b, h) + boff + n * 2048 + k * 1024); } while (0)
; #define PG8_MMA(ai, bj, At, Bt) do { __builtin_amdgcn_s_setprio(1); _Pragma("unroll") for (int m = 0; m < 4; ++m) _Pragma("unroll") for (int n = 0; n < 2; ++n) _Pragma("unroll") for (int k = 0; k < 2; ++k) \
;         acc[ai][bj][m][n] = __builtin_amdgcn_mfma_f32_16x16x32_bf16(Bt[n][k], At[m][k], acc[ai][bj][m][n], 0, 0, 0); __builtin_amdgcn_s_setprio(0); } while (0)
; #define PG8_BAR __builtin_amdgcn_s_barrier()
; template <class Epi, class Sched, bool ALIGN_EPI>
; __device__ __forceinline__ void gemm_phase(LAS unsigned char* lds, const Gemm g, const Sched& S, const Epi& E) {
;     ...
;         const bool has_next = S.next(ui + 1, nxt);
;         const char* nA = has_next ? (const char*)g.A + (size_t)nxt.pm * tstepA : cA; const char* nB = has_next ? (const char*)g.Bt + (size_t)nxt.pn * tstepB : cB;
;         for (int t = 0; t < nt; t += 2) {
;             const bool last = (t == nt - 2);
;             const char* a1 = cA + (size_t)(t + 1) * kstep;
;             const char* a2 = last ? nA : cA + (size_t)(t + 2) * kstep; const char* b2 = last ? nB : cB + (size_t)(t + 2) * kstep;
;             const char* a3 = a2 + kstep; const char* b3 = b2 + kstep;
;             PG8_LDB(B0, 0, 0); PG8_LDB(B1, 0, 1); PG8_SCHED; PG8_LDA(At, 0, 0); PG8_STAGE(PG8_SA(1, 1), a1 + hstepA, voffA);
;             PG8_WAIT_V(8); PG8_WAIT_L(0); PG8_BAR; PG8_MMA(0, 0, At, B0); PG8_MMA(0, 1, At, B1); PG8_BAR; PG8_SCHED;
;             PG8_LDA(At, 0, 1); PG8_STAGE(PG8_SB(0, 0), b2, voffB); PG8_STAGE(PG8_SB(0, 1), b2 + hstepB, voffB); PG8_STAGE(PG8_SA(0, 0), a2, voffA);
;             PG8_WAIT_V(8); PG8_WAIT_L(0); PG8_BAR; PG8_MMA(1, 0, At, B0); PG8_MMA(1, 1, At, B1); PG8_BAR; PG8_SCHED;
.LBB0_208:
	s_ashr_i32 s81, s80, 31
	s_lshl_b64 s[54:55], s[80:81], 21
	s_add_u32 s84, s33, s54
	s_addc_u32 s85, s51, s55
	s_and_b64 s[54:55], s[42:43], exec
	s_cselect_b32 s56, s85, s45
	s_cselect_b32 s57, s84, s44
	s_ashr_i32 s63, s62, 31
	s_lshl_b64 s[54:55], s[62:63], 21
	v_readlane_b32 s52, v255, 48
	s_add_u32 s90, s52, s54
	s_addc_u32 s91, s48, s55
	s_and_b64 s[54:55], s[42:43], exec
	s_cselect_b32 s63, s91, s47
	s_cselect_b32 s64, s90, s46
	s_add_u32 s44, s44, 0x100080
	s_addc_u32 s45, s45, 0
	s_add_u32 s65, s46, 0x100
	s_addc_u32 s81, s47, 0
	s_mov_b32 s92, -2
	s_cmp_eq_u32 s9, 1
	s_cbranch_scc1 .Ldc_ph_first
	s_add_u32 s46, s44, 0xfff00080
	s_addc_u32 s47, s45, -1
	s_add_i32 s52, 0, 0x10000
	s_cmp_eq_u32 s92, 60
	s_cselect_b32 s55, s56, s47
	s_cselect_b32 s54, s57, s46
	s_cselect_b32 s47, s63, s81
	s_cselect_b32 s46, s64, s65
	s_add_i32 s53, 0, 0x14000
	v_add_u32_e32 v140, s52, v247
	v_add_u32_e32 v156, s53, v247
	ds_read_b128 v[104:107], v140
	ds_read_b128 v[112:115], v140 offset:1024
	ds_read_b128 v[136:139], v140 offset:2048
	ds_read_b128 v[140:143], v140 offset:3072
	ds_read_b128 v[144:147], v156
	ds_read_b128 v[148:151], v156 offset:1024
	ds_read_b128 v[152:155], v156 offset:2048
	ds_read_b128 v[156:159], v156 offset:3072
	ds_read_b128 v[160:163], v248
	ds_read_b128 v[164:167], v248 offset:1024
	ds_read_b128 v[168:171], v248 offset:2048
	ds_read_b128 v[172:175], v248 offset:3072
	ds_read_b128 v[176:179], v248 offset:4096
	ds_read_b128 v[180:183], v248 offset:5120
	ds_read_b128 v[184:187], v248 offset:6144
	ds_read_b128 v[188:191], v248 offset:7168
	s_waitcnt lgkmcnt(0)
	s_barrier
	s_setprio 1
	s_waitcnt lgkmcnt(0)
	v_mfma_f32_16x16x32_bf16 v[132:135], v[104:107], v[160:163], 0
	v_mfma_f32_16x16x32_bf16 v[128:131], v[136:139], v[160:163], 0
	v_mfma_f32_16x16x32_bf16 v[116:119], v[104:107], v[168:171], 0
	v_mfma_f32_16x16x32_bf16 v[108:111], v[136:139], v[168:171], 0
	v_mfma_f32_16x16x32_bf16 v[96:99], v[104:107], v[176:179], 0
	v_mfma_f32_16x16x32_bf16 v[88:91], v[136:139], v[176:179], 0
	v_mfma_f32_16x16x32_bf16 v[80:83], v[104:107], v[184:187], 0
	v_mfma_f32_16x16x32_bf16 v[72:75], v[136:139], v[184:187], 0
	v_mfma_f32_16x16x32_bf16 v[132:135], v[112:115], v[164:167], v[132:135]
	v_mfma_f32_16x16x32_bf16 v[128:131], v[140:143], v[164:167], v[128:131]
	v_mfma_f32_16x16x32_bf16 v[116:119], v[112:115], v[172:175], v[116:119]
	v_mfma_f32_16x16x32_bf16 v[108:111], v[140:143], v[172:175], v[108:111]
	v_mfma_f32_16x16x32_bf16 v[96:99], v[112:115], v[180:183], v[96:99]
	v_mfma_f32_16x16x32_bf16 v[88:91], v[140:143], v[180:183], v[88:91]
	v_mfma_f32_16x16x32_bf16 v[80:83], v[112:115], v[188:191], v[80:83]
	v_mfma_f32_16x16x32_bf16 v[72:75], v[140:143], v[188:191], v[72:75]
	s_setprio 0
	s_setprio 1
	v_mfma_f32_16x16x32_bf16 v[124:127], v[144:147], v[160:163], 0
	v_mfma_f32_16x16x32_bf16 v[120:123], v[152:155], v[160:163], 0
	v_mfma_f32_16x16x32_bf16 v[100:103], v[144:147], v[168:171], 0
	v_mfma_f32_16x16x32_bf16 v[92:95], v[152:155], v[168:171], 0
	v_mfma_f32_16x16x32_bf16 v[84:87], v[144:147], v[176:179], 0
	v_mfma_f32_16x16x32_bf16 v[76:79], v[152:155], v[176:179], 0
	v_mfma_f32_16x16x32_bf16 v[68:71], v[144:147], v[184:187], 0
	v_mfma_f32_16x16x32_bf16 v[64:67], v[152:155], v[184:187], 0
	v_mfma_f32_16x16x32_bf16 v[124:127], v[148:151], v[164:167], v[124:127]
	v_mfma_f32_16x16x32_bf16 v[120:123], v[156:159], v[164:167], v[120:123]
	v_mfma_f32_16x16x32_bf16 v[100:103], v[148:151], v[172:175], v[100:103]
	v_mfma_f32_16x16x32_bf16 v[92:95], v[156:159], v[172:175], v[92:95]
	v_mfma_f32_16x16x32_bf16 v[84:87], v[148:151], v[180:183], v[84:87]
	v_mfma_f32_16x16x32_bf16 v[76:79], v[156:159], v[180:183], v[76:79]
	v_mfma_f32_16x16x32_bf16 v[68:71], v[148:151], v[188:191], v[68:71]
	v_mfma_f32_16x16x32_bf16 v[64:67], v[156:159], v[188:191], v[64:67]
	s_setprio 0
	s_barrier
	s_add_i32 s52, s52, s50
	v_lshl_add_u64 v[194:195], s[46:47], 0, v[216:217]
	s_mov_b32 m0, s52
	ds_read_b128 v[160:163], v248 offset:16384
	ds_read_b128 v[164:167], v248 offset:17408
	ds_read_b128 v[168:171], v248 offset:18432
	ds_read_b128 v[172:175], v248 offset:19456
	ds_read_b128 v[176:179], v248 offset:20480
	ds_read_b128 v[180:183], v248 offset:21504
	ds_read_b128 v[184:187], v248 offset:22528
	ds_read_b128 v[188:191], v248 offset:23552
	global_load_lds_dwordx4 v[194:195], off
	s_add_i32 m0, s52, 0x2000
	s_add_u32 vcc_lo, s46, 0x100000
	v_lshl_add_u64 v[196:197], s[46:47], 0, v[212:213]
	s_addc_u32 vcc_hi, s47, 0
	s_add_i32 s52, s53, s50
	global_load_lds_dwordx4 v[196:197], off
	v_lshl_add_u64 v[198:199], vcc, 0, v[216:217]
	s_mov_b32 m0, s52
	v_lshl_add_u64 v[200:201], s[54:55], 0, v[214:215]
	global_load_lds_dwordx4 v[198:199], off
	v_lshl_add_u64 v[198:199], vcc, 0, v[212:213]
	s_add_i32 m0, s52, 0x2000
	s_nop 0
	global_load_lds_dwordx4 v[198:199], off
	v_lshl_add_u64 v[198:199], s[54:55], 0, v[218:219]
	s_mov_b32 m0, s49
	s_nop 0
	global_load_lds_dwordx4 v[198:199], off
	s_mov_b32 m0, s67
	s_nop 0
	global_load_lds_dwordx4 v[200:201], off
	s_waitcnt lgkmcnt(0)
	s_barrier
; #define PG8_STAGE(bufoff, gbase, voff) do { _Pragma("unroll") for (int _i = 0; _i < 2; ++_i) \
;         __builtin_amdgcn_global_load_lds((const unsigned*)((const char*)(gbase) + (voff)[_i]), (LAS unsigned*)(lds + (bufoff) + ldsw + _i * 8192), 16, 0, 0); } while (0)
; #define PG8_LDA(dst, b, h) do { _Pragma("unroll") for (int m = 0; m < 4; ++m) _Pragma("unroll") for (int k = 0; k < 2; ++k) dst[m][k] = *(const LAS bf16x8*)(lds + PG8_SA(b, h) + aoff + m * 2048 + k * 1024); } while (0)
; #define PG8_LDB(dst, b, h) do { _Pragma("unroll") for (int n = 0; n < 2; ++n) _Pragma("unroll") for (int k = 0; k < 2; ++k) dst[n][k] = *(const LAS bf16x8*)(lds + PG8_SB(b, h) + boff + n * 2048 + k * 1024); } while (0)
; #define PG8_MMA(ai, bj, At, Bt) do { __builtin_amdgcn_s_setprio(1); _Pragma("unroll") for (int m = 0; m < 4; ++m) _Pragma("unroll") for (int n = 0; n < 2; ++n) _Pragma("unroll") for (int k = 0; k < 2; ++k) \
;         acc[ai][bj][m][n] = __builtin_amdgcn_mfma_f32_16x16x32_bf16(Bt[n][k], At[m][k], acc[ai][bj][m][n], 0, 0, 0); __builtin_amdgcn_s_setprio(0); } while (0)
; #define PG8_WAIT_V(n) asm volatile("s_waitcnt vmcnt(" #n ")" ::: "memory")
; #define PG8_WAIT_L(n) asm volatile("s_waitcnt lgkmcnt(" #n ")" ::: "memory")
; #define PG8_BAR __builtin_amdgcn_s_barrier()
; #define PG8_SCHED __builtin_amdgcn_sched_barrier(0)
; template <class Epi, class Sched, bool ALIGN_EPI>
; __device__ __forceinline__ void gemm_phase(LAS unsigned char* lds, const Gemm g, const Sched& S, const Epi& E) {
;     ...
;             PG8_WAIT_V(8); PG8_WAIT_L(0); PG8_BAR; PG8_MMA(1, 0, At, B0); PG8_MMA(1, 1, At, B1); PG8_BAR; PG8_SCHED;
;             PG8_LDB(B0, 1, 0); PG8_LDB(B1, 1, 1); PG8_SCHED; PG8_LDA(At, 1, 0); PG8_STAGE(PG8_SA(0, 1), a2 + hstepA, voffA);
;             PG8_WAIT_V(8); PG8_WAIT_L(0); PG8_BAR; PG8_MMA(0, 0, At, B0); PG8_MMA(0, 1, At, B1); PG8_BAR; PG8_SCHED;
	s_setprio 1
	s_waitcnt lgkmcnt(0)
	v_mfma_f32_16x16x32_bf16 v[60:63], v[104:107], v[160:163], 0
	v_mfma_f32_16x16x32_bf16 v[56:59], v[136:139], v[160:163], 0
	v_mfma_f32_16x16x32_bf16 v[44:47], v[104:107], v[168:171], 0
	v_mfma_f32_16x16x32_bf16 v[40:43], v[136:139], v[168:171], 0
	v_mfma_f32_16x16x32_bf16 v[32:35], v[104:107], v[176:179], 0
	v_mfma_f32_16x16x32_bf16 v[24:27], v[136:139], v[176:179], 0
	v_mfma_f32_16x16x32_bf16 v[16:19], v[104:107], v[184:187], 0
	v_mfma_f32_16x16x32_bf16 v[8:11], v[136:139], v[184:187], 0
	v_mfma_f32_16x16x32_bf16 v[60:63], v[112:115], v[164:167], v[60:63]
	v_mfma_f32_16x16x32_bf16 v[56:59], v[140:143], v[164:167], v[56:59]
	v_mfma_f32_16x16x32_bf16 v[44:47], v[112:115], v[172:175], v[44:47]
	v_mfma_f32_16x16x32_bf16 v[40:43], v[140:143], v[172:175], v[40:43]
	v_mfma_f32_16x16x32_bf16 v[32:35], v[112:115], v[180:183], v[32:35]
	v_mfma_f32_16x16x32_bf16 v[24:27], v[140:143], v[180:183], v[24:27]
	v_mfma_f32_16x16x32_bf16 v[16:19], v[112:115], v[188:191], v[16:19]
	v_mfma_f32_16x16x32_bf16 v[8:11], v[140:143], v[188:191], v[8:11]
	s_setprio 0
	s_setprio 1
	v_mfma_f32_16x16x32_bf16 v[52:55], v[144:147], v[160:163], 0
	v_mfma_f32_16x16x32_bf16 v[48:51], v[152:155], v[160:163], 0
	v_mfma_f32_16x16x32_bf16 v[36:39], v[144:147], v[168:171], 0
	v_mfma_f32_16x16x32_bf16 v[28:31], v[152:155], v[168:171], 0
	v_mfma_f32_16x16x32_bf16 v[20:23], v[144:147], v[176:179], 0
	v_mfma_f32_16x16x32_bf16 v[12:15], v[152:155], v[176:179], 0
	v_mfma_f32_16x16x32_bf16 v[4:7], v[144:147], v[184:187], 0
	v_mfma_f32_16x16x32_bf16 v[0:3], v[152:155], v[184:187], 0
	v_mfma_f32_16x16x32_bf16 v[52:55], v[148:151], v[164:167], v[52:55]
	v_mfma_f32_16x16x32_bf16 v[48:51], v[156:159], v[164:167], v[48:51]
	v_mfma_f32_16x16x32_bf16 v[36:39], v[148:151], v[172:175], v[36:39]
	v_mfma_f32_16x16x32_bf16 v[28:31], v[156:159], v[172:175], v[28:31]
	v_mfma_f32_16x16x32_bf16 v[20:23], v[148:151], v[180:183], v[20:23]
	v_mfma_f32_16x16x32_bf16 v[12:15], v[156:159], v[180:183], v[12:15]
	v_mfma_f32_16x16x32_bf16 v[4:7], v[148:151], v[188:191], v[4:7]
	v_mfma_f32_16x16x32_bf16 v[0:3], v[156:159], v[188:191], v[0:3]
	s_setprio 0
	s_barrier
	s_add_i32 s52, 0, 0x18000
	s_add_i32 s53, 0, 0x1c000
	v_add_u32_e32 v140, s52, v247
	v_add_u32_e32 v156, s53, v247
	ds_read_b128 v[104:107], v140
	ds_read_b128 v[112:115], v140 offset:1024
	ds_read_b128 v[136:139], v140 offset:2048
	ds_read_b128 v[140:143], v140 offset:3072
	ds_read_b128 v[144:147], v156
	ds_read_b128 v[148:151], v156 offset:1024
	ds_read_b128 v[152:155], v156 offset:2048
	ds_read_b128 v[156:159], v156 offset:3072
	s_add_u32 s54, s54, 0x100000
	s_addc_u32 s55, s55, 0
	s_mov_b32 m0, s86
	v_lshl_add_u64 v[202:203], s[54:55], 0, v[218:219]
	ds_read_b128 v[160:163], v248 offset:32768
	ds_read_b128 v[164:167], v248 offset:33792
	ds_read_b128 v[168:171], v248 offset:34816
	ds_read_b128 v[172:175], v248 offset:35840
	ds_read_b128 v[176:179], v248 offset:36864
	ds_read_b128 v[180:183], v248 offset:37888
	ds_read_b128 v[184:187], v248 offset:38912
	ds_read_b128 v[188:191], v248 offset:39936
	global_load_lds_dwordx4 v[202:203], off
	v_lshl_add_u64 v[202:203], s[54:55], 0, v[214:215]
	s_mov_b32 m0, s66
	s_nop 0
	global_load_lds_dwordx4 v[202:203], off
	s_waitcnt lgkmcnt(0)
	s_barrier
	s_setprio 1
	s_waitcnt lgkmcnt(0)
	v_mfma_f32_16x16x32_bf16 v[132:135], v[104:107], v[160:163], v[132:135]
	v_mfma_f32_16x16x32_bf16 v[128:131], v[136:139], v[160:163], v[128:131]
	v_mfma_f32_16x16x32_bf16 v[116:119], v[104:107], v[168:171], v[116:119]
	v_mfma_f32_16x16x32_bf16 v[108:111], v[136:139], v[168:171], v[108:111]
	v_mfma_f32_16x16x32_bf16 v[96:99], v[104:107], v[176:179], v[96:99]
	v_mfma_f32_16x16x32_bf16 v[88:91], v[136:139], v[176:179], v[88:91]
	v_mfma_f32_16x16x32_bf16 v[80:83], v[104:107], v[184:187], v[80:83]
	v_mfma_f32_16x16x32_bf16 v[72:75], v[136:139], v[184:187], v[72:75]
	v_mfma_f32_16x16x32_bf16 v[132:135], v[112:115], v[164:167], v[132:135]
	v_mfma_f32_16x16x32_bf16 v[128:131], v[140:143], v[164:167], v[128:131]
	v_mfma_f32_16x16x32_bf16 v[116:119], v[112:115], v[172:175], v[116:119]
	v_mfma_f32_16x16x32_bf16 v[108:111], v[140:143], v[172:175], v[108:111]
	v_mfma_f32_16x16x32_bf16 v[96:99], v[112:115], v[180:183], v[96:99]
	v_mfma_f32_16x16x32_bf16 v[88:91], v[140:143], v[180:183], v[88:91]
	v_mfma_f32_16x16x32_bf16 v[80:83], v[112:115], v[188:191], v[80:83]
	v_mfma_f32_16x16x32_bf16 v[72:75], v[140:143], v[188:191], v[72:75]
	s_setprio 0
	s_setprio 1
	v_mfma_f32_16x16x32_bf16 v[124:127], v[144:147], v[160:163], v[124:127]
	v_mfma_f32_16x16x32_bf16 v[120:123], v[152:155], v[160:163], v[120:123]
	v_mfma_f32_16x16x32_bf16 v[100:103], v[144:147], v[168:171], v[100:103]
	v_mfma_f32_16x16x32_bf16 v[92:95], v[152:155], v[168:171], v[92:95]
	v_mfma_f32_16x16x32_bf16 v[84:87], v[144:147], v[176:179], v[84:87]
	v_mfma_f32_16x16x32_bf16 v[76:79], v[152:155], v[176:179], v[76:79]
	v_mfma_f32_16x16x32_bf16 v[68:71], v[144:147], v[184:187], v[68:71]
	v_mfma_f32_16x16x32_bf16 v[64:67], v[152:155], v[184:187], v[64:67]
	v_mfma_f32_16x16x32_bf16 v[124:127], v[148:151], v[164:167], v[124:127]
	v_mfma_f32_16x16x32_bf16 v[120:123], v[156:159], v[164:167], v[120:123]
	v_mfma_f32_16x16x32_bf16 v[100:103], v[148:151], v[172:175], v[100:103]
	v_mfma_f32_16x16x32_bf16 v[92:95], v[156:159], v[172:175], v[92:95]
	v_mfma_f32_16x16x32_bf16 v[84:87], v[148:151], v[180:183], v[84:87]
	v_mfma_f32_16x16x32_bf16 v[76:79], v[156:159], v[180:183], v[76:79]
	v_mfma_f32_16x16x32_bf16 v[68:71], v[148:151], v[188:191], v[68:71]
	v_mfma_f32_16x16x32_bf16 v[64:67], v[156:159], v[188:191], v[64:67]
	s_setprio 0
	s_barrier
; #define PG8_STAGE(bufoff, gbase, voff) do { _Pragma("unroll") for (int _i = 0; _i < 2; ++_i) \
;         __builtin_amdgcn_global_load_lds((const unsigned*)((const char*)(gbase) + (voff)[_i]), (LAS unsigned*)(lds + (bufoff) + ldsw + _i * 8192), 16, 0, 0); } while (0)
; #define PG8_LDA(dst, b, h) do { _Pragma("unroll") for (int m = 0; m < 4; ++m) _Pragma("unroll") for (int k = 0; k < 2; ++k) dst[m][k] = *(const LAS bf16x8*)(lds + PG8_SA(b, h) + aoff + m * 2048 + k * 1024); } while (0)
; #define PG8_LDB(dst, b, h) do { _Pragma("unroll") for (int n = 0; n < 2; ++n) _Pragma("unroll") for (int k = 0; k < 2; ++k) dst[n][k] = *(const LAS bf16x8*)(lds + PG8_SB(b, h) + boff + n * 2048 + k * 1024); } while (0)
; #define PG8_MMA(ai, bj, At, Bt) do { __builtin_amdgcn_s_setprio(1); _Pragma("unroll") for (int m = 0; m < 4; ++m) _Pragma("unroll") for (int n = 0; n < 2; ++n) _Pragma("unroll") for (int k = 0; k < 2; ++k) \
;         acc[ai][bj][m][n] = __builtin_amdgcn_mfma_f32_16x16x32_bf16(Bt[n][k], At[m][k], acc[ai][bj][m][n], 0, 0, 0); __builtin_amdgcn_s_setprio(0); } while (0)
; #define PG8_WAIT_V(n) asm volatile("s_waitcnt vmcnt(" #n ")" ::: "memory")
; #define PG8_WAIT_L(n) asm volatile("s_waitcnt lgkmcnt(" #n ")" ::: "memory")
; #define PG8_BAR __builtin_amdgcn_s_barrier()
; #define PG8_SCHED __builtin_amdgcn_sched_barrier(0)
; template <class Epi, class Sched, bool ALIGN_EPI>
; __device__ __forceinline__ void gemm_phase(LAS unsigned char* lds, const Gemm g, const Sched& S, const Epi& E) {
;     ...
;             PG8_LDB(B0, 0, 0); PG8_LDB(B1, 0, 1); PG8_SCHED; PG8_LDA(At, 0, 0); PG8_STAGE(PG8_SA(1, 1), a1 + hstepA, voffA);
;             PG8_WAIT_V(8); PG8_WAIT_L(0); PG8_BAR; PG8_MMA(0, 0, At, B0); PG8_MMA(0, 1, At, B1); PG8_BAR; PG8_SCHED;
;     ...
;             PG8_LDB(B0, 1, 0); PG8_LDB(B1, 1, 1); PG8_SCHED; PG8_LDA(At, 1, 0); PG8_STAGE(PG8_SA(0, 1), a2 + hstepA, voffA);
;             PG8_WAIT_V(8); PG8_WAIT_L(0); PG8_BAR; PG8_MMA(0, 0, At, B0); PG8_MMA(0, 1, At, B1); PG8_BAR; PG8_SCHED;
;             PG8_LDA(At, 1, 1); PG8_STAGE(PG8_SB(1, 0), b3, voffB); PG8_STAGE(PG8_SB(1, 1), b3 + hstepB, voffB); PG8_STAGE(PG8_SA(1, 0), a3, voffA);
;             PG8_WAIT_V(8); PG8_WAIT_L(0); PG8_BAR; PG8_MMA(1, 0, At, B0); PG8_MMA(1, 1, At, B1); PG8_BAR; PG8_SCHED;
	s_add_i32 s52, s52, s50
	v_lshl_add_u64 v[194:195], v[194:195], 0, s[12:13]
	s_mov_b32 m0, s52
	ds_read_b128 v[160:163], v248 offset:49152
	ds_read_b128 v[164:167], v248 offset:50176
	ds_read_b128 v[168:171], v248 offset:51200
	ds_read_b128 v[172:175], v248 offset:52224
	ds_read_b128 v[176:179], v248 offset:53248
	ds_read_b128 v[180:183], v248 offset:54272
	ds_read_b128 v[184:187], v248 offset:55296
	ds_read_b128 v[188:191], v248 offset:56320
	global_load_lds_dwordx4 v[194:195], off
	s_add_i32 m0, s52, 0x2000
	s_add_u32 s46, s46, 0x100080
	v_lshl_add_u64 v[194:195], v[196:197], 0, s[12:13]
	s_addc_u32 s47, s47, 0
	s_add_i32 s52, s53, s50
	global_load_lds_dwordx4 v[194:195], off
	v_lshl_add_u64 v[194:195], s[46:47], 0, v[216:217]
	s_mov_b32 m0, s52
	s_nop 0
	global_load_lds_dwordx4 v[194:195], off
	v_lshl_add_u64 v[194:195], s[46:47], 0, v[212:213]
	s_add_i32 m0, s52, 0x2000
	s_nop 0
	global_load_lds_dwordx4 v[194:195], off
	v_lshl_add_u64 v[194:195], v[198:199], 0, s[12:13]
	s_mov_b32 m0, s59
	s_nop 0
	global_load_lds_dwordx4 v[194:195], off
	v_lshl_add_u64 v[194:195], v[200:201], 0, s[12:13]
	s_mov_b32 m0, s4
	s_nop 0
	global_load_lds_dwordx4 v[194:195], off
	s_waitcnt lgkmcnt(0)
	s_barrier
	s_setprio 1
	s_waitcnt lgkmcnt(0)
	v_mfma_f32_16x16x32_bf16 v[60:63], v[104:107], v[160:163], v[60:63]
	v_mfma_f32_16x16x32_bf16 v[56:59], v[136:139], v[160:163], v[56:59]
	v_mfma_f32_16x16x32_bf16 v[44:47], v[104:107], v[168:171], v[44:47]
	v_mfma_f32_16x16x32_bf16 v[40:43], v[136:139], v[168:171], v[40:43]
	v_mfma_f32_16x16x32_bf16 v[32:35], v[104:107], v[176:179], v[32:35]
	v_mfma_f32_16x16x32_bf16 v[24:27], v[136:139], v[176:179], v[24:27]
	v_mfma_f32_16x16x32_bf16 v[16:19], v[104:107], v[184:187], v[16:19]
	v_mfma_f32_16x16x32_bf16 v[8:11], v[136:139], v[184:187], v[8:11]
	v_mfma_f32_16x16x32_bf16 v[60:63], v[112:115], v[164:167], v[60:63]
	v_mfma_f32_16x16x32_bf16 v[56:59], v[140:143], v[164:167], v[56:59]
	v_mfma_f32_16x16x32_bf16 v[44:47], v[112:115], v[172:175], v[44:47]
	v_mfma_f32_16x16x32_bf16 v[40:43], v[140:143], v[172:175], v[40:43]
	v_mfma_f32_16x16x32_bf16 v[32:35], v[112:115], v[180:183], v[32:35]
	v_mfma_f32_16x16x32_bf16 v[24:27], v[140:143], v[180:183], v[24:27]
	v_mfma_f32_16x16x32_bf16 v[16:19], v[112:115], v[188:191], v[16:19]
	v_mfma_f32_16x16x32_bf16 v[8:11], v[140:143], v[188:191], v[8:11]
	s_setprio 0
	s_setprio 1
	v_mfma_f32_16x16x32_bf16 v[52:55], v[144:147], v[160:163], v[52:55]
	s_add_i32 s92, s92, 2
	v_mfma_f32_16x16x32_bf16 v[48:51], v[152:155], v[160:163], v[48:51]
	s_add_u32 s44, s44, 0x100
	v_mfma_f32_16x16x32_bf16 v[36:39], v[144:147], v[168:171], v[36:39]
	s_addc_u32 s45, s45, 0
	v_mfma_f32_16x16x32_bf16 v[28:31], v[152:155], v[168:171], v[28:31]
	s_add_u32 s65, s65, 0x100
	v_mfma_f32_16x16x32_bf16 v[20:23], v[144:147], v[176:179], v[20:23]
	s_addc_u32 s81, s81, 0
	v_mfma_f32_16x16x32_bf16 v[12:15], v[152:155], v[176:179], v[12:15]
	s_add_u32 s46, s44, 0xfff00080
	v_mfma_f32_16x16x32_bf16 v[4:7], v[144:147], v[184:187], v[4:7]
	s_addc_u32 s47, s45, -1
	v_mfma_f32_16x16x32_bf16 v[0:3], v[152:155], v[184:187], v[0:3]
	s_add_i32 s52, 0, 0x10000
	v_mfma_f32_16x16x32_bf16 v[52:55], v[148:151], v[164:167], v[52:55]
	s_cmp_eq_u32 s92, 60
	v_mfma_f32_16x16x32_bf16 v[48:51], v[156:159], v[164:167], v[48:51]
	s_cselect_b32 s55, s56, s47
	v_mfma_f32_16x16x32_bf16 v[36:39], v[148:151], v[172:175], v[36:39]
	s_cselect_b32 s54, s57, s46
	v_mfma_f32_16x16x32_bf16 v[28:31], v[156:159], v[172:175], v[28:31]
	s_cselect_b32 s47, s63, s81
	v_mfma_f32_16x16x32_bf16 v[20:23], v[148:151], v[180:183], v[20:23]
	s_cselect_b32 s46, s64, s65
	v_mfma_f32_16x16x32_bf16 v[12:15], v[156:159], v[180:183], v[12:15]
	s_add_i32 s53, 0, 0x14000
	v_mfma_f32_16x16x32_bf16 v[4:7], v[148:151], v[188:191], v[4:7]
	s_cmp_gt_u32 s92, 61
	v_mfma_f32_16x16x32_bf16 v[0:3], v[156:159], v[188:191], v[0:3]
	s_waitcnt vmcnt(8)
	s_setprio 0
	s_barrier
	s_barrier
	s_branch .LBB0_209
.Ldc_ph_first:
	s_add_u32 s46, s44, 0xfff00080
	s_addc_u32 s47, s45, -1
	s_add_i32 s52, 0, 0x10000
	s_cmp_eq_u32 s92, 60
	s_cselect_b32 s55, s56, s47
	s_cselect_b32 s54, s57, s46
	s_cselect_b32 s47, s63, s81
	s_cselect_b32 s46, s64, s65
	s_add_i32 s53, 0, 0x14000
	v_add_u32_e32 v140, s52, v247
	v_add_u32_e32 v156, s53, v247
	ds_read_b128 v[104:107], v140
	ds_read_b128 v[112:115], v140 offset:1024
	ds_read_b128 v[136:139], v140 offset:2048
	ds_read_b128 v[140:143], v140 offset:3072
	ds_read_b128 v[144:147], v156
	ds_read_b128 v[148:151], v156 offset:1024
	ds_read_b128 v[152:155], v156 offset:2048
	ds_read_b128 v[156:159], v156 offset:3072
	v_lshl_add_u64 v[194:195], s[44:45], 0, v[220:221]
	s_add_i32 m0, s49, 0xc000
	ds_read_b128 v[160:163], v248
	ds_read_b128 v[164:167], v248 offset:1024
	ds_read_b128 v[168:171], v248 offset:2048
	ds_read_b128 v[172:175], v248 offset:3072
	ds_read_b128 v[176:179], v248 offset:4096
	ds_read_b128 v[180:183], v248 offset:5120
	ds_read_b128 v[184:187], v248 offset:6144
	ds_read_b128 v[188:191], v248 offset:7168
	global_load_lds_dwordx4 v[194:195], off
	v_lshl_add_u64 v[194:195], s[44:45], 0, v[222:223]
	s_add_i32 m0, s49, 0xe000
	s_nop 0
	global_load_lds_dwordx4 v[194:195], off
	s_waitcnt vmcnt(8)
	s_waitcnt lgkmcnt(0)
	s_barrier
; #define PG8_STAGE(bufoff, gbase, voff) do { _Pragma("unroll") for (int _i = 0; _i < 2; ++_i) \
;         __builtin_amdgcn_global_load_lds((const unsigned*)((const char*)(gbase) + (voff)[_i]), (LAS unsigned*)(lds + (bufoff) + ldsw + _i * 8192), 16, 0, 0); } while (0)
; #define PG8_LDA(dst, b, h) do { _Pragma("unroll") for (int m = 0; m < 4; ++m) _Pragma("unroll") for (int k = 0; k < 2; ++k) dst[m][k] = *(const LAS bf16x8*)(lds + PG8_SA(b, h) + aoff + m * 2048 + k * 1024); } while (0)
; #define PG8_MMA(ai, bj, At, Bt) do { __builtin_amdgcn_s_setprio(1); _Pragma("unroll") for (int m = 0; m < 4; ++m) _Pragma("unroll") for (int n = 0; n < 2; ++n) _Pragma("unroll") for (int k = 0; k < 2; ++k) \
;         acc[ai][bj][m][n] = __builtin_amdgcn_mfma_f32_16x16x32_bf16(Bt[n][k], At[m][k], acc[ai][bj][m][n], 0, 0, 0); __builtin_amdgcn_s_setprio(0); } while (0)
; #define PG8_WAIT_V(n) asm volatile("s_waitcnt vmcnt(" #n ")" ::: "memory")
; #define PG8_WAIT_L(n) asm volatile("s_waitcnt lgkmcnt(" #n ")" ::: "memory")
; #define PG8_BAR __builtin_amdgcn_s_barrier()
; #define PG8_SCHED __builtin_amdgcn_sched_barrier(0)
; template <class Epi, class Sched, bool ALIGN_EPI>
; __device__ __forceinline__ void gemm_phase(LAS unsigned char* lds, const Gemm g, const Sched& S, const Epi& E) {
;     ...
;             PG8_WAIT_V(8); PG8_WAIT_L(0); PG8_BAR; PG8_MMA(0, 0, At, B0); PG8_MMA(0, 1, At, B1); PG8_BAR; PG8_SCHED;
;             PG8_LDA(At, 0, 1); PG8_STAGE(PG8_SB(0, 0), b2, voffB); PG8_STAGE(PG8_SB(0, 1), b2 + hstepB, voffB); PG8_STAGE(PG8_SA(0, 0), a2, voffA);
;             PG8_WAIT_V(8); PG8_WAIT_L(0); PG8_BAR; PG8_MMA(1, 0, At, B0); PG8_MMA(1, 1, At, B1); PG8_BAR; PG8_SCHED;
	s_setprio 1
	s_waitcnt lgkmcnt(0)
	v_mfma_f32_16x16x32_bf16 v[132:135], v[104:107], v[160:163], 0
	v_mfma_f32_16x16x32_bf16 v[128:131], v[136:139], v[160:163], 0
	v_mfma_f32_16x16x32_bf16 v[116:119], v[104:107], v[168:171], 0
	v_mfma_f32_16x16x32_bf16 v[108:111], v[136:139], v[168:171], 0
	v_mfma_f32_16x16x32_bf16 v[96:99], v[104:107], v[176:179], 0
	v_mfma_f32_16x16x32_bf16 v[88:91], v[136:139], v[176:179], 0
	v_mfma_f32_16x16x32_bf16 v[80:83], v[104:107], v[184:187], 0
	v_mfma_f32_16x16x32_bf16 v[72:75], v[136:139], v[184:187], 0
	v_mfma_f32_16x16x32_bf16 v[132:135], v[112:115], v[164:167], v[132:135]
	v_mfma_f32_16x16x32_bf16 v[128:131], v[140:143], v[164:167], v[128:131]
	v_mfma_f32_16x16x32_bf16 v[116:119], v[112:115], v[172:175], v[116:119]
	v_mfma_f32_16x16x32_bf16 v[108:111], v[140:143], v[172:175], v[108:111]
	v_mfma_f32_16x16x32_bf16 v[96:99], v[112:115], v[180:183], v[96:99]
	v_mfma_f32_16x16x32_bf16 v[88:91], v[140:143], v[180:183], v[88:91]
	v_mfma_f32_16x16x32_bf16 v[80:83], v[112:115], v[188:191], v[80:83]
	v_mfma_f32_16x16x32_bf16 v[72:75], v[140:143], v[188:191], v[72:75]
	s_setprio 0
	s_setprio 1
	v_mfma_f32_16x16x32_bf16 v[124:127], v[144:147], v[160:163], 0
	v_mfma_f32_16x16x32_bf16 v[120:123], v[152:155], v[160:163], 0
	v_mfma_f32_16x16x32_bf16 v[100:103], v[144:147], v[168:171], 0
	v_mfma_f32_16x16x32_bf16 v[92:95], v[152:155], v[168:171], 0
	v_mfma_f32_16x16x32_bf16 v[84:87], v[144:147], v[176:179], 0
	v_mfma_f32_16x16x32_bf16 v[76:79], v[152:155], v[176:179], 0
	v_mfma_f32_16x16x32_bf16 v[68:71], v[144:147], v[184:187], 0
	v_mfma_f32_16x16x32_bf16 v[64:67], v[152:155], v[184:187], 0
	v_mfma_f32_16x16x32_bf16 v[124:127], v[148:151], v[164:167], v[124:127]
	v_mfma_f32_16x16x32_bf16 v[120:123], v[156:159], v[164:167], v[120:123]
	v_mfma_f32_16x16x32_bf16 v[100:103], v[148:151], v[172:175], v[100:103]
	v_mfma_f32_16x16x32_bf16 v[92:95], v[156:159], v[172:175], v[92:95]
	v_mfma_f32_16x16x32_bf16 v[84:87], v[148:151], v[180:183], v[84:87]
	v_mfma_f32_16x16x32_bf16 v[76:79], v[156:159], v[180:183], v[76:79]
	v_mfma_f32_16x16x32_bf16 v[68:71], v[148:151], v[188:191], v[68:71]
	v_mfma_f32_16x16x32_bf16 v[64:67], v[156:159], v[188:191], v[64:67]
	s_setprio 0
	s_barrier
	s_add_i32 s52, s52, s50
	v_lshl_add_u64 v[194:195], s[46:47], 0, v[216:217]
	s_mov_b32 m0, s52
	ds_read_b128 v[160:163], v248 offset:16384
	ds_read_b128 v[164:167], v248 offset:17408
	ds_read_b128 v[168:171], v248 offset:18432
	ds_read_b128 v[172:175], v248 offset:19456
	ds_read_b128 v[176:179], v248 offset:20480
	ds_read_b128 v[180:183], v248 offset:21504
	ds_read_b128 v[184:187], v248 offset:22528
	ds_read_b128 v[188:191], v248 offset:23552
	global_load_lds_dwordx4 v[194:195], off
	s_add_i32 m0, s52, 0x2000
	s_add_u32 vcc_lo, s46, 0x100000
	v_lshl_add_u64 v[196:197], s[46:47], 0, v[212:213]
	s_addc_u32 vcc_hi, s47, 0
	s_add_i32 s52, s53, s50
	global_load_lds_dwordx4 v[196:197], off
	v_lshl_add_u64 v[198:199], vcc, 0, v[216:217]
	s_mov_b32 m0, s52
	v_lshl_add_u64 v[200:201], s[54:55], 0, v[214:215]
	global_load_lds_dwordx4 v[198:199], off
	v_lshl_add_u64 v[198:199], vcc, 0, v[212:213]
	s_add_i32 m0, s52, 0x2000
	s_nop 0
	global_load_lds_dwordx4 v[198:199], off
	v_lshl_add_u64 v[198:199], s[54:55], 0, v[218:219]
	s_mov_b32 m0, s49
	s_nop 0
	global_load_lds_dwordx4 v[198:199], off
	s_mov_b32 m0, s67
	s_nop 0
	global_load_lds_dwordx4 v[200:201], off
	s_waitcnt vmcnt(8)
	s_waitcnt lgkmcnt(0)
	s_barrier
	s_setprio 1
	s_waitcnt lgkmcnt(0)
	v_mfma_f32_16x16x32_bf16 v[60:63], v[104:107], v[160:163], 0
	v_mfma_f32_16x16x32_bf16 v[56:59], v[136:139], v[160:163], 0
	v_mfma_f32_16x16x32_bf16 v[44:47], v[104:107], v[168:171], 0
	v_mfma_f32_16x16x32_bf16 v[40:43], v[136:139], v[168:171], 0
	v_mfma_f32_16x16x32_bf16 v[32:35], v[104:107], v[176:179], 0
	v_mfma_f32_16x16x32_bf16 v[24:27], v[136:139], v[176:179], 0
	v_mfma_f32_16x16x32_bf16 v[16:19], v[104:107], v[184:187], 0
	v_mfma_f32_16x16x32_bf16 v[8:11], v[136:139], v[184:187], 0
	v_mfma_f32_16x16x32_bf16 v[60:63], v[112:115], v[164:167], v[60:63]
	v_mfma_f32_16x16x32_bf16 v[56:59], v[140:143], v[164:167], v[56:59]
	v_mfma_f32_16x16x32_bf16 v[44:47], v[112:115], v[172:175], v[44:47]
	v_mfma_f32_16x16x32_bf16 v[40:43], v[140:143], v[172:175], v[40:43]
	v_mfma_f32_16x16x32_bf16 v[32:35], v[112:115], v[180:183], v[32:35]
	v_mfma_f32_16x16x32_bf16 v[24:27], v[140:143], v[180:183], v[24:27]
	v_mfma_f32_16x16x32_bf16 v[16:19], v[112:115], v[188:191], v[16:19]
	v_mfma_f32_16x16x32_bf16 v[8:11], v[140:143], v[188:191], v[8:11]
	s_setprio 0
	s_setprio 1
	v_mfma_f32_16x16x32_bf16 v[52:55], v[144:147], v[160:163], 0
	v_mfma_f32_16x16x32_bf16 v[48:51], v[152:155], v[160:163], 0
	v_mfma_f32_16x16x32_bf16 v[36:39], v[144:147], v[168:171], 0
	v_mfma_f32_16x16x32_bf16 v[28:31], v[152:155], v[168:171], 0
	v_mfma_f32_16x16x32_bf16 v[20:23], v[144:147], v[176:179], 0
	v_mfma_f32_16x16x32_bf16 v[12:15], v[152:155], v[176:179], 0
	v_mfma_f32_16x16x32_bf16 v[4:7], v[144:147], v[184:187], 0
	v_mfma_f32_16x16x32_bf16 v[0:3], v[152:155], v[184:187], 0
	v_mfma_f32_16x16x32_bf16 v[52:55], v[148:151], v[164:167], v[52:55]
	v_mfma_f32_16x16x32_bf16 v[48:51], v[156:159], v[164:167], v[48:51]
	v_mfma_f32_16x16x32_bf16 v[36:39], v[148:151], v[172:175], v[36:39]
	v_mfma_f32_16x16x32_bf16 v[28:31], v[156:159], v[172:175], v[28:31]
	v_mfma_f32_16x16x32_bf16 v[20:23], v[148:151], v[180:183], v[20:23]
	v_mfma_f32_16x16x32_bf16 v[12:15], v[156:159], v[180:183], v[12:15]
	v_mfma_f32_16x16x32_bf16 v[4:7], v[148:151], v[188:191], v[4:7]
	v_mfma_f32_16x16x32_bf16 v[0:3], v[156:159], v[188:191], v[0:3]
	s_setprio 0
	s_barrier
; #define PG8_STAGE(bufoff, gbase, voff) do { _Pragma("unroll") for (int _i = 0; _i < 2; ++_i) \
;         __builtin_amdgcn_global_load_lds((const unsigned*)((const char*)(gbase) + (voff)[_i]), (LAS unsigned*)(lds + (bufoff) + ldsw + _i * 8192), 16, 0, 0); } while (0)
; #define PG8_LDA(dst, b, h) do { _Pragma("unroll") for (int m = 0; m < 4; ++m) _Pragma("unroll") for (int k = 0; k < 2; ++k) dst[m][k] = *(const LAS bf16x8*)(lds + PG8_SA(b, h) + aoff + m * 2048 + k * 1024); } while (0)
; #define PG8_LDB(dst, b, h) do { _Pragma("unroll") for (int n = 0; n < 2; ++n) _Pragma("unroll") for (int k = 0; k < 2; ++k) dst[n][k] = *(const LAS bf16x8*)(lds + PG8_SB(b, h) + boff + n * 2048 + k * 1024); } while (0)
; #define PG8_MMA(ai, bj, At, Bt) do { __builtin_amdgcn_s_setprio(1); _Pragma("unroll") for (int m = 0; m < 4; ++m) _Pragma("unroll") for (int n = 0; n < 2; ++n) _Pragma("unroll") for (int k = 0; k < 2; ++k) \
;         acc[ai][bj][m][n] = __builtin_amdgcn_mfma_f32_16x16x32_bf16(Bt[n][k], At[m][k], acc[ai][bj][m][n], 0, 0, 0); __builtin_amdgcn_s_setprio(0); } while (0)
; #define PG8_WAIT_V(n) asm volatile("s_waitcnt vmcnt(" #n ")" ::: "memory")
; #define PG8_WAIT_L(n) asm volatile("s_waitcnt lgkmcnt(" #n ")" ::: "memory")
; #define PG8_BAR __builtin_amdgcn_s_barrier()
; #define PG8_SCHED __builtin_amdgcn_sched_barrier(0)
; template <class Epi, class Sched, bool ALIGN_EPI>
; __device__ __forceinline__ void gemm_phase(LAS unsigned char* lds, const Gemm g, const Sched& S, const Epi& E) {
;     ...
;             PG8_LDB(B0, 1, 0); PG8_LDB(B1, 1, 1); PG8_SCHED; PG8_LDA(At, 1, 0); PG8_STAGE(PG8_SA(0, 1), a2 + hstepA, voffA);
;             PG8_WAIT_V(8); PG8_WAIT_L(0); PG8_BAR; PG8_MMA(0, 0, At, B0); PG8_MMA(0, 1, At, B1); PG8_BAR; PG8_SCHED;
	s_add_i32 s52, 0, 0x18000
	s_add_i32 s53, 0, 0x1c000
	v_add_u32_e32 v140, s52, v247
	v_add_u32_e32 v156, s53, v247
	ds_read_b128 v[104:107], v140
	ds_read_b128 v[112:115], v140 offset:1024
	ds_read_b128 v[136:139], v140 offset:2048
	ds_read_b128 v[140:143], v140 offset:3072
	ds_read_b128 v[144:147], v156
	ds_read_b128 v[148:151], v156 offset:1024
	ds_read_b128 v[152:155], v156 offset:2048
	ds_read_b128 v[156:159], v156 offset:3072
	s_add_u32 s54, s54, 0x100000
	s_addc_u32 s55, s55, 0
	s_mov_b32 m0, s86
	v_lshl_add_u64 v[202:203], s[54:55], 0, v[218:219]
	ds_read_b128 v[160:163], v248 offset:32768
	ds_read_b128 v[164:167], v248 offset:33792
	ds_read_b128 v[168:171], v248 offset:34816
	ds_read_b128 v[172:175], v248 offset:35840
	ds_read_b128 v[176:179], v248 offset:36864
	ds_read_b128 v[180:183], v248 offset:37888
	ds_read_b128 v[184:187], v248 offset:38912
	ds_read_b128 v[188:191], v248 offset:39936
	global_load_lds_dwordx4 v[202:203], off
	v_lshl_add_u64 v[202:203], s[54:55], 0, v[214:215]
	s_mov_b32 m0, s66
	s_nop 0
	global_load_lds_dwordx4 v[202:203], off
	s_waitcnt vmcnt(8)
	s_waitcnt lgkmcnt(0)
	s_barrier
	s_setprio 1
	s_waitcnt lgkmcnt(0)
	v_mfma_f32_16x16x32_bf16 v[132:135], v[104:107], v[160:163], v[132:135]
	v_mfma_f32_16x16x32_bf16 v[128:131], v[136:139], v[160:163], v[128:131]
	v_mfma_f32_16x16x32_bf16 v[116:119], v[104:107], v[168:171], v[116:119]
	v_mfma_f32_16x16x32_bf16 v[108:111], v[136:139], v[168:171], v[108:111]
	v_mfma_f32_16x16x32_bf16 v[96:99], v[104:107], v[176:179], v[96:99]
	v_mfma_f32_16x16x32_bf16 v[88:91], v[136:139], v[176:179], v[88:91]
	v_mfma_f32_16x16x32_bf16 v[80:83], v[104:107], v[184:187], v[80:83]
	v_mfma_f32_16x16x32_bf16 v[72:75], v[136:139], v[184:187], v[72:75]
	v_mfma_f32_16x16x32_bf16 v[132:135], v[112:115], v[164:167], v[132:135]
	v_mfma_f32_16x16x32_bf16 v[128:131], v[140:143], v[164:167], v[128:131]
	v_mfma_f32_16x16x32_bf16 v[116:119], v[112:115], v[172:175], v[116:119]
	v_mfma_f32_16x16x32_bf16 v[108:111], v[140:143], v[172:175], v[108:111]
	v_mfma_f32_16x16x32_bf16 v[96:99], v[112:115], v[180:183], v[96:99]
	v_mfma_f32_16x16x32_bf16 v[88:91], v[140:143], v[180:183], v[88:91]
	v_mfma_f32_16x16x32_bf16 v[80:83], v[112:115], v[188:191], v[80:83]
	v_mfma_f32_16x16x32_bf16 v[72:75], v[140:143], v[188:191], v[72:75]
	s_setprio 0
	s_setprio 1
	v_mfma_f32_16x16x32_bf16 v[124:127], v[144:147], v[160:163], v[124:127]
	v_mfma_f32_16x16x32_bf16 v[120:123], v[152:155], v[160:163], v[120:123]
	v_mfma_f32_16x16x32_bf16 v[100:103], v[144:147], v[168:171], v[100:103]
	v_mfma_f32_16x16x32_bf16 v[92:95], v[152:155], v[168:171], v[92:95]
	v_mfma_f32_16x16x32_bf16 v[84:87], v[144:147], v[176:179], v[84:87]
	v_mfma_f32_16x16x32_bf16 v[76:79], v[152:155], v[176:179], v[76:79]
	v_mfma_f32_16x16x32_bf16 v[68:71], v[144:147], v[184:187], v[68:71]
	v_mfma_f32_16x16x32_bf16 v[64:67], v[152:155], v[184:187], v[64:67]
	v_mfma_f32_16x16x32_bf16 v[124:127], v[148:151], v[164:167], v[124:127]
	v_mfma_f32_16x16x32_bf16 v[120:123], v[156:159], v[164:167], v[120:123]
	v_mfma_f32_16x16x32_bf16 v[100:103], v[148:151], v[172:175], v[100:103]
	v_mfma_f32_16x16x32_bf16 v[92:95], v[156:159], v[172:175], v[92:95]
	v_mfma_f32_16x16x32_bf16 v[84:87], v[148:151], v[180:183], v[84:87]
	v_mfma_f32_16x16x32_bf16 v[76:79], v[156:159], v[180:183], v[76:79]
	v_mfma_f32_16x16x32_bf16 v[68:71], v[148:151], v[188:191], v[68:71]
	v_mfma_f32_16x16x32_bf16 v[64:67], v[156:159], v[188:191], v[64:67]
	s_setprio 0
	s_barrier
; #define PG8_STAGE(bufoff, gbase, voff) do { _Pragma("unroll") for (int _i = 0; _i < 2; ++_i) \
;         __builtin_amdgcn_global_load_lds((const unsigned*)((const char*)(gbase) + (voff)[_i]), (LAS unsigned*)(lds + (bufoff) + ldsw + _i * 8192), 16, 0, 0); } while (0)
; #define PG8_LDA(dst, b, h) do { _Pragma("unroll") for (int m = 0; m < 4; ++m) _Pragma("unroll") for (int k = 0; k < 2; ++k) dst[m][k] = *(const LAS bf16x8*)(lds + PG8_SA(b, h) + aoff + m * 2048 + k * 1024); } while (0)
; #define PG8_MMA(ai, bj, At, Bt) do { __builtin_amdgcn_s_setprio(1); _Pragma("unroll") for (int m = 0; m < 4; ++m) _Pragma("unroll") for (int n = 0; n < 2; ++n) _Pragma("unroll") for (int k = 0; k < 2; ++k) \
;         acc[ai][bj][m][n] = __builtin_amdgcn_mfma_f32_16x16x32_bf16(Bt[n][k], At[m][k], acc[ai][bj][m][n], 0, 0, 0); __builtin_amdgcn_s_setprio(0); } while (0)
; #define PG8_WAIT_V(n) asm volatile("s_waitcnt vmcnt(" #n ")" ::: "memory")
; #define PG8_WAIT_L(n) asm volatile("s_waitcnt lgkmcnt(" #n ")" ::: "memory")
; #define PG8_BAR __builtin_amdgcn_s_barrier()
; #define PG8_SCHED __builtin_amdgcn_sched_barrier(0)
; template <class Epi, class Sched, bool ALIGN_EPI>
; __device__ __forceinline__ void gemm_phase(LAS unsigned char* lds, const Gemm g, const Sched& S, const Epi& E) {
;     ...
;         for (int t = 0; t < nt; t += 2) {
;             const bool last = (t == nt - 2);
;             const char* a1 = cA + (size_t)(t + 1) * kstep;
;             const char* a2 = last ? nA : cA + (size_t)(t + 2) * kstep; const char* b2 = last ? nB : cB + (size_t)(t + 2) * kstep;
;             const char* a3 = a2 + kstep; const char* b3 = b2 + kstep;
;     ...
;             PG8_LDA(At, 1, 1); PG8_STAGE(PG8_SB(1, 0), b3, voffB); PG8_STAGE(PG8_SB(1, 1), b3 + hstepB, voffB); PG8_STAGE(PG8_SA(1, 0), a3, voffA);
;             PG8_WAIT_V(8); PG8_WAIT_L(0); PG8_BAR; PG8_MMA(1, 0, At, B0); PG8_MMA(1, 1, At, B1); PG8_BAR; PG8_SCHED;
	s_add_i32 s52, s52, s50
	v_lshl_add_u64 v[194:195], v[194:195], 0, s[12:13]
	s_mov_b32 m0, s52
	ds_read_b128 v[160:163], v248 offset:49152
	ds_read_b128 v[164:167], v248 offset:50176
	ds_read_b128 v[168:171], v248 offset:51200
	ds_read_b128 v[172:175], v248 offset:52224
	ds_read_b128 v[176:179], v248 offset:53248
	ds_read_b128 v[180:183], v248 offset:54272
	ds_read_b128 v[184:187], v248 offset:55296
	ds_read_b128 v[188:191], v248 offset:56320
	global_load_lds_dwordx4 v[194:195], off
	s_add_i32 m0, s52, 0x2000
	s_add_u32 s46, s46, 0x100080
	v_lshl_add_u64 v[194:195], v[196:197], 0, s[12:13]
	s_addc_u32 s47, s47, 0
	s_add_i32 s52, s53, s50
	global_load_lds_dwordx4 v[194:195], off
	v_lshl_add_u64 v[194:195], s[46:47], 0, v[216:217]
	s_mov_b32 m0, s52
	s_nop 0
	global_load_lds_dwordx4 v[194:195], off
	v_lshl_add_u64 v[194:195], s[46:47], 0, v[212:213]
	s_add_i32 m0, s52, 0x2000
	s_nop 0
	global_load_lds_dwordx4 v[194:195], off
	v_lshl_add_u64 v[194:195], v[198:199], 0, s[12:13]
	s_mov_b32 m0, s59
	s_nop 0
	global_load_lds_dwordx4 v[194:195], off
	v_lshl_add_u64 v[194:195], v[200:201], 0, s[12:13]
	s_mov_b32 m0, s4
	s_nop 0
	global_load_lds_dwordx4 v[194:195], off
	s_waitcnt vmcnt(8)
	s_waitcnt lgkmcnt(0)
	s_barrier
	s_setprio 1
	s_waitcnt lgkmcnt(0)
	v_mfma_f32_16x16x32_bf16 v[60:63], v[104:107], v[160:163], v[60:63]
	v_mfma_f32_16x16x32_bf16 v[56:59], v[136:139], v[160:163], v[56:59]
	v_mfma_f32_16x16x32_bf16 v[44:47], v[104:107], v[168:171], v[44:47]
	v_mfma_f32_16x16x32_bf16 v[40:43], v[136:139], v[168:171], v[40:43]
	v_mfma_f32_16x16x32_bf16 v[32:35], v[104:107], v[176:179], v[32:35]
	v_mfma_f32_16x16x32_bf16 v[24:27], v[136:139], v[176:179], v[24:27]
	v_mfma_f32_16x16x32_bf16 v[16:19], v[104:107], v[184:187], v[16:19]
	v_mfma_f32_16x16x32_bf16 v[8:11], v[136:139], v[184:187], v[8:11]
	v_mfma_f32_16x16x32_bf16 v[60:63], v[112:115], v[164:167], v[60:63]
	v_mfma_f32_16x16x32_bf16 v[56:59], v[140:143], v[164:167], v[56:59]
	v_mfma_f32_16x16x32_bf16 v[44:47], v[112:115], v[172:175], v[44:47]
	v_mfma_f32_16x16x32_bf16 v[40:43], v[140:143], v[172:175], v[40:43]
	v_mfma_f32_16x16x32_bf16 v[32:35], v[112:115], v[180:183], v[32:35]
	v_mfma_f32_16x16x32_bf16 v[24:27], v[140:143], v[180:183], v[24:27]
	v_mfma_f32_16x16x32_bf16 v[16:19], v[112:115], v[188:191], v[16:19]
	v_mfma_f32_16x16x32_bf16 v[8:11], v[140:143], v[188:191], v[8:11]
	s_setprio 0
	s_setprio 1
	v_mfma_f32_16x16x32_bf16 v[52:55], v[144:147], v[160:163], v[52:55]
	s_add_i32 s92, s92, 2
	v_mfma_f32_16x16x32_bf16 v[48:51], v[152:155], v[160:163], v[48:51]
	s_add_u32 s44, s44, 0x100
	v_mfma_f32_16x16x32_bf16 v[36:39], v[144:147], v[168:171], v[36:39]
	s_addc_u32 s45, s45, 0
	v_mfma_f32_16x16x32_bf16 v[28:31], v[152:155], v[168:171], v[28:31]
	s_add_u32 s65, s65, 0x100
	v_mfma_f32_16x16x32_bf16 v[20:23], v[144:147], v[176:179], v[20:23]
	s_addc_u32 s81, s81, 0
	v_mfma_f32_16x16x32_bf16 v[12:15], v[152:155], v[176:179], v[12:15]
	s_add_u32 s46, s44, 0xfff00080
	v_mfma_f32_16x16x32_bf16 v[4:7], v[144:147], v[184:187], v[4:7]
	s_addc_u32 s47, s45, -1
	v_mfma_f32_16x16x32_bf16 v[0:3], v[152:155], v[184:187], v[0:3]
	s_add_i32 s52, 0, 0x10000
	v_mfma_f32_16x16x32_bf16 v[52:55], v[148:151], v[164:167], v[52:55]
	s_cmp_eq_u32 s92, 60
	v_mfma_f32_16x16x32_bf16 v[48:51], v[156:159], v[164:167], v[48:51]
	s_cselect_b32 s55, s56, s47
	v_mfma_f32_16x16x32_bf16 v[36:39], v[148:151], v[172:175], v[36:39]
	s_cselect_b32 s54, s57, s46
	v_mfma_f32_16x16x32_bf16 v[28:31], v[156:159], v[172:175], v[28:31]
	s_cselect_b32 s47, s63, s81
	v_mfma_f32_16x16x32_bf16 v[20:23], v[148:151], v[180:183], v[20:23]
	s_cselect_b32 s46, s64, s65
	v_mfma_f32_16x16x32_bf16 v[12:15], v[156:159], v[180:183], v[12:15]
	s_add_i32 s53, 0, 0x14000
	v_mfma_f32_16x16x32_bf16 v[4:7], v[148:151], v[188:191], v[4:7]
	s_cmp_gt_u32 s92, 61
	v_mfma_f32_16x16x32_bf16 v[0:3], v[156:159], v[188:191], v[0:3]
	s_setprio 0
	s_barrier

; #define LAS __attribute__((address_space(3)))
; #define PG8_STAGE(bufoff, gbase, voff) do { _Pragma("unroll") for (int _i = 0; _i < 2; ++_i) \
;         __builtin_amdgcn_global_load_lds((const unsigned*)((const char*)(gbase) + (voff)[_i]), (LAS unsigned*)(lds + (bufoff) + ldsw + _i * 8192), 16, 0, 0); } while (0)
; #define PG8_LDA(dst, b, h) do { _Pragma("unroll") for (int m = 0; m < 4; ++m) _Pragma("unroll") for (int k = 0; k < 2; ++k) dst[m][k] = *(const LAS bf16x8*)(lds + PG8_SA(b, h) + aoff + m * 2048 + k * 1024); } while (0)
; #define PG8_LDB(dst, b, h) do { _Pragma("unroll") for (int n = 0; n < 2; ++n) _Pragma("unroll") for (int k = 0; k < 2; ++k) dst[n][k] = *(const LAS bf16x8*)(lds + PG8_SB(b, h) + boff + n * 2048 + k * 1024); } while (0)
; #define PG8_SCHED __builtin_amdgcn_sched_barrier(0)
; template <class Epi, class Sched, bool ALIGN_EPI>
; __device__ __forceinline__ void gemm_phase(LAS unsigned char* lds, const Gemm g, const Sched& S, const Epi& E) {
;     ...
;             PG8_LDB(B0, 0, 0); PG8_LDB(B1, 0, 1); PG8_SCHED; PG8_LDA(At, 0, 0); PG8_STAGE(PG8_SA(1, 1), a1 + hstepA, voffA);
;     __device__ __forceinline__ void operator()(const f32x4 (&acc)[2][2][4][2], const Unit& u, int wr, int wc, int fr, int fq) const {
;         const int b = u.pm >> 3, col0 = u.pn * 256 + wc * 32 + 8 * fq;
;         { const int t = (wr * 4 + wc) * 64 + fq * 16 + fr;
;           if (t < 64) ((LAS f32x4*)gl)[t] = *(const f32x4*)(gate + (size_t)b * gate_ld + u.pn * 256 + 4 * t);
;           else if (t < 128 && gmn) ((LAS f32x4*)gl)[t] = *(const f32x4*)(gmn + (size_t)b * DM + u.pn * 256 + 4 * (t - 64));
;           asm volatile("s_waitcnt vmcnt(0) lgkmcnt(0)" ::: "memory"); __builtin_amdgcn_s_barrier(); asm volatile("" ::: "memory"); }
.LBB0_212:
	s_add_u32 vcc_lo, s57, 0x100080
	s_addc_u32 vcc_hi, s56, 0
	v_lshl_add_u64 v[194:195], vcc, 0, v[220:221]
	s_add_i32 m0, s49, 0xc000
	s_nop 0
	global_load_lds_dwordx4 v[194:195], off
	v_lshl_add_u64 v[194:195], vcc, 0, v[222:223]
	s_add_i32 m0, s49, 0xe000
	s_nop 0
	global_load_lds_dwordx4 v[194:195], off
	s_mul_i32 s100, s5, 36
	s_add_i32 s100, s100, 0x24000
	s_cmp_eq_u32 s5, 0x1c0
	s_cselect_b32 s100, 0x20c00, s100
	s_lshl_b32 s101, s5, 4
	s_add_i32 s101, s101, 0x21800
	v_lshrrev_b32_e32 v210, 3, v242
	v_and_b32_e32 v246, 7, v242
	v_mul_u32_u24_e32 v210, 0x90, v210
	v_lshl_add_u32 v210, v246, 4, v210
	v_add_u32_e32 v210, s100, v210
	v_mul_u32_u24_e32 v208, 0x90, v211
	v_lshl_add_u32 v208, v207, 5, v208
	v_add_u32_e32 v208, s100, v208
	v_lshrrev_b32_e32 v252, 3, v242
	v_sub_u32_e32 v252, v252, v211
	v_lshlrev_b32_e32 v252, 12, v252
	v_lshl_add_u32 v246, v246, 4, v252
	v_lshlrev_b32_e32 v252, 5, v207
	v_sub_u32_e32 v246, v246, v252
	v_lshl_add_u32 v252, v242, 2, s101
	ds_write_b32 v252, v216
	ds_write_b32 v252, v218 offset:256
	ds_write_b32 v252, v220 offset:512
	ds_write_b32 v252, v222 offset:768
	s_add_u32 s100, s20, 0x8000
	s_addc_u32 s101, s21, 0
	v_and_b32_e32 v206, 3, v242
	v_lshrrev_b32_e32 v204, 2, v242
	v_lshl_add_u32 v205, v206, 4, v204
	v_sub_u32_e32 v204, v204, v211
	v_sub_u32_e32 v206, v206, v207
	v_lshlrev_b32_e32 v204, 11, v204
	v_lshl_add_u32 v204, v206, 4, v204
	v_lshlrev_b32_e32 v206, 2, v205
	v_ashrrev_i32_e32 v205, 31, v204
	v_mov_b32_e32 v106, v211
	v_mov_b32_e32 v250, v207
	s_ashr_i32 s46, s77, 3
	v_lshlrev_b32_e32 v104, 4, v250
	v_add3_u32 v107, s5, v106, v104
	s_lshl_b32 s44, s76, 8
	v_cmp_lt_i32_e32 vcc, 63, v107
	s_mov_b64 s[56:57], 0
	s_and_saveexec_b64 s[54:55], vcc
	s_xor_b64 s[54:55], exec, s[54:55]
	s_movk_i32 s63, 0x5ff
	s_cbranch_execnz .LBB0_261
	s_andn2_saveexec_b64 s[54:55], s[54:55]
	s_cbranch_execnz .LBB0_264

; #define PG8_STAGE(bufoff, gbase, voff) do { _Pragma("unroll") for (int _i = 0; _i < 2; ++_i) \
;         __builtin_amdgcn_global_load_lds((const unsigned*)((const char*)(gbase) + (voff)[_i]), (LAS unsigned*)(lds + (bufoff) + ldsw + _i * 8192), 16, 0, 0); } while (0)
; #define PG8_LDA(dst, b, h) do { _Pragma("unroll") for (int m = 0; m < 4; ++m) _Pragma("unroll") for (int k = 0; k < 2; ++k) dst[m][k] = *(const LAS bf16x8*)(lds + PG8_SA(b, h) + aoff + m * 2048 + k * 1024); } while (0)
; #define PG8_LDB(dst, b, h) do { _Pragma("unroll") for (int n = 0; n < 2; ++n) _Pragma("unroll") for (int k = 0; k < 2; ++k) dst[n][k] = *(const LAS bf16x8*)(lds + PG8_SB(b, h) + boff + n * 2048 + k * 1024); } while (0)
; #define PG8_MMA(ai, bj, At, Bt) do { __builtin_amdgcn_s_setprio(1); _Pragma("unroll") for (int m = 0; m < 4; ++m) _Pragma("unroll") for (int n = 0; n < 2; ++n) _Pragma("unroll") for (int k = 0; k < 2; ++k) \
;         acc[ai][bj][m][n] = __builtin_amdgcn_mfma_f32_16x16x32_bf16(Bt[n][k], At[m][k], acc[ai][bj][m][n], 0, 0, 0); __builtin_amdgcn_s_setprio(0); } while (0)
; #define PG8_BAR __builtin_amdgcn_s_barrier()
; template <class Epi, class Sched, bool ALIGN_EPI>
; __device__ __forceinline__ void gemm_phase(LAS unsigned char* lds, const Gemm g, const Sched& S, const Epi& E) {
;     ...
;         const bool has_next = S.next(ui + 1, nxt);
;         const char* nA = has_next ? (const char*)g.A + (size_t)nxt.pm * tstepA : cA; const char* nB = has_next ? (const char*)g.Bt + (size_t)nxt.pn * tstepB : cB;
;         for (int t = 0; t < nt; t += 2) {
;             const bool last = (t == nt - 2);
;             const char* a1 = cA + (size_t)(t + 1) * kstep;
;             const char* a2 = last ? nA : cA + (size_t)(t + 2) * kstep; const char* b2 = last ? nB : cB + (size_t)(t + 2) * kstep;
;             const char* a3 = a2 + kstep; const char* b3 = b2 + kstep;
;             PG8_LDB(B0, 0, 0); PG8_LDB(B1, 0, 1); PG8_SCHED; PG8_LDA(At, 0, 0); PG8_STAGE(PG8_SA(1, 1), a1 + hstepA, voffA);
;             PG8_WAIT_V(8); PG8_WAIT_L(0); PG8_BAR; PG8_MMA(0, 0, At, B0); PG8_MMA(0, 1, At, B1); PG8_BAR; PG8_SCHED;
;             PG8_LDA(At, 0, 1); PG8_STAGE(PG8_SB(0, 0), b2, voffB); PG8_STAGE(PG8_SB(0, 1), b2 + hstepB, voffB); PG8_STAGE(PG8_SA(0, 0), a2, voffA);
;             PG8_WAIT_V(8); PG8_WAIT_L(0); PG8_BAR; PG8_MMA(1, 0, At, B0); PG8_MMA(1, 1, At, B1); PG8_BAR; PG8_SCHED;
.LBB0_286:
	s_ashr_i32 s23, s22, 31
	s_lshl_b64 s[38:39], s[22:23], 19
	s_add_u32 s38, s48, s38
	s_addc_u32 s39, s49, s39
	s_and_b64 s[40:41], s[42:43], exec
	s_cselect_b32 s23, s39, s45
	s_cselect_b32 s85, s38, s44
	s_ashr_i32 s21, s20, 31
	s_lshl_b64 s[40:41], s[20:21], 19
	s_add_u32 s40, s50, s40
	s_addc_u32 s41, s51, s41
	s_and_b64 s[54:55], s[42:43], exec
	s_cselect_b32 s21, s41, s47
	s_cselect_b32 s86, s40, s46
	s_add_u32 s44, s44, 0x40080
	s_addc_u32 s45, s45, 0
	s_add_u32 s87, s46, 0x100
	s_addc_u32 s90, s47, 0
	s_mov_b32 s91, -2
	s_cmp_eq_u32 s80, 1
	s_cbranch_scc1 .Ldc_pg_first
	s_add_u32 s46, s44, 0xfffc0080
	s_addc_u32 s47, s45, -1
	s_add_i32 s92, 0, 0x10000
	s_cmp_eq_u32 s91, 12
	s_cselect_b32 s55, s23, s47
	s_cselect_b32 s54, s85, s46
	s_cselect_b32 s47, s21, s90
	s_cselect_b32 s46, s86, s87
	s_add_i32 s4, 0, 0x14000
	v_add_u32_e32 v132, s92, v160
	v_add_u32_e32 v170, s4, v160
	ds_read_b128 v[120:123], v132
	ds_read_b128 v[124:127], v132 offset:1024
	ds_read_b128 v[128:131], v132 offset:2048
	ds_read_b128 v[132:135], v132 offset:3072
	ds_read_b128 v[154:157], v170
	ds_read_b128 v[162:165], v170 offset:1024
	ds_read_b128 v[166:169], v170 offset:2048
	ds_read_b128 v[170:173], v170 offset:3072
	ds_read_b128 v[174:177], v161
	ds_read_b128 v[178:181], v161 offset:1024
	ds_read_b128 v[182:185], v161 offset:2048
	ds_read_b128 v[186:189], v161 offset:3072
	ds_read_b128 v[194:197], v161 offset:4096
	ds_read_b128 v[198:201], v161 offset:5120
	ds_read_b128 v[202:205], v161 offset:6144
	ds_read_b128 v[212:215], v161 offset:7168
	s_waitcnt lgkmcnt(0)
	s_barrier
	s_setprio 1
	s_waitcnt lgkmcnt(0)
	v_mfma_f32_16x16x32_bf16 v[140:143], v[120:123], v[174:177], 0
	v_mfma_f32_16x16x32_bf16 v[136:139], v[128:131], v[174:177], 0
	v_mfma_f32_16x16x32_bf16 v[108:111], v[120:123], v[182:185], 0
	v_mfma_f32_16x16x32_bf16 v[104:107], v[128:131], v[182:185], 0
	v_mfma_f32_16x16x32_bf16 v[92:95], v[120:123], v[194:197], 0
	v_mfma_f32_16x16x32_bf16 v[88:91], v[128:131], v[194:197], 0
	v_mfma_f32_16x16x32_bf16 v[76:79], v[120:123], v[202:205], 0
	v_mfma_f32_16x16x32_bf16 v[72:75], v[128:131], v[202:205], 0
	v_mfma_f32_16x16x32_bf16 v[140:143], v[124:127], v[178:181], v[140:143]
	v_mfma_f32_16x16x32_bf16 v[136:139], v[132:135], v[178:181], v[136:139]
	v_mfma_f32_16x16x32_bf16 v[108:111], v[124:127], v[186:189], v[108:111]
	v_mfma_f32_16x16x32_bf16 v[104:107], v[132:135], v[186:189], v[104:107]
	v_mfma_f32_16x16x32_bf16 v[92:95], v[124:127], v[198:201], v[92:95]
	v_mfma_f32_16x16x32_bf16 v[88:91], v[132:135], v[198:201], v[88:91]
	v_mfma_f32_16x16x32_bf16 v[76:79], v[124:127], v[212:215], v[76:79]
	v_mfma_f32_16x16x32_bf16 v[72:75], v[132:135], v[212:215], v[72:75]
	s_setprio 0
	s_setprio 1
	v_mfma_f32_16x16x32_bf16 v[116:119], v[154:157], v[174:177], 0
	v_mfma_f32_16x16x32_bf16 v[112:115], v[166:169], v[174:177], 0
	v_mfma_f32_16x16x32_bf16 v[100:103], v[154:157], v[182:185], 0
	v_mfma_f32_16x16x32_bf16 v[96:99], v[166:169], v[182:185], 0
	v_mfma_f32_16x16x32_bf16 v[84:87], v[154:157], v[194:197], 0
	v_mfma_f32_16x16x32_bf16 v[80:83], v[166:169], v[194:197], 0
	v_mfma_f32_16x16x32_bf16 v[68:71], v[154:157], v[202:205], 0
	v_mfma_f32_16x16x32_bf16 v[64:67], v[166:169], v[202:205], 0
	v_mfma_f32_16x16x32_bf16 v[116:119], v[162:165], v[178:181], v[116:119]
	v_mfma_f32_16x16x32_bf16 v[112:115], v[170:173], v[178:181], v[112:115]
	v_mfma_f32_16x16x32_bf16 v[100:103], v[162:165], v[186:189], v[100:103]
	v_mfma_f32_16x16x32_bf16 v[96:99], v[170:173], v[186:189], v[96:99]
	v_mfma_f32_16x16x32_bf16 v[84:87], v[162:165], v[198:201], v[84:87]
	v_mfma_f32_16x16x32_bf16 v[80:83], v[170:173], v[198:201], v[80:83]
	v_mfma_f32_16x16x32_bf16 v[68:71], v[162:165], v[212:215], v[68:71]
	v_mfma_f32_16x16x32_bf16 v[64:67], v[170:173], v[212:215], v[64:67]
	s_setprio 0
	s_barrier
	s_add_i32 s5, s92, s52
	v_lshl_add_u64 v[190:191], s[46:47], 0, v[192:193]
	s_mov_b32 m0, s5
	ds_read_b128 v[174:177], v161 offset:16384
	ds_read_b128 v[178:181], v161 offset:17408
	ds_read_b128 v[182:185], v161 offset:18432
	ds_read_b128 v[186:189], v161 offset:19456
	ds_read_b128 v[194:197], v161 offset:20480
	ds_read_b128 v[198:201], v161 offset:21504
	ds_read_b128 v[202:205], v161 offset:22528
	ds_read_b128 v[212:215], v161 offset:23552
	global_load_lds_dwordx4 v[190:191], off
	s_add_i32 m0, s5, 0x2000
	s_add_u32 vcc_lo, s46, 0x40000
	v_lshl_add_u64 v[216:217], s[46:47], 0, v[144:145]
	s_addc_u32 vcc_hi, s47, 0
	s_add_i32 s4, s4, s52
	global_load_lds_dwordx4 v[216:217], off
	v_lshl_add_u64 v[218:219], vcc, 0, v[192:193]
	s_mov_b32 m0, s4
	v_lshl_add_u64 v[220:221], s[54:55], 0, v[146:147]
	global_load_lds_dwordx4 v[218:219], off
	v_lshl_add_u64 v[218:219], vcc, 0, v[144:145]
	s_add_i32 m0, s4, 0x2000
	s_nop 0
	global_load_lds_dwordx4 v[218:219], off
	v_lshl_add_u64 v[218:219], s[54:55], 0, v[148:149]
	s_mov_b32 m0, s53
	s_nop 0
	global_load_lds_dwordx4 v[218:219], off
	s_mov_b32 m0, s56
	s_nop 0
	global_load_lds_dwordx4 v[220:221], off
	s_waitcnt lgkmcnt(0)
	s_barrier
; #define PG8_STAGE(bufoff, gbase, voff) do { _Pragma("unroll") for (int _i = 0; _i < 2; ++_i) \
;         __builtin_amdgcn_global_load_lds((const unsigned*)((const char*)(gbase) + (voff)[_i]), (LAS unsigned*)(lds + (bufoff) + ldsw + _i * 8192), 16, 0, 0); } while (0)
; #define PG8_LDA(dst, b, h) do { _Pragma("unroll") for (int m = 0; m < 4; ++m) _Pragma("unroll") for (int k = 0; k < 2; ++k) dst[m][k] = *(const LAS bf16x8*)(lds + PG8_SA(b, h) + aoff + m * 2048 + k * 1024); } while (0)
; #define PG8_LDB(dst, b, h) do { _Pragma("unroll") for (int n = 0; n < 2; ++n) _Pragma("unroll") for (int k = 0; k < 2; ++k) dst[n][k] = *(const LAS bf16x8*)(lds + PG8_SB(b, h) + boff + n * 2048 + k * 1024); } while (0)
; #define PG8_MMA(ai, bj, At, Bt) do { __builtin_amdgcn_s_setprio(1); _Pragma("unroll") for (int m = 0; m < 4; ++m) _Pragma("unroll") for (int n = 0; n < 2; ++n) _Pragma("unroll") for (int k = 0; k < 2; ++k) \
;         acc[ai][bj][m][n] = __builtin_amdgcn_mfma_f32_16x16x32_bf16(Bt[n][k], At[m][k], acc[ai][bj][m][n], 0, 0, 0); __builtin_amdgcn_s_setprio(0); } while (0)
; #define PG8_WAIT_V(n) asm volatile("s_waitcnt vmcnt(" #n ")" ::: "memory")
; #define PG8_WAIT_L(n) asm volatile("s_waitcnt lgkmcnt(" #n ")" ::: "memory")
; #define PG8_BAR __builtin_amdgcn_s_barrier()
; #define PG8_SCHED __builtin_amdgcn_sched_barrier(0)
; template <class Epi, class Sched, bool ALIGN_EPI>
; __device__ __forceinline__ void gemm_phase(LAS unsigned char* lds, const Gemm g, const Sched& S, const Epi& E) {
;     ...
;             PG8_WAIT_V(8); PG8_WAIT_L(0); PG8_BAR; PG8_MMA(1, 0, At, B0); PG8_MMA(1, 1, At, B1); PG8_BAR; PG8_SCHED;
;             PG8_LDB(B0, 1, 0); PG8_LDB(B1, 1, 1); PG8_SCHED; PG8_LDA(At, 1, 0); PG8_STAGE(PG8_SA(0, 1), a2 + hstepA, voffA);
;             PG8_WAIT_V(8); PG8_WAIT_L(0); PG8_BAR; PG8_MMA(0, 0, At, B0); PG8_MMA(0, 1, At, B1); PG8_BAR; PG8_SCHED;
	s_setprio 1
	s_waitcnt lgkmcnt(0)
	v_mfma_f32_16x16x32_bf16 v[60:63], v[120:123], v[174:177], 0
	v_mfma_f32_16x16x32_bf16 v[56:59], v[128:131], v[174:177], 0
	v_mfma_f32_16x16x32_bf16 v[48:51], v[120:123], v[182:185], 0
	v_mfma_f32_16x16x32_bf16 v[40:43], v[128:131], v[182:185], 0
	v_mfma_f32_16x16x32_bf16 v[32:35], v[120:123], v[194:197], 0
	v_mfma_f32_16x16x32_bf16 v[24:27], v[128:131], v[194:197], 0
	v_mfma_f32_16x16x32_bf16 v[16:19], v[120:123], v[202:205], 0
	v_mfma_f32_16x16x32_bf16 v[8:11], v[128:131], v[202:205], 0
	v_mfma_f32_16x16x32_bf16 v[60:63], v[124:127], v[178:181], v[60:63]
	v_mfma_f32_16x16x32_bf16 v[56:59], v[132:135], v[178:181], v[56:59]
	v_mfma_f32_16x16x32_bf16 v[48:51], v[124:127], v[186:189], v[48:51]
	v_mfma_f32_16x16x32_bf16 v[40:43], v[132:135], v[186:189], v[40:43]
	v_mfma_f32_16x16x32_bf16 v[32:35], v[124:127], v[198:201], v[32:35]
	v_mfma_f32_16x16x32_bf16 v[24:27], v[132:135], v[198:201], v[24:27]
	v_mfma_f32_16x16x32_bf16 v[16:19], v[124:127], v[212:215], v[16:19]
	v_mfma_f32_16x16x32_bf16 v[8:11], v[132:135], v[212:215], v[8:11]
	s_setprio 0
	s_setprio 1
	v_mfma_f32_16x16x32_bf16 v[52:55], v[154:157], v[174:177], 0
	v_mfma_f32_16x16x32_bf16 v[44:47], v[166:169], v[174:177], 0
	v_mfma_f32_16x16x32_bf16 v[36:39], v[154:157], v[182:185], 0
	v_mfma_f32_16x16x32_bf16 v[28:31], v[166:169], v[182:185], 0
	v_mfma_f32_16x16x32_bf16 v[20:23], v[154:157], v[194:197], 0
	v_mfma_f32_16x16x32_bf16 v[12:15], v[166:169], v[194:197], 0
	v_mfma_f32_16x16x32_bf16 v[4:7], v[154:157], v[202:205], 0
	v_mfma_f32_16x16x32_bf16 v[0:3], v[166:169], v[202:205], 0
	v_mfma_f32_16x16x32_bf16 v[52:55], v[162:165], v[178:181], v[52:55]
	v_mfma_f32_16x16x32_bf16 v[44:47], v[170:173], v[178:181], v[44:47]
	v_mfma_f32_16x16x32_bf16 v[36:39], v[162:165], v[186:189], v[36:39]
	v_mfma_f32_16x16x32_bf16 v[28:31], v[170:173], v[186:189], v[28:31]
	v_mfma_f32_16x16x32_bf16 v[20:23], v[162:165], v[198:201], v[20:23]
	v_mfma_f32_16x16x32_bf16 v[12:15], v[170:173], v[198:201], v[12:15]
	v_mfma_f32_16x16x32_bf16 v[4:7], v[162:165], v[212:215], v[4:7]
	v_mfma_f32_16x16x32_bf16 v[0:3], v[170:173], v[212:215], v[0:3]
	s_setprio 0
	s_barrier
	s_add_i32 s4, 0, 0x18000
	s_add_i32 s5, 0, 0x1c000
	v_add_u32_e32 v132, s4, v160
	v_add_u32_e32 v170, s5, v160
	ds_read_b128 v[120:123], v132
	ds_read_b128 v[124:127], v132 offset:1024
	ds_read_b128 v[128:131], v132 offset:2048
	ds_read_b128 v[132:135], v132 offset:3072
	ds_read_b128 v[154:157], v170
	ds_read_b128 v[162:165], v170 offset:1024
	ds_read_b128 v[166:169], v170 offset:2048
	ds_read_b128 v[170:173], v170 offset:3072
	s_add_u32 s54, s54, 0x40000
	s_addc_u32 s55, s55, 0
	s_mov_b32 m0, s57
	v_lshl_add_u64 v[222:223], s[54:55], 0, v[148:149]
	ds_read_b128 v[174:177], v161 offset:32768
	ds_read_b128 v[178:181], v161 offset:33792
	ds_read_b128 v[182:185], v161 offset:34816
	ds_read_b128 v[186:189], v161 offset:35840
	ds_read_b128 v[194:197], v161 offset:36864
	ds_read_b128 v[198:201], v161 offset:37888
	ds_read_b128 v[202:205], v161 offset:38912
	ds_read_b128 v[212:215], v161 offset:39936
	global_load_lds_dwordx4 v[222:223], off
	v_lshl_add_u64 v[222:223], s[54:55], 0, v[146:147]
	s_mov_b32 m0, s58
	s_nop 0
	global_load_lds_dwordx4 v[222:223], off
	s_waitcnt lgkmcnt(0)
	s_barrier
	s_setprio 1
	s_waitcnt lgkmcnt(0)
	v_mfma_f32_16x16x32_bf16 v[140:143], v[120:123], v[174:177], v[140:143]
	v_mfma_f32_16x16x32_bf16 v[136:139], v[128:131], v[174:177], v[136:139]
	v_mfma_f32_16x16x32_bf16 v[108:111], v[120:123], v[182:185], v[108:111]
	v_mfma_f32_16x16x32_bf16 v[104:107], v[128:131], v[182:185], v[104:107]
	v_mfma_f32_16x16x32_bf16 v[92:95], v[120:123], v[194:197], v[92:95]
	v_mfma_f32_16x16x32_bf16 v[88:91], v[128:131], v[194:197], v[88:91]
	v_mfma_f32_16x16x32_bf16 v[76:79], v[120:123], v[202:205], v[76:79]
	v_mfma_f32_16x16x32_bf16 v[72:75], v[128:131], v[202:205], v[72:75]
	v_mfma_f32_16x16x32_bf16 v[140:143], v[124:127], v[178:181], v[140:143]
	v_mfma_f32_16x16x32_bf16 v[136:139], v[132:135], v[178:181], v[136:139]
	v_mfma_f32_16x16x32_bf16 v[108:111], v[124:127], v[186:189], v[108:111]
	v_mfma_f32_16x16x32_bf16 v[104:107], v[132:135], v[186:189], v[104:107]
	v_mfma_f32_16x16x32_bf16 v[92:95], v[124:127], v[198:201], v[92:95]
	v_mfma_f32_16x16x32_bf16 v[88:91], v[132:135], v[198:201], v[88:91]
	v_mfma_f32_16x16x32_bf16 v[76:79], v[124:127], v[212:215], v[76:79]
	v_mfma_f32_16x16x32_bf16 v[72:75], v[132:135], v[212:215], v[72:75]
	s_setprio 0
	s_setprio 1
	v_mfma_f32_16x16x32_bf16 v[116:119], v[154:157], v[174:177], v[116:119]
	v_mfma_f32_16x16x32_bf16 v[112:115], v[166:169], v[174:177], v[112:115]
	v_mfma_f32_16x16x32_bf16 v[100:103], v[154:157], v[182:185], v[100:103]
	v_mfma_f32_16x16x32_bf16 v[96:99], v[166:169], v[182:185], v[96:99]
	v_mfma_f32_16x16x32_bf16 v[84:87], v[154:157], v[194:197], v[84:87]
	v_mfma_f32_16x16x32_bf16 v[80:83], v[166:169], v[194:197], v[80:83]
	v_mfma_f32_16x16x32_bf16 v[68:71], v[154:157], v[202:205], v[68:71]
	v_mfma_f32_16x16x32_bf16 v[64:67], v[166:169], v[202:205], v[64:67]
	v_mfma_f32_16x16x32_bf16 v[116:119], v[162:165], v[178:181], v[116:119]
	v_mfma_f32_16x16x32_bf16 v[112:115], v[170:173], v[178:181], v[112:115]
	v_mfma_f32_16x16x32_bf16 v[100:103], v[162:165], v[186:189], v[100:103]
	v_mfma_f32_16x16x32_bf16 v[96:99], v[170:173], v[186:189], v[96:99]
	v_mfma_f32_16x16x32_bf16 v[84:87], v[162:165], v[198:201], v[84:87]
	v_mfma_f32_16x16x32_bf16 v[80:83], v[170:173], v[198:201], v[80:83]
	v_mfma_f32_16x16x32_bf16 v[68:71], v[162:165], v[212:215], v[68:71]
	v_mfma_f32_16x16x32_bf16 v[64:67], v[170:173], v[212:215], v[64:67]
	s_setprio 0
	s_barrier
; #define PG8_STAGE(bufoff, gbase, voff) do { _Pragma("unroll") for (int _i = 0; _i < 2; ++_i) \
;         __builtin_amdgcn_global_load_lds((const unsigned*)((const char*)(gbase) + (voff)[_i]), (LAS unsigned*)(lds + (bufoff) + ldsw + _i * 8192), 16, 0, 0); } while (0)
; #define PG8_LDA(dst, b, h) do { _Pragma("unroll") for (int m = 0; m < 4; ++m) _Pragma("unroll") for (int k = 0; k < 2; ++k) dst[m][k] = *(const LAS bf16x8*)(lds + PG8_SA(b, h) + aoff + m * 2048 + k * 1024); } while (0)
; #define PG8_LDB(dst, b, h) do { _Pragma("unroll") for (int n = 0; n < 2; ++n) _Pragma("unroll") for (int k = 0; k < 2; ++k) dst[n][k] = *(const LAS bf16x8*)(lds + PG8_SB(b, h) + boff + n * 2048 + k * 1024); } while (0)
; #define PG8_MMA(ai, bj, At, Bt) do { __builtin_amdgcn_s_setprio(1); _Pragma("unroll") for (int m = 0; m < 4; ++m) _Pragma("unroll") for (int n = 0; n < 2; ++n) _Pragma("unroll") for (int k = 0; k < 2; ++k) \
;         acc[ai][bj][m][n] = __builtin_amdgcn_mfma_f32_16x16x32_bf16(Bt[n][k], At[m][k], acc[ai][bj][m][n], 0, 0, 0); __builtin_amdgcn_s_setprio(0); } while (0)
; #define PG8_WAIT_V(n) asm volatile("s_waitcnt vmcnt(" #n ")" ::: "memory")
; #define PG8_WAIT_L(n) asm volatile("s_waitcnt lgkmcnt(" #n ")" ::: "memory")
; #define PG8_BAR __builtin_amdgcn_s_barrier()
; #define PG8_SCHED __builtin_amdgcn_sched_barrier(0)
; template <class Epi, class Sched, bool ALIGN_EPI>
; __device__ __forceinline__ void gemm_phase(LAS unsigned char* lds, const Gemm g, const Sched& S, const Epi& E) {
;     ...
;             PG8_LDB(B0, 0, 0); PG8_LDB(B1, 0, 1); PG8_SCHED; PG8_LDA(At, 0, 0); PG8_STAGE(PG8_SA(1, 1), a1 + hstepA, voffA);
;             PG8_WAIT_V(8); PG8_WAIT_L(0); PG8_BAR; PG8_MMA(0, 0, At, B0); PG8_MMA(0, 1, At, B1); PG8_BAR; PG8_SCHED;
;     ...
;             PG8_LDA(At, 1, 1); PG8_STAGE(PG8_SB(1, 0), b3, voffB); PG8_STAGE(PG8_SB(1, 1), b3 + hstepB, voffB); PG8_STAGE(PG8_SA(1, 0), a3, voffA);
;             PG8_WAIT_V(8); PG8_WAIT_L(0); PG8_BAR; PG8_MMA(1, 0, At, B0); PG8_MMA(1, 1, At, B1); PG8_BAR; PG8_SCHED;
	s_add_i32 s4, s4, s52
	v_lshl_add_u64 v[190:191], v[190:191], 0, s[12:13]
	s_mov_b32 m0, s4
	ds_read_b128 v[174:177], v161 offset:49152
	ds_read_b128 v[178:181], v161 offset:50176
	ds_read_b128 v[182:185], v161 offset:51200
	ds_read_b128 v[186:189], v161 offset:52224
	ds_read_b128 v[194:197], v161 offset:53248
	ds_read_b128 v[198:201], v161 offset:54272
	ds_read_b128 v[202:205], v161 offset:55296
	ds_read_b128 v[212:215], v161 offset:56320
	global_load_lds_dwordx4 v[190:191], off
	s_add_i32 m0, s4, 0x2000
	s_add_u32 s46, s46, 0x40080
	v_lshl_add_u64 v[190:191], v[216:217], 0, s[12:13]
	s_addc_u32 s47, s47, 0
	s_add_i32 s4, s5, s52
	global_load_lds_dwordx4 v[190:191], off
	v_lshl_add_u64 v[190:191], s[46:47], 0, v[192:193]
	s_mov_b32 m0, s4
	s_nop 0
	global_load_lds_dwordx4 v[190:191], off
	v_lshl_add_u64 v[190:191], s[46:47], 0, v[144:145]
	s_add_i32 m0, s4, 0x2000
	s_nop 0
	global_load_lds_dwordx4 v[190:191], off
	v_lshl_add_u64 v[190:191], v[218:219], 0, s[12:13]
	s_mov_b32 m0, s65
	s_nop 0
	global_load_lds_dwordx4 v[190:191], off
	v_lshl_add_u64 v[190:191], v[220:221], 0, s[12:13]
	s_mov_b32 m0, s66
	s_nop 0
	global_load_lds_dwordx4 v[190:191], off
	s_waitcnt lgkmcnt(0)
	s_barrier
	s_setprio 1
	s_waitcnt lgkmcnt(0)
	v_mfma_f32_16x16x32_bf16 v[60:63], v[120:123], v[174:177], v[60:63]
	v_mfma_f32_16x16x32_bf16 v[56:59], v[128:131], v[174:177], v[56:59]
	v_mfma_f32_16x16x32_bf16 v[48:51], v[120:123], v[182:185], v[48:51]
	v_mfma_f32_16x16x32_bf16 v[40:43], v[128:131], v[182:185], v[40:43]
	v_mfma_f32_16x16x32_bf16 v[32:35], v[120:123], v[194:197], v[32:35]
	v_mfma_f32_16x16x32_bf16 v[24:27], v[128:131], v[194:197], v[24:27]
	v_mfma_f32_16x16x32_bf16 v[16:19], v[120:123], v[202:205], v[16:19]
	v_mfma_f32_16x16x32_bf16 v[8:11], v[128:131], v[202:205], v[8:11]
	v_mfma_f32_16x16x32_bf16 v[60:63], v[124:127], v[178:181], v[60:63]
	v_mfma_f32_16x16x32_bf16 v[56:59], v[132:135], v[178:181], v[56:59]
	v_mfma_f32_16x16x32_bf16 v[48:51], v[124:127], v[186:189], v[48:51]
	v_mfma_f32_16x16x32_bf16 v[40:43], v[132:135], v[186:189], v[40:43]
	v_mfma_f32_16x16x32_bf16 v[32:35], v[124:127], v[198:201], v[32:35]
	v_mfma_f32_16x16x32_bf16 v[24:27], v[132:135], v[198:201], v[24:27]
	v_mfma_f32_16x16x32_bf16 v[16:19], v[124:127], v[212:215], v[16:19]
	v_mfma_f32_16x16x32_bf16 v[8:11], v[132:135], v[212:215], v[8:11]
	s_setprio 0
	s_setprio 1
	v_mfma_f32_16x16x32_bf16 v[52:55], v[154:157], v[174:177], v[52:55]
	s_add_i32 s91, s91, 2
	v_mfma_f32_16x16x32_bf16 v[44:47], v[166:169], v[174:177], v[44:47]
	s_add_u32 s44, s44, 0x100
	v_mfma_f32_16x16x32_bf16 v[36:39], v[154:157], v[182:185], v[36:39]
	s_addc_u32 s45, s45, 0
	v_mfma_f32_16x16x32_bf16 v[28:31], v[166:169], v[182:185], v[28:31]
	s_add_u32 s87, s87, 0x100
	v_mfma_f32_16x16x32_bf16 v[20:23], v[154:157], v[194:197], v[20:23]
	s_addc_u32 s90, s90, 0
	v_mfma_f32_16x16x32_bf16 v[12:15], v[166:169], v[194:197], v[12:15]
	s_add_u32 s46, s44, 0xfffc0080
	v_mfma_f32_16x16x32_bf16 v[4:7], v[154:157], v[202:205], v[4:7]
	s_addc_u32 s47, s45, -1
	v_mfma_f32_16x16x32_bf16 v[0:3], v[166:169], v[202:205], v[0:3]
	s_add_i32 s92, 0, 0x10000
	v_mfma_f32_16x16x32_bf16 v[52:55], v[162:165], v[178:181], v[52:55]
	s_cmp_eq_u32 s91, 12
	v_mfma_f32_16x16x32_bf16 v[44:47], v[170:173], v[178:181], v[44:47]
	s_cselect_b32 s55, s23, s47
	v_mfma_f32_16x16x32_bf16 v[36:39], v[162:165], v[186:189], v[36:39]
	s_cselect_b32 s54, s85, s46
	v_mfma_f32_16x16x32_bf16 v[28:31], v[170:173], v[186:189], v[28:31]
	s_cselect_b32 s47, s21, s90
	v_mfma_f32_16x16x32_bf16 v[20:23], v[162:165], v[198:201], v[20:23]
	s_cselect_b32 s46, s86, s87
	v_mfma_f32_16x16x32_bf16 v[12:15], v[170:173], v[198:201], v[12:15]
	s_add_i32 s4, 0, 0x14000
	v_mfma_f32_16x16x32_bf16 v[4:7], v[162:165], v[212:215], v[4:7]
	s_cmp_gt_u32 s91, 13
	v_mfma_f32_16x16x32_bf16 v[0:3], v[170:173], v[212:215], v[0:3]
	s_waitcnt vmcnt(8)
	s_setprio 0
	s_barrier
	s_barrier
	s_branch .LBB0_287
.Ldc_pg_first:
	s_add_u32 s46, s44, 0xfffc0080
	s_addc_u32 s47, s45, -1
	s_add_i32 s92, 0, 0x10000
	s_cmp_eq_u32 s91, 12
	s_cselect_b32 s55, s23, s47
	s_cselect_b32 s54, s85, s46
	s_cselect_b32 s47, s21, s90
	s_cselect_b32 s46, s86, s87
	s_add_i32 s4, 0, 0x14000
	v_add_u32_e32 v132, s92, v160
	v_add_u32_e32 v170, s4, v160
	ds_read_b128 v[120:123], v132
	ds_read_b128 v[124:127], v132 offset:1024
	ds_read_b128 v[128:131], v132 offset:2048
	ds_read_b128 v[132:135], v132 offset:3072
	ds_read_b128 v[154:157], v170
	ds_read_b128 v[162:165], v170 offset:1024
	ds_read_b128 v[166:169], v170 offset:2048
	ds_read_b128 v[170:173], v170 offset:3072
	v_lshl_add_u64 v[190:191], s[44:45], 0, v[150:151]
	s_add_i32 m0, s53, 0xc000
	ds_read_b128 v[174:177], v161
	ds_read_b128 v[178:181], v161 offset:1024
	ds_read_b128 v[182:185], v161 offset:2048
	ds_read_b128 v[186:189], v161 offset:3072
	ds_read_b128 v[194:197], v161 offset:4096
	ds_read_b128 v[198:201], v161 offset:5120
	ds_read_b128 v[202:205], v161 offset:6144
	ds_read_b128 v[212:215], v161 offset:7168
	global_load_lds_dwordx4 v[190:191], off
	v_lshl_add_u64 v[190:191], s[44:45], 0, v[152:153]
	s_add_i32 m0, s53, 0xe000
	s_nop 0
	global_load_lds_dwordx4 v[190:191], off
	s_waitcnt vmcnt(8)
	s_waitcnt lgkmcnt(0)
	s_barrier
; #define PG8_STAGE(bufoff, gbase, voff) do { _Pragma("unroll") for (int _i = 0; _i < 2; ++_i) \
;         __builtin_amdgcn_global_load_lds((const unsigned*)((const char*)(gbase) + (voff)[_i]), (LAS unsigned*)(lds + (bufoff) + ldsw + _i * 8192), 16, 0, 0); } while (0)
; #define PG8_LDA(dst, b, h) do { _Pragma("unroll") for (int m = 0; m < 4; ++m) _Pragma("unroll") for (int k = 0; k < 2; ++k) dst[m][k] = *(const LAS bf16x8*)(lds + PG8_SA(b, h) + aoff + m * 2048 + k * 1024); } while (0)
; #define PG8_MMA(ai, bj, At, Bt) do { __builtin_amdgcn_s_setprio(1); _Pragma("unroll") for (int m = 0; m < 4; ++m) _Pragma("unroll") for (int n = 0; n < 2; ++n) _Pragma("unroll") for (int k = 0; k < 2; ++k) \
;         acc[ai][bj][m][n] = __builtin_amdgcn_mfma_f32_16x16x32_bf16(Bt[n][k], At[m][k], acc[ai][bj][m][n], 0, 0, 0); __builtin_amdgcn_s_setprio(0); } while (0)
; #define PG8_WAIT_V(n) asm volatile("s_waitcnt vmcnt(" #n ")" ::: "memory")
; #define PG8_WAIT_L(n) asm volatile("s_waitcnt lgkmcnt(" #n ")" ::: "memory")
; #define PG8_BAR __builtin_amdgcn_s_barrier()
; #define PG8_SCHED __builtin_amdgcn_sched_barrier(0)
; template <class Epi, class Sched, bool ALIGN_EPI>
; __device__ __forceinline__ void gemm_phase(LAS unsigned char* lds, const Gemm g, const Sched& S, const Epi& E) {
;     ...
;             PG8_WAIT_V(8); PG8_WAIT_L(0); PG8_BAR; PG8_MMA(0, 0, At, B0); PG8_MMA(0, 1, At, B1); PG8_BAR; PG8_SCHED;
;             PG8_LDA(At, 0, 1); PG8_STAGE(PG8_SB(0, 0), b2, voffB); PG8_STAGE(PG8_SB(0, 1), b2 + hstepB, voffB); PG8_STAGE(PG8_SA(0, 0), a2, voffA);
;             PG8_WAIT_V(8); PG8_WAIT_L(0); PG8_BAR; PG8_MMA(1, 0, At, B0); PG8_MMA(1, 1, At, B1); PG8_BAR; PG8_SCHED;
	s_setprio 1
	s_waitcnt lgkmcnt(0)
	v_mfma_f32_16x16x32_bf16 v[140:143], v[120:123], v[174:177], 0
	v_mfma_f32_16x16x32_bf16 v[136:139], v[128:131], v[174:177], 0
	v_mfma_f32_16x16x32_bf16 v[108:111], v[120:123], v[182:185], 0
	v_mfma_f32_16x16x32_bf16 v[104:107], v[128:131], v[182:185], 0
	v_mfma_f32_16x16x32_bf16 v[92:95], v[120:123], v[194:197], 0
	v_mfma_f32_16x16x32_bf16 v[88:91], v[128:131], v[194:197], 0
	v_mfma_f32_16x16x32_bf16 v[76:79], v[120:123], v[202:205], 0
	v_mfma_f32_16x16x32_bf16 v[72:75], v[128:131], v[202:205], 0
	v_mfma_f32_16x16x32_bf16 v[140:143], v[124:127], v[178:181], v[140:143]
	v_mfma_f32_16x16x32_bf16 v[136:139], v[132:135], v[178:181], v[136:139]
	v_mfma_f32_16x16x32_bf16 v[108:111], v[124:127], v[186:189], v[108:111]
	v_mfma_f32_16x16x32_bf16 v[104:107], v[132:135], v[186:189], v[104:107]
	v_mfma_f32_16x16x32_bf16 v[92:95], v[124:127], v[198:201], v[92:95]
	v_mfma_f32_16x16x32_bf16 v[88:91], v[132:135], v[198:201], v[88:91]
	v_mfma_f32_16x16x32_bf16 v[76:79], v[124:127], v[212:215], v[76:79]
	v_mfma_f32_16x16x32_bf16 v[72:75], v[132:135], v[212:215], v[72:75]
	s_setprio 0
	s_setprio 1
	v_mfma_f32_16x16x32_bf16 v[116:119], v[154:157], v[174:177], 0
	v_mfma_f32_16x16x32_bf16 v[112:115], v[166:169], v[174:177], 0
	v_mfma_f32_16x16x32_bf16 v[100:103], v[154:157], v[182:185], 0
	v_mfma_f32_16x16x32_bf16 v[96:99], v[166:169], v[182:185], 0
	v_mfma_f32_16x16x32_bf16 v[84:87], v[154:157], v[194:197], 0
	v_mfma_f32_16x16x32_bf16 v[80:83], v[166:169], v[194:197], 0
	v_mfma_f32_16x16x32_bf16 v[68:71], v[154:157], v[202:205], 0
	v_mfma_f32_16x16x32_bf16 v[64:67], v[166:169], v[202:205], 0
	v_mfma_f32_16x16x32_bf16 v[116:119], v[162:165], v[178:181], v[116:119]
	v_mfma_f32_16x16x32_bf16 v[112:115], v[170:173], v[178:181], v[112:115]
	v_mfma_f32_16x16x32_bf16 v[100:103], v[162:165], v[186:189], v[100:103]
	v_mfma_f32_16x16x32_bf16 v[96:99], v[170:173], v[186:189], v[96:99]
	v_mfma_f32_16x16x32_bf16 v[84:87], v[162:165], v[198:201], v[84:87]
	v_mfma_f32_16x16x32_bf16 v[80:83], v[170:173], v[198:201], v[80:83]
	v_mfma_f32_16x16x32_bf16 v[68:71], v[162:165], v[212:215], v[68:71]
	v_mfma_f32_16x16x32_bf16 v[64:67], v[170:173], v[212:215], v[64:67]
	s_setprio 0
	s_barrier
	s_add_i32 s5, s92, s52
	v_lshl_add_u64 v[190:191], s[46:47], 0, v[192:193]
	s_mov_b32 m0, s5
	ds_read_b128 v[174:177], v161 offset:16384
	ds_read_b128 v[178:181], v161 offset:17408
	ds_read_b128 v[182:185], v161 offset:18432
	ds_read_b128 v[186:189], v161 offset:19456
	ds_read_b128 v[194:197], v161 offset:20480
	ds_read_b128 v[198:201], v161 offset:21504
	ds_read_b128 v[202:205], v161 offset:22528
	ds_read_b128 v[212:215], v161 offset:23552
	global_load_lds_dwordx4 v[190:191], off
	s_add_i32 m0, s5, 0x2000
	s_add_u32 vcc_lo, s46, 0x40000
	v_lshl_add_u64 v[216:217], s[46:47], 0, v[144:145]
	s_addc_u32 vcc_hi, s47, 0
	s_add_i32 s4, s4, s52
	global_load_lds_dwordx4 v[216:217], off
	v_lshl_add_u64 v[218:219], vcc, 0, v[192:193]
	s_mov_b32 m0, s4
	v_lshl_add_u64 v[220:221], s[54:55], 0, v[146:147]
	global_load_lds_dwordx4 v[218:219], off
	v_lshl_add_u64 v[218:219], vcc, 0, v[144:145]
	s_add_i32 m0, s4, 0x2000
	s_nop 0
	global_load_lds_dwordx4 v[218:219], off
	v_lshl_add_u64 v[218:219], s[54:55], 0, v[148:149]
	s_mov_b32 m0, s53
	s_nop 0
	global_load_lds_dwordx4 v[218:219], off
	s_mov_b32 m0, s56
	s_nop 0
	global_load_lds_dwordx4 v[220:221], off
	s_waitcnt vmcnt(8)
	s_waitcnt lgkmcnt(0)
	s_barrier
	s_setprio 1
	s_waitcnt lgkmcnt(0)
	v_mfma_f32_16x16x32_bf16 v[60:63], v[120:123], v[174:177], 0
	v_mfma_f32_16x16x32_bf16 v[56:59], v[128:131], v[174:177], 0
	v_mfma_f32_16x16x32_bf16 v[48:51], v[120:123], v[182:185], 0
	v_mfma_f32_16x16x32_bf16 v[40:43], v[128:131], v[182:185], 0
	v_mfma_f32_16x16x32_bf16 v[32:35], v[120:123], v[194:197], 0
	v_mfma_f32_16x16x32_bf16 v[24:27], v[128:131], v[194:197], 0
	v_mfma_f32_16x16x32_bf16 v[16:19], v[120:123], v[202:205], 0
	v_mfma_f32_16x16x32_bf16 v[8:11], v[128:131], v[202:205], 0
	v_mfma_f32_16x16x32_bf16 v[60:63], v[124:127], v[178:181], v[60:63]
	v_mfma_f32_16x16x32_bf16 v[56:59], v[132:135], v[178:181], v[56:59]
	v_mfma_f32_16x16x32_bf16 v[48:51], v[124:127], v[186:189], v[48:51]
	v_mfma_f32_16x16x32_bf16 v[40:43], v[132:135], v[186:189], v[40:43]
	v_mfma_f32_16x16x32_bf16 v[32:35], v[124:127], v[198:201], v[32:35]
	v_mfma_f32_16x16x32_bf16 v[24:27], v[132:135], v[198:201], v[24:27]
	v_mfma_f32_16x16x32_bf16 v[16:19], v[124:127], v[212:215], v[16:19]
	v_mfma_f32_16x16x32_bf16 v[8:11], v[132:135], v[212:215], v[8:11]
	s_setprio 0
	s_setprio 1
	v_mfma_f32_16x16x32_bf16 v[52:55], v[154:157], v[174:177], 0
	v_mfma_f32_16x16x32_bf16 v[44:47], v[166:169], v[174:177], 0
	v_mfma_f32_16x16x32_bf16 v[36:39], v[154:157], v[182:185], 0
	v_mfma_f32_16x16x32_bf16 v[28:31], v[166:169], v[182:185], 0
	v_mfma_f32_16x16x32_bf16 v[20:23], v[154:157], v[194:197], 0
	v_mfma_f32_16x16x32_bf16 v[12:15], v[166:169], v[194:197], 0
	v_mfma_f32_16x16x32_bf16 v[4:7], v[154:157], v[202:205], 0
	v_mfma_f32_16x16x32_bf16 v[0:3], v[166:169], v[202:205], 0
	v_mfma_f32_16x16x32_bf16 v[52:55], v[162:165], v[178:181], v[52:55]
	v_mfma_f32_16x16x32_bf16 v[44:47], v[170:173], v[178:181], v[44:47]
	v_mfma_f32_16x16x32_bf16 v[36:39], v[162:165], v[186:189], v[36:39]
	v_mfma_f32_16x16x32_bf16 v[28:31], v[170:173], v[186:189], v[28:31]
	v_mfma_f32_16x16x32_bf16 v[20:23], v[162:165], v[198:201], v[20:23]
	v_mfma_f32_16x16x32_bf16 v[12:15], v[170:173], v[198:201], v[12:15]
	v_mfma_f32_16x16x32_bf16 v[4:7], v[162:165], v[212:215], v[4:7]
	v_mfma_f32_16x16x32_bf16 v[0:3], v[170:173], v[212:215], v[0:3]
	s_setprio 0
	s_barrier
; #define PG8_STAGE(bufoff, gbase, voff) do { _Pragma("unroll") for (int _i = 0; _i < 2; ++_i) \
;         __builtin_amdgcn_global_load_lds((const unsigned*)((const char*)(gbase) + (voff)[_i]), (LAS unsigned*)(lds + (bufoff) + ldsw + _i * 8192), 16, 0, 0); } while (0)
; #define PG8_LDA(dst, b, h) do { _Pragma("unroll") for (int m = 0; m < 4; ++m) _Pragma("unroll") for (int k = 0; k < 2; ++k) dst[m][k] = *(const LAS bf16x8*)(lds + PG8_SA(b, h) + aoff + m * 2048 + k * 1024); } while (0)
; #define PG8_LDB(dst, b, h) do { _Pragma("unroll") for (int n = 0; n < 2; ++n) _Pragma("unroll") for (int k = 0; k < 2; ++k) dst[n][k] = *(const LAS bf16x8*)(lds + PG8_SB(b, h) + boff + n * 2048 + k * 1024); } while (0)
; #define PG8_MMA(ai, bj, At, Bt) do { __builtin_amdgcn_s_setprio(1); _Pragma("unroll") for (int m = 0; m < 4; ++m) _Pragma("unroll") for (int n = 0; n < 2; ++n) _Pragma("unroll") for (int k = 0; k < 2; ++k) \
;         acc[ai][bj][m][n] = __builtin_amdgcn_mfma_f32_16x16x32_bf16(Bt[n][k], At[m][k], acc[ai][bj][m][n], 0, 0, 0); __builtin_amdgcn_s_setprio(0); } while (0)
; #define PG8_WAIT_V(n) asm volatile("s_waitcnt vmcnt(" #n ")" ::: "memory")
; #define PG8_WAIT_L(n) asm volatile("s_waitcnt lgkmcnt(" #n ")" ::: "memory")
; #define PG8_BAR __builtin_amdgcn_s_barrier()
; #define PG8_SCHED __builtin_amdgcn_sched_barrier(0)
; template <class Epi, class Sched, bool ALIGN_EPI>
; __device__ __forceinline__ void gemm_phase(LAS unsigned char* lds, const Gemm g, const Sched& S, const Epi& E) {
;     ...
;             PG8_LDB(B0, 1, 0); PG8_LDB(B1, 1, 1); PG8_SCHED; PG8_LDA(At, 1, 0); PG8_STAGE(PG8_SA(0, 1), a2 + hstepA, voffA);
;             PG8_WAIT_V(8); PG8_WAIT_L(0); PG8_BAR; PG8_MMA(0, 0, At, B0); PG8_MMA(0, 1, At, B1); PG8_BAR; PG8_SCHED;
	s_add_i32 s4, 0, 0x18000
	s_add_i32 s5, 0, 0x1c000
	v_add_u32_e32 v132, s4, v160
	v_add_u32_e32 v170, s5, v160
	ds_read_b128 v[120:123], v132
	ds_read_b128 v[124:127], v132 offset:1024
	ds_read_b128 v[128:131], v132 offset:2048
	ds_read_b128 v[132:135], v132 offset:3072
	ds_read_b128 v[154:157], v170
	ds_read_b128 v[162:165], v170 offset:1024
	ds_read_b128 v[166:169], v170 offset:2048
	ds_read_b128 v[170:173], v170 offset:3072
	s_add_u32 s54, s54, 0x40000
	s_addc_u32 s55, s55, 0
	s_mov_b32 m0, s57
	v_lshl_add_u64 v[222:223], s[54:55], 0, v[148:149]
	ds_read_b128 v[174:177], v161 offset:32768
	ds_read_b128 v[178:181], v161 offset:33792
	ds_read_b128 v[182:185], v161 offset:34816
	ds_read_b128 v[186:189], v161 offset:35840
	ds_read_b128 v[194:197], v161 offset:36864
	ds_read_b128 v[198:201], v161 offset:37888
	ds_read_b128 v[202:205], v161 offset:38912
	ds_read_b128 v[212:215], v161 offset:39936
	global_load_lds_dwordx4 v[222:223], off
	v_lshl_add_u64 v[222:223], s[54:55], 0, v[146:147]
	s_mov_b32 m0, s58
	s_nop 0
	global_load_lds_dwordx4 v[222:223], off
	s_waitcnt vmcnt(8)
	s_waitcnt lgkmcnt(0)
	s_barrier
	s_setprio 1
	s_waitcnt lgkmcnt(0)
	v_mfma_f32_16x16x32_bf16 v[140:143], v[120:123], v[174:177], v[140:143]
	v_mfma_f32_16x16x32_bf16 v[136:139], v[128:131], v[174:177], v[136:139]
	v_mfma_f32_16x16x32_bf16 v[108:111], v[120:123], v[182:185], v[108:111]
	v_mfma_f32_16x16x32_bf16 v[104:107], v[128:131], v[182:185], v[104:107]
	v_mfma_f32_16x16x32_bf16 v[92:95], v[120:123], v[194:197], v[92:95]
	v_mfma_f32_16x16x32_bf16 v[88:91], v[128:131], v[194:197], v[88:91]
	v_mfma_f32_16x16x32_bf16 v[76:79], v[120:123], v[202:205], v[76:79]
	v_mfma_f32_16x16x32_bf16 v[72:75], v[128:131], v[202:205], v[72:75]
	v_mfma_f32_16x16x32_bf16 v[140:143], v[124:127], v[178:181], v[140:143]
	v_mfma_f32_16x16x32_bf16 v[136:139], v[132:135], v[178:181], v[136:139]
	v_mfma_f32_16x16x32_bf16 v[108:111], v[124:127], v[186:189], v[108:111]
	v_mfma_f32_16x16x32_bf16 v[104:107], v[132:135], v[186:189], v[104:107]
	v_mfma_f32_16x16x32_bf16 v[92:95], v[124:127], v[198:201], v[92:95]
	v_mfma_f32_16x16x32_bf16 v[88:91], v[132:135], v[198:201], v[88:91]
	v_mfma_f32_16x16x32_bf16 v[76:79], v[124:127], v[212:215], v[76:79]
	v_mfma_f32_16x16x32_bf16 v[72:75], v[132:135], v[212:215], v[72:75]
	s_setprio 0
	s_setprio 1
	v_mfma_f32_16x16x32_bf16 v[116:119], v[154:157], v[174:177], v[116:119]
	v_mfma_f32_16x16x32_bf16 v[112:115], v[166:169], v[174:177], v[112:115]
	v_mfma_f32_16x16x32_bf16 v[100:103], v[154:157], v[182:185], v[100:103]
	v_mfma_f32_16x16x32_bf16 v[96:99], v[166:169], v[182:185], v[96:99]
	v_mfma_f32_16x16x32_bf16 v[84:87], v[154:157], v[194:197], v[84:87]
	v_mfma_f32_16x16x32_bf16 v[80:83], v[166:169], v[194:197], v[80:83]
	v_mfma_f32_16x16x32_bf16 v[68:71], v[154:157], v[202:205], v[68:71]
	v_mfma_f32_16x16x32_bf16 v[64:67], v[166:169], v[202:205], v[64:67]
	v_mfma_f32_16x16x32_bf16 v[116:119], v[162:165], v[178:181], v[116:119]
	v_mfma_f32_16x16x32_bf16 v[112:115], v[170:173], v[178:181], v[112:115]
	v_mfma_f32_16x16x32_bf16 v[100:103], v[162:165], v[186:189], v[100:103]
	v_mfma_f32_16x16x32_bf16 v[96:99], v[170:173], v[186:189], v[96:99]
	v_mfma_f32_16x16x32_bf16 v[84:87], v[162:165], v[198:201], v[84:87]
	v_mfma_f32_16x16x32_bf16 v[80:83], v[170:173], v[198:201], v[80:83]
	v_mfma_f32_16x16x32_bf16 v[68:71], v[162:165], v[212:215], v[68:71]
	v_mfma_f32_16x16x32_bf16 v[64:67], v[170:173], v[212:215], v[64:67]
	s_setprio 0
	s_barrier
; #define PG8_STAGE(bufoff, gbase, voff) do { _Pragma("unroll") for (int _i = 0; _i < 2; ++_i) \
;         __builtin_amdgcn_global_load_lds((const unsigned*)((const char*)(gbase) + (voff)[_i]), (LAS unsigned*)(lds + (bufoff) + ldsw + _i * 8192), 16, 0, 0); } while (0)
; #define PG8_LDA(dst, b, h) do { _Pragma("unroll") for (int m = 0; m < 4; ++m) _Pragma("unroll") for (int k = 0; k < 2; ++k) dst[m][k] = *(const LAS bf16x8*)(lds + PG8_SA(b, h) + aoff + m * 2048 + k * 1024); } while (0)
; #define PG8_MMA(ai, bj, At, Bt) do { __builtin_amdgcn_s_setprio(1); _Pragma("unroll") for (int m = 0; m < 4; ++m) _Pragma("unroll") for (int n = 0; n < 2; ++n) _Pragma("unroll") for (int k = 0; k < 2; ++k) \
;         acc[ai][bj][m][n] = __builtin_amdgcn_mfma_f32_16x16x32_bf16(Bt[n][k], At[m][k], acc[ai][bj][m][n], 0, 0, 0); __builtin_amdgcn_s_setprio(0); } while (0)
; #define PG8_WAIT_V(n) asm volatile("s_waitcnt vmcnt(" #n ")" ::: "memory")
; #define PG8_WAIT_L(n) asm volatile("s_waitcnt lgkmcnt(" #n ")" ::: "memory")
; #define PG8_BAR __builtin_amdgcn_s_barrier()
; #define PG8_SCHED __builtin_amdgcn_sched_barrier(0)
; template <class Epi, class Sched, bool ALIGN_EPI>
; __device__ __forceinline__ void gemm_phase(LAS unsigned char* lds, const Gemm g, const Sched& S, const Epi& E) {
;     ...
;         for (int t = 0; t < nt; t += 2) {
;             const bool last = (t == nt - 2);
;             const char* a1 = cA + (size_t)(t + 1) * kstep;
;             const char* a2 = last ? nA : cA + (size_t)(t + 2) * kstep; const char* b2 = last ? nB : cB + (size_t)(t + 2) * kstep;
;             const char* a3 = a2 + kstep; const char* b3 = b2 + kstep;
;     ...
;             PG8_LDA(At, 1, 1); PG8_STAGE(PG8_SB(1, 0), b3, voffB); PG8_STAGE(PG8_SB(1, 1), b3 + hstepB, voffB); PG8_STAGE(PG8_SA(1, 0), a3, voffA);
;             PG8_WAIT_V(8); PG8_WAIT_L(0); PG8_BAR; PG8_MMA(1, 0, At, B0); PG8_MMA(1, 1, At, B1); PG8_BAR; PG8_SCHED;
	s_add_i32 s4, s4, s52
	v_lshl_add_u64 v[190:191], v[190:191], 0, s[12:13]
	s_mov_b32 m0, s4
	ds_read_b128 v[174:177], v161 offset:49152
	ds_read_b128 v[178:181], v161 offset:50176
	ds_read_b128 v[182:185], v161 offset:51200
	ds_read_b128 v[186:189], v161 offset:52224
	ds_read_b128 v[194:197], v161 offset:53248
	ds_read_b128 v[198:201], v161 offset:54272
	ds_read_b128 v[202:205], v161 offset:55296
	ds_read_b128 v[212:215], v161 offset:56320
	global_load_lds_dwordx4 v[190:191], off
	s_add_i32 m0, s4, 0x2000
	s_add_u32 s46, s46, 0x40080
	v_lshl_add_u64 v[190:191], v[216:217], 0, s[12:13]
	s_addc_u32 s47, s47, 0
	s_add_i32 s4, s5, s52
	global_load_lds_dwordx4 v[190:191], off
	v_lshl_add_u64 v[190:191], s[46:47], 0, v[192:193]
	s_mov_b32 m0, s4
	s_nop 0
	global_load_lds_dwordx4 v[190:191], off
	v_lshl_add_u64 v[190:191], s[46:47], 0, v[144:145]
	s_add_i32 m0, s4, 0x2000
	s_nop 0
	global_load_lds_dwordx4 v[190:191], off
	v_lshl_add_u64 v[190:191], v[218:219], 0, s[12:13]
	s_mov_b32 m0, s65
	s_nop 0
	global_load_lds_dwordx4 v[190:191], off
	v_lshl_add_u64 v[190:191], v[220:221], 0, s[12:13]
	s_mov_b32 m0, s66
	s_nop 0
	global_load_lds_dwordx4 v[190:191], off
	s_waitcnt vmcnt(8)
	s_waitcnt lgkmcnt(0)
	s_barrier
	s_setprio 1
	s_waitcnt lgkmcnt(0)
	v_mfma_f32_16x16x32_bf16 v[60:63], v[120:123], v[174:177], v[60:63]
	v_mfma_f32_16x16x32_bf16 v[56:59], v[128:131], v[174:177], v[56:59]
	v_mfma_f32_16x16x32_bf16 v[48:51], v[120:123], v[182:185], v[48:51]
	v_mfma_f32_16x16x32_bf16 v[40:43], v[128:131], v[182:185], v[40:43]
	v_mfma_f32_16x16x32_bf16 v[32:35], v[120:123], v[194:197], v[32:35]
	v_mfma_f32_16x16x32_bf16 v[24:27], v[128:131], v[194:197], v[24:27]
	v_mfma_f32_16x16x32_bf16 v[16:19], v[120:123], v[202:205], v[16:19]
	v_mfma_f32_16x16x32_bf16 v[8:11], v[128:131], v[202:205], v[8:11]
	v_mfma_f32_16x16x32_bf16 v[60:63], v[124:127], v[178:181], v[60:63]
	v_mfma_f32_16x16x32_bf16 v[56:59], v[132:135], v[178:181], v[56:59]
	v_mfma_f32_16x16x32_bf16 v[48:51], v[124:127], v[186:189], v[48:51]
	v_mfma_f32_16x16x32_bf16 v[40:43], v[132:135], v[186:189], v[40:43]
	v_mfma_f32_16x16x32_bf16 v[32:35], v[124:127], v[198:201], v[32:35]
	v_mfma_f32_16x16x32_bf16 v[24:27], v[132:135], v[198:201], v[24:27]
	v_mfma_f32_16x16x32_bf16 v[16:19], v[124:127], v[212:215], v[16:19]
	v_mfma_f32_16x16x32_bf16 v[8:11], v[132:135], v[212:215], v[8:11]
	s_setprio 0
	s_setprio 1
	v_mfma_f32_16x16x32_bf16 v[52:55], v[154:157], v[174:177], v[52:55]
	s_add_i32 s91, s91, 2
	v_mfma_f32_16x16x32_bf16 v[44:47], v[166:169], v[174:177], v[44:47]
	s_add_u32 s44, s44, 0x100
	v_mfma_f32_16x16x32_bf16 v[36:39], v[154:157], v[182:185], v[36:39]
	s_addc_u32 s45, s45, 0
	v_mfma_f32_16x16x32_bf16 v[28:31], v[166:169], v[182:185], v[28:31]
	s_add_u32 s87, s87, 0x100
	v_mfma_f32_16x16x32_bf16 v[20:23], v[154:157], v[194:197], v[20:23]
	s_addc_u32 s90, s90, 0
	v_mfma_f32_16x16x32_bf16 v[12:15], v[166:169], v[194:197], v[12:15]
	s_add_u32 s46, s44, 0xfffc0080
	v_mfma_f32_16x16x32_bf16 v[4:7], v[154:157], v[202:205], v[4:7]
	s_addc_u32 s47, s45, -1
	v_mfma_f32_16x16x32_bf16 v[0:3], v[166:169], v[202:205], v[0:3]
	s_add_i32 s92, 0, 0x10000
	v_mfma_f32_16x16x32_bf16 v[52:55], v[162:165], v[178:181], v[52:55]
	s_cmp_eq_u32 s91, 12
	v_mfma_f32_16x16x32_bf16 v[44:47], v[170:173], v[178:181], v[44:47]
	s_cselect_b32 s55, s23, s47
	v_mfma_f32_16x16x32_bf16 v[36:39], v[162:165], v[186:189], v[36:39]
	s_cselect_b32 s54, s85, s46
	v_mfma_f32_16x16x32_bf16 v[28:31], v[170:173], v[186:189], v[28:31]
	s_cselect_b32 s47, s21, s90
	v_mfma_f32_16x16x32_bf16 v[20:23], v[162:165], v[198:201], v[20:23]
	s_cselect_b32 s46, s86, s87
	v_mfma_f32_16x16x32_bf16 v[12:15], v[170:173], v[198:201], v[12:15]
	s_add_i32 s4, 0, 0x14000
	v_mfma_f32_16x16x32_bf16 v[4:7], v[162:165], v[212:215], v[4:7]
	s_cmp_gt_u32 s91, 13
	v_mfma_f32_16x16x32_bf16 v[0:3], v[170:173], v[212:215], v[0:3]
	s_setprio 0
	s_barrier

; #define LAS __attribute__((address_space(3)))
; __device__ __forceinline__ float rsq(float x) { return __builtin_amdgcn_rsqf(x); }
; __device__ __forceinline__ float sum4(f32x4 v) { return (v[0] + v[1]) + (v[2] + v[3]); }
; __device__ __forceinline__ float row_rstd16(const float* statx, int row) {
;     const f32x4* p = (const f32x4*)(statx + (size_t)row * 16);
;     const f32x4 a = p[0], b = p[1], c = p[2], d = p[3];
;     return rsq(((sum4(a) + sum4(b)) + (sum4(c) + sum4(d))) * (1.0f / DM) + EPS);
; }
; __device__ __forceinline__ void tile_rstd_to_lds(const float* statx, int row0, LAS float* rsl, int wr, int wc, int fr, int fq) {
;     const int t = (wr * 4 + wc) * 64 + fq * 16 + fr;
;     if (t < 256) rsl[t] = row_rstd16(statx, row0 + t);
;     __device__ __forceinline__ void operator()(const f32x4 (&acc)[2][2][4][2], const Unit& u, int wr, int wc, int fr, int fq) const {
;         const int b = u.pm >> 3, col0 = u.pn * 256 + wc * 32 + 8 * fq;
;         f32x4 sw[2][2];
; #pragma unroll
;         for (int bj = 0; bj < 2; ++bj)
; #pragma unroll
;             for (int n = 0; n < 2; ++n) sw[bj][n] = *(const f32x4*)(shw + (size_t)b * DFF + col0 + 128 * bj + 4 * n);
;         tile_rstd_to_lds(statx, u.pm * 256, rsl, wr, wc, fr, fq);
.LBB0_290:
	s_add_u32 vcc_lo, s85, 0x40080
	s_addc_u32 vcc_hi, s23, 0
	v_lshl_add_u64 v[190:191], vcc, 0, v[150:151]
	s_add_i32 m0, s53, 0xc000
	s_nop 0
	global_load_lds_dwordx4 v[190:191], off
	v_lshl_add_u64 v[190:191], vcc, 0, v[152:153]
	s_add_i32 m0, s53, 0xe000
	s_nop 0
	global_load_lds_dwordx4 v[190:191], off
	s_ashr_i32 s44, s81, 3
	s_lshl_b32 s4, s84, 8
	s_ashr_i32 s45, s44, 31
	v_and_b32_e32 v224, 3, v242
	v_lshrrev_b32_e32 v225, 2, v242
	v_lshl_add_u32 v226, v224, 4, v225
	v_lshlrev_b32_e32 v226, 2, v226
	v_sub_u32_e32 v227, v224, v159
	v_lshlrev_b32_e32 v227, 3, v227
	v_sub_u32_e32 v224, v225, v158
	v_mov_b32_e32 v155, v159
	v_mov_b32_e32 v154, v158
	s_or_b32 s4, s4, s64
	s_lshl_b64 s[44:45], s[44:45], 14
	s_add_u32 s44, s59, s44
	v_lshl_add_u32 v156, v155, 3, s4
	s_addc_u32 s45, s62, s45
	v_ashrrev_i32_e32 v157, 31, v156
	v_lshl_add_u64 v[124:125], v[156:157], 2, s[44:45]
	global_load_dwordx4 v[128:131], v[124:125], off offset:16
	global_load_dwordx4 v[132:135], v[124:125], off
	global_load_dwordx4 v[120:123], v[124:125], off offset:528
	s_nop 0
	global_load_dwordx4 v[124:127], v[124:125], off offset:512
	v_lshlrev_b32_e32 v155, 4, v155
	v_add3_u32 v155, s67, v154, v155
	s_movk_i32 s4, 0x100
	s_lshl_b32 s21, s81, 8
	v_cmp_gt_i32_e32 vcc, s4, v155
	s_and_saveexec_b64 s[44:45], vcc
	s_load_dword s85, s[0:1], 0xd8
	s_mov_b32 s90, 0xfffe8000
	s_mov_b32 s91, 0xffff4000
	s_cbranch_execz .LBB0_292
	v_add_u32_e32 v162, s21, v155
	v_ashrrev_i32_e32 v163, 31, v162
	v_lshlrev_b64 v[162:163], 6, v[162:163]
	v_lshl_add_u64 v[174:175], s[6:7], 0, v[162:163]
	global_load_dwordx4 v[162:165], v[174:175], off
	global_load_dwordx4 v[166:169], v[174:175], off offset:32
	global_load_dwordx4 v[170:173], v[174:175], off offset:16
	s_nop 0
	global_load_dwordx4 v[174:177], v[174:175], off offset:48
	v_lshl_add_u32 v155, v155, 2, 0
	v_add_u32_e32 v155, 0x20000, v155
	s_waitcnt vmcnt(0)
	v_mov_b32_e32 v178, v162
	v_mov_b32_e32 v179, v166
	v_mov_b32_e32 v166, v163
	v_mov_b32_e32 v162, v164
	v_mov_b32_e32 v163, v168
	v_mov_b32_e32 v168, v165
	v_mov_b32_e32 v164, v170
	v_mov_b32_e32 v165, v174
	v_mov_b32_e32 v174, v171
	v_mov_b32_e32 v170, v172
	v_mov_b32_e32 v171, v176
	v_mov_b32_e32 v176, v173
	v_pk_add_f32 v[166:167], v[178:179], v[166:167]
	v_pk_add_f32 v[162:163], v[162:163], v[168:169]
	v_pk_add_f32 v[164:165], v[164:165], v[174:175]
	v_pk_add_f32 v[168:169], v[170:171], v[176:177]
	v_pk_add_f32 v[162:163], v[166:167], v[162:163]
	v_pk_add_f32 v[164:165], v[164:165], v[168:169]
	s_nop 0
	v_pk_add_f32 v[162:163], v[162:163], v[164:165]
	s_nop 0
	v_add_f32_e32 v162, v162, v163
	v_fmamk_f32 v162, v162, 0x3a800000, v241
	v_rsq_f32_e32 v162, v162
	ds_write_b32 v155, v162

; #define PG8_STAGE(bufoff, gbase, voff) do { _Pragma("unroll") for (int _i = 0; _i < 2; ++_i) \
;         __builtin_amdgcn_global_load_lds((const unsigned*)((const char*)(gbase) + (voff)[_i]), (LAS unsigned*)(lds + (bufoff) + ldsw + _i * 8192), 16, 0, 0); } while (0)
; #define PG8_LDA(dst, b, h) do { _Pragma("unroll") for (int m = 0; m < 4; ++m) _Pragma("unroll") for (int k = 0; k < 2; ++k) dst[m][k] = *(const LAS bf16x8*)(lds + PG8_SA(b, h) + aoff + m * 2048 + k * 1024); } while (0)
; #define PG8_LDB(dst, b, h) do { _Pragma("unroll") for (int n = 0; n < 2; ++n) _Pragma("unroll") for (int k = 0; k < 2; ++k) dst[n][k] = *(const LAS bf16x8*)(lds + PG8_SB(b, h) + boff + n * 2048 + k * 1024); } while (0)
; #define PG8_MMA(ai, bj, At, Bt) do { __builtin_amdgcn_s_setprio(1); _Pragma("unroll") for (int m = 0; m < 4; ++m) _Pragma("unroll") for (int n = 0; n < 2; ++n) _Pragma("unroll") for (int k = 0; k < 2; ++k) \
;         acc[ai][bj][m][n] = __builtin_amdgcn_mfma_f32_16x16x32_bf16(Bt[n][k], At[m][k], acc[ai][bj][m][n], 0, 0, 0); __builtin_amdgcn_s_setprio(0); } while (0)
; #define PG8_BAR __builtin_amdgcn_s_barrier()
; template <class Epi, class Sched, bool ALIGN_EPI>
; __device__ __forceinline__ void gemm_phase(LAS unsigned char* lds, const Gemm g, const Sched& S, const Epi& E) {
;     ...
;         const bool has_next = S.next(ui + 1, nxt);
;         const char* nA = has_next ? (const char*)g.A + (size_t)nxt.pm * tstepA : cA; const char* nB = has_next ? (const char*)g.Bt + (size_t)nxt.pn * tstepB : cB;
;         for (int t = 0; t < nt; t += 2) {
;             const bool last = (t == nt - 2);
;             const char* a1 = cA + (size_t)(t + 1) * kstep;
;             const char* a2 = last ? nA : cA + (size_t)(t + 2) * kstep; const char* b2 = last ? nB : cB + (size_t)(t + 2) * kstep;
;             const char* a3 = a2 + kstep; const char* b3 = b2 + kstep;
;             PG8_LDB(B0, 0, 0); PG8_LDB(B1, 0, 1); PG8_SCHED; PG8_LDA(At, 0, 0); PG8_STAGE(PG8_SA(1, 1), a1 + hstepA, voffA);
;             PG8_WAIT_V(8); PG8_WAIT_L(0); PG8_BAR; PG8_MMA(0, 0, At, B0); PG8_MMA(0, 1, At, B1); PG8_BAR; PG8_SCHED;
;             PG8_LDA(At, 0, 1); PG8_STAGE(PG8_SB(0, 0), b2, voffB); PG8_STAGE(PG8_SB(0, 1), b2 + hstepB, voffB); PG8_STAGE(PG8_SA(0, 0), a2, voffA);
;             PG8_WAIT_V(8); PG8_WAIT_L(0); PG8_BAR; PG8_MMA(1, 0, At, B0); PG8_MMA(1, 1, At, B1); PG8_BAR; PG8_SCHED;
.LBB0_315:
	s_ashr_i32 s63, s62, 31
	s_lshl_b64 s[54:55], s[62:63], 19
	s_add_u32 s80, s33, s54
	s_addc_u32 s81, s51, s55
	s_and_b64 s[54:55], s[42:43], exec
	s_cselect_b32 s56, s81, s45
	s_cselect_b32 s57, s80, s44
	s_ashr_i32 s59, s58, 31
	s_lshl_b64 s[54:55], s[58:59], 19
	v_readlane_b32 s52, v255, 46
	s_add_u32 s84, s52, s54
	s_addc_u32 s85, s87, s55
	s_and_b64 s[54:55], s[42:43], exec
	s_cselect_b32 s59, s85, s47
	s_cselect_b32 s63, s84, s46
	s_add_u32 s44, s44, 0x40080
	s_addc_u32 s45, s45, 0
	s_add_u32 s64, s46, 0x100
	s_addc_u32 s65, s47, 0
	s_mov_b32 s92, -2
	s_cmp_eq_u32 s5, 1
	s_cbranch_scc1 .Ldc_pf_first
	s_add_u32 s46, s44, 0xfffc0080
	s_addc_u32 s47, s45, -1
	s_add_i32 s52, 0, 0x10000
	s_cmp_eq_u32 s92, 12
	s_cselect_b32 s55, s56, s47
	s_cselect_b32 s54, s57, s46
	s_cselect_b32 s47, s59, s65
	s_cselect_b32 s46, s63, s64
	s_add_i32 s53, 0, 0x14000
	v_add_u32_e32 v140, s52, v247
	v_add_u32_e32 v156, s53, v247
	ds_read_b128 v[104:107], v140
	ds_read_b128 v[112:115], v140 offset:1024
	ds_read_b128 v[136:139], v140 offset:2048
	ds_read_b128 v[140:143], v140 offset:3072
	ds_read_b128 v[144:147], v156
	ds_read_b128 v[148:151], v156 offset:1024
	ds_read_b128 v[152:155], v156 offset:2048
	ds_read_b128 v[156:159], v156 offset:3072
	ds_read_b128 v[160:163], v248
	ds_read_b128 v[164:167], v248 offset:1024
	ds_read_b128 v[168:171], v248 offset:2048
	ds_read_b128 v[172:175], v248 offset:3072
	ds_read_b128 v[176:179], v248 offset:4096
	ds_read_b128 v[180:183], v248 offset:5120
	ds_read_b128 v[184:187], v248 offset:6144
	ds_read_b128 v[188:191], v248 offset:7168
	s_waitcnt lgkmcnt(0)
	s_barrier
	s_setprio 1
	s_waitcnt lgkmcnt(0)
	v_mfma_f32_16x16x32_bf16 v[132:135], v[104:107], v[160:163], 0
	v_mfma_f32_16x16x32_bf16 v[128:131], v[136:139], v[160:163], 0
	v_mfma_f32_16x16x32_bf16 v[116:119], v[104:107], v[168:171], 0
	v_mfma_f32_16x16x32_bf16 v[108:111], v[136:139], v[168:171], 0
	v_mfma_f32_16x16x32_bf16 v[96:99], v[104:107], v[176:179], 0
	v_mfma_f32_16x16x32_bf16 v[88:91], v[136:139], v[176:179], 0
	v_mfma_f32_16x16x32_bf16 v[80:83], v[104:107], v[184:187], 0
	v_mfma_f32_16x16x32_bf16 v[72:75], v[136:139], v[184:187], 0
	v_mfma_f32_16x16x32_bf16 v[132:135], v[112:115], v[164:167], v[132:135]
	v_mfma_f32_16x16x32_bf16 v[128:131], v[140:143], v[164:167], v[128:131]
	v_mfma_f32_16x16x32_bf16 v[116:119], v[112:115], v[172:175], v[116:119]
	v_mfma_f32_16x16x32_bf16 v[108:111], v[140:143], v[172:175], v[108:111]
	v_mfma_f32_16x16x32_bf16 v[96:99], v[112:115], v[180:183], v[96:99]
	v_mfma_f32_16x16x32_bf16 v[88:91], v[140:143], v[180:183], v[88:91]
	v_mfma_f32_16x16x32_bf16 v[80:83], v[112:115], v[188:191], v[80:83]
	v_mfma_f32_16x16x32_bf16 v[72:75], v[140:143], v[188:191], v[72:75]
	s_setprio 0
	s_setprio 1
	v_mfma_f32_16x16x32_bf16 v[124:127], v[144:147], v[160:163], 0
	v_mfma_f32_16x16x32_bf16 v[120:123], v[152:155], v[160:163], 0
	v_mfma_f32_16x16x32_bf16 v[100:103], v[144:147], v[168:171], 0
	v_mfma_f32_16x16x32_bf16 v[92:95], v[152:155], v[168:171], 0
	v_mfma_f32_16x16x32_bf16 v[84:87], v[144:147], v[176:179], 0
	v_mfma_f32_16x16x32_bf16 v[76:79], v[152:155], v[176:179], 0
	v_mfma_f32_16x16x32_bf16 v[68:71], v[144:147], v[184:187], 0
	v_mfma_f32_16x16x32_bf16 v[64:67], v[152:155], v[184:187], 0
	v_mfma_f32_16x16x32_bf16 v[124:127], v[148:151], v[164:167], v[124:127]
	v_mfma_f32_16x16x32_bf16 v[120:123], v[156:159], v[164:167], v[120:123]
	v_mfma_f32_16x16x32_bf16 v[100:103], v[148:151], v[172:175], v[100:103]
	v_mfma_f32_16x16x32_bf16 v[92:95], v[156:159], v[172:175], v[92:95]
	v_mfma_f32_16x16x32_bf16 v[84:87], v[148:151], v[180:183], v[84:87]
	v_mfma_f32_16x16x32_bf16 v[76:79], v[156:159], v[180:183], v[76:79]
	v_mfma_f32_16x16x32_bf16 v[68:71], v[148:151], v[188:191], v[68:71]
	v_mfma_f32_16x16x32_bf16 v[64:67], v[156:159], v[188:191], v[64:67]
	s_setprio 0
	s_barrier
	s_add_i32 s52, s52, s50
	v_lshl_add_u64 v[194:195], s[46:47], 0, v[216:217]
	s_mov_b32 m0, s52
	ds_read_b128 v[160:163], v248 offset:16384
	ds_read_b128 v[164:167], v248 offset:17408
	ds_read_b128 v[168:171], v248 offset:18432
	ds_read_b128 v[172:175], v248 offset:19456
	ds_read_b128 v[176:179], v248 offset:20480
	ds_read_b128 v[180:183], v248 offset:21504
	ds_read_b128 v[184:187], v248 offset:22528
	ds_read_b128 v[188:191], v248 offset:23552
	global_load_lds_dwordx4 v[194:195], off
	s_add_i32 m0, s52, 0x2000
	s_add_u32 vcc_lo, s46, 0x40000
	v_lshl_add_u64 v[196:197], s[46:47], 0, v[212:213]
	s_addc_u32 vcc_hi, s47, 0
	s_add_i32 s52, s53, s50
	global_load_lds_dwordx4 v[196:197], off
	v_lshl_add_u64 v[198:199], vcc, 0, v[216:217]
	s_mov_b32 m0, s52
	v_lshl_add_u64 v[200:201], s[54:55], 0, v[214:215]
	global_load_lds_dwordx4 v[198:199], off
	v_lshl_add_u64 v[198:199], vcc, 0, v[212:213]
	s_add_i32 m0, s52, 0x2000
	s_nop 0
	global_load_lds_dwordx4 v[198:199], off
	v_lshl_add_u64 v[198:199], s[54:55], 0, v[218:219]
	s_mov_b32 m0, s48
	s_nop 0
	global_load_lds_dwordx4 v[198:199], off
	s_mov_b32 m0, s49
	s_nop 0
	global_load_lds_dwordx4 v[200:201], off
	s_waitcnt lgkmcnt(0)
	s_barrier
; #define PG8_STAGE(bufoff, gbase, voff) do { _Pragma("unroll") for (int _i = 0; _i < 2; ++_i) \
;         __builtin_amdgcn_global_load_lds((const unsigned*)((const char*)(gbase) + (voff)[_i]), (LAS unsigned*)(lds + (bufoff) + ldsw + _i * 8192), 16, 0, 0); } while (0)
; #define PG8_LDA(dst, b, h) do { _Pragma("unroll") for (int m = 0; m < 4; ++m) _Pragma("unroll") for (int k = 0; k < 2; ++k) dst[m][k] = *(const LAS bf16x8*)(lds + PG8_SA(b, h) + aoff + m * 2048 + k * 1024); } while (0)
; #define PG8_LDB(dst, b, h) do { _Pragma("unroll") for (int n = 0; n < 2; ++n) _Pragma("unroll") for (int k = 0; k < 2; ++k) dst[n][k] = *(const LAS bf16x8*)(lds + PG8_SB(b, h) + boff + n * 2048 + k * 1024); } while (0)
; #define PG8_MMA(ai, bj, At, Bt) do { __builtin_amdgcn_s_setprio(1); _Pragma("unroll") for (int m = 0; m < 4; ++m) _Pragma("unroll") for (int n = 0; n < 2; ++n) _Pragma("unroll") for (int k = 0; k < 2; ++k) \
;         acc[ai][bj][m][n] = __builtin_amdgcn_mfma_f32_16x16x32_bf16(Bt[n][k], At[m][k], acc[ai][bj][m][n], 0, 0, 0); __builtin_amdgcn_s_setprio(0); } while (0)
; #define PG8_WAIT_V(n) asm volatile("s_waitcnt vmcnt(" #n ")" ::: "memory")
; #define PG8_WAIT_L(n) asm volatile("s_waitcnt lgkmcnt(" #n ")" ::: "memory")
; #define PG8_BAR __builtin_amdgcn_s_barrier()
; #define PG8_SCHED __builtin_amdgcn_sched_barrier(0)
; template <class Epi, class Sched, bool ALIGN_EPI>
; __device__ __forceinline__ void gemm_phase(LAS unsigned char* lds, const Gemm g, const Sched& S, const Epi& E) {
;     ...
;             PG8_WAIT_V(8); PG8_WAIT_L(0); PG8_BAR; PG8_MMA(1, 0, At, B0); PG8_MMA(1, 1, At, B1); PG8_BAR; PG8_SCHED;
;             PG8_LDB(B0, 1, 0); PG8_LDB(B1, 1, 1); PG8_SCHED; PG8_LDA(At, 1, 0); PG8_STAGE(PG8_SA(0, 1), a2 + hstepA, voffA);
;             PG8_WAIT_V(8); PG8_WAIT_L(0); PG8_BAR; PG8_MMA(0, 0, At, B0); PG8_MMA(0, 1, At, B1); PG8_BAR; PG8_SCHED;
	s_setprio 1
	s_waitcnt lgkmcnt(0)
	v_mfma_f32_16x16x32_bf16 v[60:63], v[104:107], v[160:163], 0
	v_mfma_f32_16x16x32_bf16 v[56:59], v[136:139], v[160:163], 0
	v_mfma_f32_16x16x32_bf16 v[44:47], v[104:107], v[168:171], 0
	v_mfma_f32_16x16x32_bf16 v[40:43], v[136:139], v[168:171], 0
	v_mfma_f32_16x16x32_bf16 v[32:35], v[104:107], v[176:179], 0
	v_mfma_f32_16x16x32_bf16 v[24:27], v[136:139], v[176:179], 0
	v_mfma_f32_16x16x32_bf16 v[16:19], v[104:107], v[184:187], 0
	v_mfma_f32_16x16x32_bf16 v[8:11], v[136:139], v[184:187], 0
	v_mfma_f32_16x16x32_bf16 v[60:63], v[112:115], v[164:167], v[60:63]
	v_mfma_f32_16x16x32_bf16 v[56:59], v[140:143], v[164:167], v[56:59]
	v_mfma_f32_16x16x32_bf16 v[44:47], v[112:115], v[172:175], v[44:47]
	v_mfma_f32_16x16x32_bf16 v[40:43], v[140:143], v[172:175], v[40:43]
	v_mfma_f32_16x16x32_bf16 v[32:35], v[112:115], v[180:183], v[32:35]
	v_mfma_f32_16x16x32_bf16 v[24:27], v[140:143], v[180:183], v[24:27]
	v_mfma_f32_16x16x32_bf16 v[16:19], v[112:115], v[188:191], v[16:19]
	v_mfma_f32_16x16x32_bf16 v[8:11], v[140:143], v[188:191], v[8:11]
	s_setprio 0
	s_setprio 1
	v_mfma_f32_16x16x32_bf16 v[52:55], v[144:147], v[160:163], 0
	v_mfma_f32_16x16x32_bf16 v[48:51], v[152:155], v[160:163], 0
	v_mfma_f32_16x16x32_bf16 v[36:39], v[144:147], v[168:171], 0
	v_mfma_f32_16x16x32_bf16 v[28:31], v[152:155], v[168:171], 0
	v_mfma_f32_16x16x32_bf16 v[20:23], v[144:147], v[176:179], 0
	v_mfma_f32_16x16x32_bf16 v[12:15], v[152:155], v[176:179], 0
	v_mfma_f32_16x16x32_bf16 v[4:7], v[144:147], v[184:187], 0
	v_mfma_f32_16x16x32_bf16 v[0:3], v[152:155], v[184:187], 0
	v_mfma_f32_16x16x32_bf16 v[52:55], v[148:151], v[164:167], v[52:55]
	v_mfma_f32_16x16x32_bf16 v[48:51], v[156:159], v[164:167], v[48:51]
	v_mfma_f32_16x16x32_bf16 v[36:39], v[148:151], v[172:175], v[36:39]
	v_mfma_f32_16x16x32_bf16 v[28:31], v[156:159], v[172:175], v[28:31]
	v_mfma_f32_16x16x32_bf16 v[20:23], v[148:151], v[180:183], v[20:23]
	v_mfma_f32_16x16x32_bf16 v[12:15], v[156:159], v[180:183], v[12:15]
	v_mfma_f32_16x16x32_bf16 v[4:7], v[148:151], v[188:191], v[4:7]
	v_mfma_f32_16x16x32_bf16 v[0:3], v[156:159], v[188:191], v[0:3]
	s_setprio 0
	s_barrier
	s_add_i32 s52, 0, 0x18000
	s_add_i32 s53, 0, 0x1c000
	v_add_u32_e32 v140, s52, v247
	v_add_u32_e32 v156, s53, v247
	ds_read_b128 v[104:107], v140
	ds_read_b128 v[112:115], v140 offset:1024
	ds_read_b128 v[136:139], v140 offset:2048
	ds_read_b128 v[140:143], v140 offset:3072
	ds_read_b128 v[144:147], v156
	ds_read_b128 v[148:151], v156 offset:1024
	ds_read_b128 v[152:155], v156 offset:2048
	ds_read_b128 v[156:159], v156 offset:3072
	s_add_u32 s54, s54, 0x40000
	s_addc_u32 s55, s55, 0
	s_mov_b32 m0, s67
	v_lshl_add_u64 v[202:203], s[54:55], 0, v[218:219]
	ds_read_b128 v[160:163], v248 offset:32768
	ds_read_b128 v[164:167], v248 offset:33792
	ds_read_b128 v[168:171], v248 offset:34816
	ds_read_b128 v[172:175], v248 offset:35840
	ds_read_b128 v[176:179], v248 offset:36864
	ds_read_b128 v[180:183], v248 offset:37888
	ds_read_b128 v[184:187], v248 offset:38912
	ds_read_b128 v[188:191], v248 offset:39936
	global_load_lds_dwordx4 v[202:203], off
	v_lshl_add_u64 v[202:203], s[54:55], 0, v[214:215]
	s_mov_b32 m0, s90
	s_nop 0
	global_load_lds_dwordx4 v[202:203], off
	s_waitcnt lgkmcnt(0)
	s_barrier
	s_setprio 1
	s_waitcnt lgkmcnt(0)
	v_mfma_f32_16x16x32_bf16 v[132:135], v[104:107], v[160:163], v[132:135]
	v_mfma_f32_16x16x32_bf16 v[128:131], v[136:139], v[160:163], v[128:131]
	v_mfma_f32_16x16x32_bf16 v[116:119], v[104:107], v[168:171], v[116:119]
	v_mfma_f32_16x16x32_bf16 v[108:111], v[136:139], v[168:171], v[108:111]
	v_mfma_f32_16x16x32_bf16 v[96:99], v[104:107], v[176:179], v[96:99]
	v_mfma_f32_16x16x32_bf16 v[88:91], v[136:139], v[176:179], v[88:91]
	v_mfma_f32_16x16x32_bf16 v[80:83], v[104:107], v[184:187], v[80:83]
	v_mfma_f32_16x16x32_bf16 v[72:75], v[136:139], v[184:187], v[72:75]
	v_mfma_f32_16x16x32_bf16 v[132:135], v[112:115], v[164:167], v[132:135]
	v_mfma_f32_16x16x32_bf16 v[128:131], v[140:143], v[164:167], v[128:131]
	v_mfma_f32_16x16x32_bf16 v[116:119], v[112:115], v[172:175], v[116:119]
	v_mfma_f32_16x16x32_bf16 v[108:111], v[140:143], v[172:175], v[108:111]
	v_mfma_f32_16x16x32_bf16 v[96:99], v[112:115], v[180:183], v[96:99]
	v_mfma_f32_16x16x32_bf16 v[88:91], v[140:143], v[180:183], v[88:91]
	v_mfma_f32_16x16x32_bf16 v[80:83], v[112:115], v[188:191], v[80:83]
	v_mfma_f32_16x16x32_bf16 v[72:75], v[140:143], v[188:191], v[72:75]
	s_setprio 0
	s_setprio 1
	v_mfma_f32_16x16x32_bf16 v[124:127], v[144:147], v[160:163], v[124:127]
	v_mfma_f32_16x16x32_bf16 v[120:123], v[152:155], v[160:163], v[120:123]
	v_mfma_f32_16x16x32_bf16 v[100:103], v[144:147], v[168:171], v[100:103]
	v_mfma_f32_16x16x32_bf16 v[92:95], v[152:155], v[168:171], v[92:95]
	v_mfma_f32_16x16x32_bf16 v[84:87], v[144:147], v[176:179], v[84:87]
	v_mfma_f32_16x16x32_bf16 v[76:79], v[152:155], v[176:179], v[76:79]
	v_mfma_f32_16x16x32_bf16 v[68:71], v[144:147], v[184:187], v[68:71]
	v_mfma_f32_16x16x32_bf16 v[64:67], v[152:155], v[184:187], v[64:67]
	v_mfma_f32_16x16x32_bf16 v[124:127], v[148:151], v[164:167], v[124:127]
	v_mfma_f32_16x16x32_bf16 v[120:123], v[156:159], v[164:167], v[120:123]
	v_mfma_f32_16x16x32_bf16 v[100:103], v[148:151], v[172:175], v[100:103]
	v_mfma_f32_16x16x32_bf16 v[92:95], v[156:159], v[172:175], v[92:95]
	v_mfma_f32_16x16x32_bf16 v[84:87], v[148:151], v[180:183], v[84:87]
	v_mfma_f32_16x16x32_bf16 v[76:79], v[156:159], v[180:183], v[76:79]
	v_mfma_f32_16x16x32_bf16 v[68:71], v[148:151], v[188:191], v[68:71]
	v_mfma_f32_16x16x32_bf16 v[64:67], v[156:159], v[188:191], v[64:67]
	s_setprio 0
	s_barrier
; #define PG8_STAGE(bufoff, gbase, voff) do { _Pragma("unroll") for (int _i = 0; _i < 2; ++_i) \
;         __builtin_amdgcn_global_load_lds((const unsigned*)((const char*)(gbase) + (voff)[_i]), (LAS unsigned*)(lds + (bufoff) + ldsw + _i * 8192), 16, 0, 0); } while (0)
; #define PG8_LDA(dst, b, h) do { _Pragma("unroll") for (int m = 0; m < 4; ++m) _Pragma("unroll") for (int k = 0; k < 2; ++k) dst[m][k] = *(const LAS bf16x8*)(lds + PG8_SA(b, h) + aoff + m * 2048 + k * 1024); } while (0)
; #define PG8_LDB(dst, b, h) do { _Pragma("unroll") for (int n = 0; n < 2; ++n) _Pragma("unroll") for (int k = 0; k < 2; ++k) dst[n][k] = *(const LAS bf16x8*)(lds + PG8_SB(b, h) + boff + n * 2048 + k * 1024); } while (0)
; #define PG8_MMA(ai, bj, At, Bt) do { __builtin_amdgcn_s_setprio(1); _Pragma("unroll") for (int m = 0; m < 4; ++m) _Pragma("unroll") for (int n = 0; n < 2; ++n) _Pragma("unroll") for (int k = 0; k < 2; ++k) \
;         acc[ai][bj][m][n] = __builtin_amdgcn_mfma_f32_16x16x32_bf16(Bt[n][k], At[m][k], acc[ai][bj][m][n], 0, 0, 0); __builtin_amdgcn_s_setprio(0); } while (0)
; #define PG8_WAIT_V(n) asm volatile("s_waitcnt vmcnt(" #n ")" ::: "memory")
; #define PG8_WAIT_L(n) asm volatile("s_waitcnt lgkmcnt(" #n ")" ::: "memory")
; #define PG8_BAR __builtin_amdgcn_s_barrier()
; #define PG8_SCHED __builtin_amdgcn_sched_barrier(0)
; template <class Epi, class Sched, bool ALIGN_EPI>
; __device__ __forceinline__ void gemm_phase(LAS unsigned char* lds, const Gemm g, const Sched& S, const Epi& E) {
;     ...
;             PG8_LDB(B0, 0, 0); PG8_LDB(B1, 0, 1); PG8_SCHED; PG8_LDA(At, 0, 0); PG8_STAGE(PG8_SA(1, 1), a1 + hstepA, voffA);
;             PG8_WAIT_V(8); PG8_WAIT_L(0); PG8_BAR; PG8_MMA(0, 0, At, B0); PG8_MMA(0, 1, At, B1); PG8_BAR; PG8_SCHED;
;     ...
;             PG8_LDA(At, 1, 1); PG8_STAGE(PG8_SB(1, 0), b3, voffB); PG8_STAGE(PG8_SB(1, 1), b3 + hstepB, voffB); PG8_STAGE(PG8_SA(1, 0), a3, voffA);
;             PG8_WAIT_V(8); PG8_WAIT_L(0); PG8_BAR; PG8_MMA(1, 0, At, B0); PG8_MMA(1, 1, At, B1); PG8_BAR; PG8_SCHED;
	s_add_i32 s52, s52, s50
	v_lshl_add_u64 v[194:195], v[194:195], 0, s[12:13]
	s_mov_b32 m0, s52
	ds_read_b128 v[160:163], v248 offset:49152
	ds_read_b128 v[164:167], v248 offset:50176
	ds_read_b128 v[168:171], v248 offset:51200
	ds_read_b128 v[172:175], v248 offset:52224
	ds_read_b128 v[176:179], v248 offset:53248
	ds_read_b128 v[180:183], v248 offset:54272
	ds_read_b128 v[184:187], v248 offset:55296
	ds_read_b128 v[188:191], v248 offset:56320
	global_load_lds_dwordx4 v[194:195], off
	s_add_i32 m0, s52, 0x2000
	s_add_u32 s46, s46, 0x40080
	v_lshl_add_u64 v[194:195], v[196:197], 0, s[12:13]
	s_addc_u32 s47, s47, 0
	s_add_i32 s52, s53, s50
	global_load_lds_dwordx4 v[194:195], off
	v_lshl_add_u64 v[194:195], s[46:47], 0, v[216:217]
	s_mov_b32 m0, s52
	s_nop 0
	global_load_lds_dwordx4 v[194:195], off
	v_lshl_add_u64 v[194:195], s[46:47], 0, v[212:213]
	s_add_i32 m0, s52, 0x2000
	s_nop 0
	global_load_lds_dwordx4 v[194:195], off
	v_lshl_add_u64 v[194:195], v[198:199], 0, s[12:13]
	s_mov_b32 m0, s66
	s_nop 0
	global_load_lds_dwordx4 v[194:195], off
	v_lshl_add_u64 v[194:195], v[200:201], 0, s[12:13]
	s_mov_b32 m0, s86
	s_nop 0
	global_load_lds_dwordx4 v[194:195], off
	s_waitcnt lgkmcnt(0)
	s_barrier
	s_setprio 1
	s_waitcnt lgkmcnt(0)
	v_mfma_f32_16x16x32_bf16 v[60:63], v[104:107], v[160:163], v[60:63]
	v_mfma_f32_16x16x32_bf16 v[56:59], v[136:139], v[160:163], v[56:59]
	v_mfma_f32_16x16x32_bf16 v[44:47], v[104:107], v[168:171], v[44:47]
	v_mfma_f32_16x16x32_bf16 v[40:43], v[136:139], v[168:171], v[40:43]
	v_mfma_f32_16x16x32_bf16 v[32:35], v[104:107], v[176:179], v[32:35]
	v_mfma_f32_16x16x32_bf16 v[24:27], v[136:139], v[176:179], v[24:27]
	v_mfma_f32_16x16x32_bf16 v[16:19], v[104:107], v[184:187], v[16:19]
	v_mfma_f32_16x16x32_bf16 v[8:11], v[136:139], v[184:187], v[8:11]
	v_mfma_f32_16x16x32_bf16 v[60:63], v[112:115], v[164:167], v[60:63]
	v_mfma_f32_16x16x32_bf16 v[56:59], v[140:143], v[164:167], v[56:59]
	v_mfma_f32_16x16x32_bf16 v[44:47], v[112:115], v[172:175], v[44:47]
	v_mfma_f32_16x16x32_bf16 v[40:43], v[140:143], v[172:175], v[40:43]
	v_mfma_f32_16x16x32_bf16 v[32:35], v[112:115], v[180:183], v[32:35]
	v_mfma_f32_16x16x32_bf16 v[24:27], v[140:143], v[180:183], v[24:27]
	v_mfma_f32_16x16x32_bf16 v[16:19], v[112:115], v[188:191], v[16:19]
	v_mfma_f32_16x16x32_bf16 v[8:11], v[140:143], v[188:191], v[8:11]
	s_setprio 0
	s_setprio 1
	v_mfma_f32_16x16x32_bf16 v[52:55], v[144:147], v[160:163], v[52:55]
	s_add_i32 s92, s92, 2
	v_mfma_f32_16x16x32_bf16 v[48:51], v[152:155], v[160:163], v[48:51]
	s_add_u32 s44, s44, 0x100
	v_mfma_f32_16x16x32_bf16 v[36:39], v[144:147], v[168:171], v[36:39]
	s_addc_u32 s45, s45, 0
	v_mfma_f32_16x16x32_bf16 v[28:31], v[152:155], v[168:171], v[28:31]
	s_add_u32 s64, s64, 0x100
	v_mfma_f32_16x16x32_bf16 v[20:23], v[144:147], v[176:179], v[20:23]
	s_addc_u32 s65, s65, 0
	v_mfma_f32_16x16x32_bf16 v[12:15], v[152:155], v[176:179], v[12:15]
	s_add_u32 s46, s44, 0xfffc0080
	v_mfma_f32_16x16x32_bf16 v[4:7], v[144:147], v[184:187], v[4:7]
	s_addc_u32 s47, s45, -1
	v_mfma_f32_16x16x32_bf16 v[0:3], v[152:155], v[184:187], v[0:3]
	s_add_i32 s52, 0, 0x10000
	v_mfma_f32_16x16x32_bf16 v[52:55], v[148:151], v[164:167], v[52:55]
	s_cmp_eq_u32 s92, 12
	v_mfma_f32_16x16x32_bf16 v[48:51], v[156:159], v[164:167], v[48:51]
	s_cselect_b32 s55, s56, s47
	v_mfma_f32_16x16x32_bf16 v[36:39], v[148:151], v[172:175], v[36:39]
	s_cselect_b32 s54, s57, s46
	v_mfma_f32_16x16x32_bf16 v[28:31], v[156:159], v[172:175], v[28:31]
	s_cselect_b32 s47, s59, s65
	v_mfma_f32_16x16x32_bf16 v[20:23], v[148:151], v[180:183], v[20:23]
	s_cselect_b32 s46, s63, s64
	v_mfma_f32_16x16x32_bf16 v[12:15], v[156:159], v[180:183], v[12:15]
	s_add_i32 s53, 0, 0x14000
	v_mfma_f32_16x16x32_bf16 v[4:7], v[148:151], v[188:191], v[4:7]
	s_cmp_gt_u32 s92, 13
	v_mfma_f32_16x16x32_bf16 v[0:3], v[156:159], v[188:191], v[0:3]
	s_waitcnt vmcnt(8)
	s_setprio 0
	s_barrier
	s_barrier
	s_branch .LBB0_316
.Ldc_pf_first:
	s_add_u32 s46, s44, 0xfffc0080
	s_addc_u32 s47, s45, -1
	s_add_i32 s52, 0, 0x10000
	s_cmp_eq_u32 s92, 12
	s_cselect_b32 s55, s56, s47
	s_cselect_b32 s54, s57, s46
	s_cselect_b32 s47, s59, s65
	s_cselect_b32 s46, s63, s64
	s_add_i32 s53, 0, 0x14000
	v_add_u32_e32 v140, s52, v247
	v_add_u32_e32 v156, s53, v247
	ds_read_b128 v[104:107], v140
	ds_read_b128 v[112:115], v140 offset:1024
	ds_read_b128 v[136:139], v140 offset:2048
	ds_read_b128 v[140:143], v140 offset:3072
	ds_read_b128 v[144:147], v156
	ds_read_b128 v[148:151], v156 offset:1024
	ds_read_b128 v[152:155], v156 offset:2048
	ds_read_b128 v[156:159], v156 offset:3072
	v_lshl_add_u64 v[194:195], s[44:45], 0, v[220:221]
	s_add_i32 m0, s48, 0xc000
	ds_read_b128 v[160:163], v248
	ds_read_b128 v[164:167], v248 offset:1024
	ds_read_b128 v[168:171], v248 offset:2048
	ds_read_b128 v[172:175], v248 offset:3072
	ds_read_b128 v[176:179], v248 offset:4096
	ds_read_b128 v[180:183], v248 offset:5120
	ds_read_b128 v[184:187], v248 offset:6144
	ds_read_b128 v[188:191], v248 offset:7168
	global_load_lds_dwordx4 v[194:195], off
	v_lshl_add_u64 v[194:195], s[44:45], 0, v[222:223]
	s_add_i32 m0, s48, 0xe000
	s_nop 0
	global_load_lds_dwordx4 v[194:195], off
	s_waitcnt vmcnt(8)
	s_waitcnt lgkmcnt(0)
	s_barrier
; #define PG8_STAGE(bufoff, gbase, voff) do { _Pragma("unroll") for (int _i = 0; _i < 2; ++_i) \
;         __builtin_amdgcn_global_load_lds((const unsigned*)((const char*)(gbase) + (voff)[_i]), (LAS unsigned*)(lds + (bufoff) + ldsw + _i * 8192), 16, 0, 0); } while (0)
; #define PG8_LDA(dst, b, h) do { _Pragma("unroll") for (int m = 0; m < 4; ++m) _Pragma("unroll") for (int k = 0; k < 2; ++k) dst[m][k] = *(const LAS bf16x8*)(lds + PG8_SA(b, h) + aoff + m * 2048 + k * 1024); } while (0)
; #define PG8_MMA(ai, bj, At, Bt) do { __builtin_amdgcn_s_setprio(1); _Pragma("unroll") for (int m = 0; m < 4; ++m) _Pragma("unroll") for (int n = 0; n < 2; ++n) _Pragma("unroll") for (int k = 0; k < 2; ++k) \
;         acc[ai][bj][m][n] = __builtin_amdgcn_mfma_f32_16x16x32_bf16(Bt[n][k], At[m][k], acc[ai][bj][m][n], 0, 0, 0); __builtin_amdgcn_s_setprio(0); } while (0)
; #define PG8_WAIT_V(n) asm volatile("s_waitcnt vmcnt(" #n ")" ::: "memory")
; #define PG8_WAIT_L(n) asm volatile("s_waitcnt lgkmcnt(" #n ")" ::: "memory")
; #define PG8_BAR __builtin_amdgcn_s_barrier()
; #define PG8_SCHED __builtin_amdgcn_sched_barrier(0)
; template <class Epi, class Sched, bool ALIGN_EPI>
; __device__ __forceinline__ void gemm_phase(LAS unsigned char* lds, const Gemm g, const Sched& S, const Epi& E) {
;     ...
;             PG8_WAIT_V(8); PG8_WAIT_L(0); PG8_BAR; PG8_MMA(0, 0, At, B0); PG8_MMA(0, 1, At, B1); PG8_BAR; PG8_SCHED;
;             PG8_LDA(At, 0, 1); PG8_STAGE(PG8_SB(0, 0), b2, voffB); PG8_STAGE(PG8_SB(0, 1), b2 + hstepB, voffB); PG8_STAGE(PG8_SA(0, 0), a2, voffA);
;             PG8_WAIT_V(8); PG8_WAIT_L(0); PG8_BAR; PG8_MMA(1, 0, At, B0); PG8_MMA(1, 1, At, B1); PG8_BAR; PG8_SCHED;
	s_setprio 1
	s_waitcnt lgkmcnt(0)
	v_mfma_f32_16x16x32_bf16 v[132:135], v[104:107], v[160:163], 0
	v_mfma_f32_16x16x32_bf16 v[128:131], v[136:139], v[160:163], 0
	v_mfma_f32_16x16x32_bf16 v[116:119], v[104:107], v[168:171], 0
	v_mfma_f32_16x16x32_bf16 v[108:111], v[136:139], v[168:171], 0
	v_mfma_f32_16x16x32_bf16 v[96:99], v[104:107], v[176:179], 0
	v_mfma_f32_16x16x32_bf16 v[88:91], v[136:139], v[176:179], 0
	v_mfma_f32_16x16x32_bf16 v[80:83], v[104:107], v[184:187], 0
	v_mfma_f32_16x16x32_bf16 v[72:75], v[136:139], v[184:187], 0
	v_mfma_f32_16x16x32_bf16 v[132:135], v[112:115], v[164:167], v[132:135]
	v_mfma_f32_16x16x32_bf16 v[128:131], v[140:143], v[164:167], v[128:131]
	v_mfma_f32_16x16x32_bf16 v[116:119], v[112:115], v[172:175], v[116:119]
	v_mfma_f32_16x16x32_bf16 v[108:111], v[140:143], v[172:175], v[108:111]
	v_mfma_f32_16x16x32_bf16 v[96:99], v[112:115], v[180:183], v[96:99]
	v_mfma_f32_16x16x32_bf16 v[88:91], v[140:143], v[180:183], v[88:91]
	v_mfma_f32_16x16x32_bf16 v[80:83], v[112:115], v[188:191], v[80:83]
	v_mfma_f32_16x16x32_bf16 v[72:75], v[140:143], v[188:191], v[72:75]
	s_setprio 0
	s_setprio 1
	v_mfma_f32_16x16x32_bf16 v[124:127], v[144:147], v[160:163], 0
	v_mfma_f32_16x16x32_bf16 v[120:123], v[152:155], v[160:163], 0
	v_mfma_f32_16x16x32_bf16 v[100:103], v[144:147], v[168:171], 0
	v_mfma_f32_16x16x32_bf16 v[92:95], v[152:155], v[168:171], 0
	v_mfma_f32_16x16x32_bf16 v[84:87], v[144:147], v[176:179], 0
	v_mfma_f32_16x16x32_bf16 v[76:79], v[152:155], v[176:179], 0
	v_mfma_f32_16x16x32_bf16 v[68:71], v[144:147], v[184:187], 0
	v_mfma_f32_16x16x32_bf16 v[64:67], v[152:155], v[184:187], 0
	v_mfma_f32_16x16x32_bf16 v[124:127], v[148:151], v[164:167], v[124:127]
	v_mfma_f32_16x16x32_bf16 v[120:123], v[156:159], v[164:167], v[120:123]
	v_mfma_f32_16x16x32_bf16 v[100:103], v[148:151], v[172:175], v[100:103]
	v_mfma_f32_16x16x32_bf16 v[92:95], v[156:159], v[172:175], v[92:95]
	v_mfma_f32_16x16x32_bf16 v[84:87], v[148:151], v[180:183], v[84:87]
	v_mfma_f32_16x16x32_bf16 v[76:79], v[156:159], v[180:183], v[76:79]
	v_mfma_f32_16x16x32_bf16 v[68:71], v[148:151], v[188:191], v[68:71]
	v_mfma_f32_16x16x32_bf16 v[64:67], v[156:159], v[188:191], v[64:67]
	s_setprio 0
	s_barrier
	s_add_i32 s52, s52, s50
	v_lshl_add_u64 v[194:195], s[46:47], 0, v[216:217]
	s_mov_b32 m0, s52
	ds_read_b128 v[160:163], v248 offset:16384
	ds_read_b128 v[164:167], v248 offset:17408
	ds_read_b128 v[168:171], v248 offset:18432
	ds_read_b128 v[172:175], v248 offset:19456
	ds_read_b128 v[176:179], v248 offset:20480
	ds_read_b128 v[180:183], v248 offset:21504
	ds_read_b128 v[184:187], v248 offset:22528
	ds_read_b128 v[188:191], v248 offset:23552
	global_load_lds_dwordx4 v[194:195], off
	s_add_i32 m0, s52, 0x2000
	s_add_u32 vcc_lo, s46, 0x40000
	v_lshl_add_u64 v[196:197], s[46:47], 0, v[212:213]
	s_addc_u32 vcc_hi, s47, 0
	s_add_i32 s52, s53, s50
	global_load_lds_dwordx4 v[196:197], off
	v_lshl_add_u64 v[198:199], vcc, 0, v[216:217]
	s_mov_b32 m0, s52
	v_lshl_add_u64 v[200:201], s[54:55], 0, v[214:215]
	global_load_lds_dwordx4 v[198:199], off
	v_lshl_add_u64 v[198:199], vcc, 0, v[212:213]
	s_add_i32 m0, s52, 0x2000
	s_nop 0
	global_load_lds_dwordx4 v[198:199], off
	v_lshl_add_u64 v[198:199], s[54:55], 0, v[218:219]
	s_mov_b32 m0, s48
	s_nop 0
	global_load_lds_dwordx4 v[198:199], off
	s_mov_b32 m0, s49
	s_nop 0
	global_load_lds_dwordx4 v[200:201], off
	s_waitcnt vmcnt(8)
	s_waitcnt lgkmcnt(0)
	s_barrier
	s_setprio 1
	s_waitcnt lgkmcnt(0)
	v_mfma_f32_16x16x32_bf16 v[60:63], v[104:107], v[160:163], 0
	v_mfma_f32_16x16x32_bf16 v[56:59], v[136:139], v[160:163], 0
	v_mfma_f32_16x16x32_bf16 v[44:47], v[104:107], v[168:171], 0
	v_mfma_f32_16x16x32_bf16 v[40:43], v[136:139], v[168:171], 0
	v_mfma_f32_16x16x32_bf16 v[32:35], v[104:107], v[176:179], 0
	v_mfma_f32_16x16x32_bf16 v[24:27], v[136:139], v[176:179], 0
	v_mfma_f32_16x16x32_bf16 v[16:19], v[104:107], v[184:187], 0
	v_mfma_f32_16x16x32_bf16 v[8:11], v[136:139], v[184:187], 0
	v_mfma_f32_16x16x32_bf16 v[60:63], v[112:115], v[164:167], v[60:63]
	v_mfma_f32_16x16x32_bf16 v[56:59], v[140:143], v[164:167], v[56:59]
	v_mfma_f32_16x16x32_bf16 v[44:47], v[112:115], v[172:175], v[44:47]
	v_mfma_f32_16x16x32_bf16 v[40:43], v[140:143], v[172:175], v[40:43]
	v_mfma_f32_16x16x32_bf16 v[32:35], v[112:115], v[180:183], v[32:35]
	v_mfma_f32_16x16x32_bf16 v[24:27], v[140:143], v[180:183], v[24:27]
	v_mfma_f32_16x16x32_bf16 v[16:19], v[112:115], v[188:191], v[16:19]
	v_mfma_f32_16x16x32_bf16 v[8:11], v[140:143], v[188:191], v[8:11]
	s_setprio 0
	s_setprio 1
	v_mfma_f32_16x16x32_bf16 v[52:55], v[144:147], v[160:163], 0
	v_mfma_f32_16x16x32_bf16 v[48:51], v[152:155], v[160:163], 0
	v_mfma_f32_16x16x32_bf16 v[36:39], v[144:147], v[168:171], 0
	v_mfma_f32_16x16x32_bf16 v[28:31], v[152:155], v[168:171], 0
	v_mfma_f32_16x16x32_bf16 v[20:23], v[144:147], v[176:179], 0
	v_mfma_f32_16x16x32_bf16 v[12:15], v[152:155], v[176:179], 0
	v_mfma_f32_16x16x32_bf16 v[4:7], v[144:147], v[184:187], 0
	v_mfma_f32_16x16x32_bf16 v[0:3], v[152:155], v[184:187], 0
	v_mfma_f32_16x16x32_bf16 v[52:55], v[148:151], v[164:167], v[52:55]
	v_mfma_f32_16x16x32_bf16 v[48:51], v[156:159], v[164:167], v[48:51]
	v_mfma_f32_16x16x32_bf16 v[36:39], v[148:151], v[172:175], v[36:39]
	v_mfma_f32_16x16x32_bf16 v[28:31], v[156:159], v[172:175], v[28:31]
	v_mfma_f32_16x16x32_bf16 v[20:23], v[148:151], v[180:183], v[20:23]
	v_mfma_f32_16x16x32_bf16 v[12:15], v[156:159], v[180:183], v[12:15]
	v_mfma_f32_16x16x32_bf16 v[4:7], v[148:151], v[188:191], v[4:7]
	v_mfma_f32_16x16x32_bf16 v[0:3], v[156:159], v[188:191], v[0:3]
	s_setprio 0
	s_barrier
; #define PG8_STAGE(bufoff, gbase, voff) do { _Pragma("unroll") for (int _i = 0; _i < 2; ++_i) \
;         __builtin_amdgcn_global_load_lds((const unsigned*)((const char*)(gbase) + (voff)[_i]), (LAS unsigned*)(lds + (bufoff) + ldsw + _i * 8192), 16, 0, 0); } while (0)
; #define PG8_LDA(dst, b, h) do { _Pragma("unroll") for (int m = 0; m < 4; ++m) _Pragma("unroll") for (int k = 0; k < 2; ++k) dst[m][k] = *(const LAS bf16x8*)(lds + PG8_SA(b, h) + aoff + m * 2048 + k * 1024); } while (0)
; #define PG8_LDB(dst, b, h) do { _Pragma("unroll") for (int n = 0; n < 2; ++n) _Pragma("unroll") for (int k = 0; k < 2; ++k) dst[n][k] = *(const LAS bf16x8*)(lds + PG8_SB(b, h) + boff + n * 2048 + k * 1024); } while (0)
; #define PG8_MMA(ai, bj, At, Bt) do { __builtin_amdgcn_s_setprio(1); _Pragma("unroll") for (int m = 0; m < 4; ++m) _Pragma("unroll") for (int n = 0; n < 2; ++n) _Pragma("unroll") for (int k = 0; k < 2; ++k) \
;         acc[ai][bj][m][n] = __builtin_amdgcn_mfma_f32_16x16x32_bf16(Bt[n][k], At[m][k], acc[ai][bj][m][n], 0, 0, 0); __builtin_amdgcn_s_setprio(0); } while (0)
; #define PG8_WAIT_V(n) asm volatile("s_waitcnt vmcnt(" #n ")" ::: "memory")
; #define PG8_WAIT_L(n) asm volatile("s_waitcnt lgkmcnt(" #n ")" ::: "memory")
; #define PG8_BAR __builtin_amdgcn_s_barrier()
; #define PG8_SCHED __builtin_amdgcn_sched_barrier(0)
; template <class Epi, class Sched, bool ALIGN_EPI>
; __device__ __forceinline__ void gemm_phase(LAS unsigned char* lds, const Gemm g, const Sched& S, const Epi& E) {
;     ...
;             PG8_LDB(B0, 1, 0); PG8_LDB(B1, 1, 1); PG8_SCHED; PG8_LDA(At, 1, 0); PG8_STAGE(PG8_SA(0, 1), a2 + hstepA, voffA);
;             PG8_WAIT_V(8); PG8_WAIT_L(0); PG8_BAR; PG8_MMA(0, 0, At, B0); PG8_MMA(0, 1, At, B1); PG8_BAR; PG8_SCHED;
	s_add_i32 s52, 0, 0x18000
	s_add_i32 s53, 0, 0x1c000
	v_add_u32_e32 v140, s52, v247
	v_add_u32_e32 v156, s53, v247
	ds_read_b128 v[104:107], v140
	ds_read_b128 v[112:115], v140 offset:1024
	ds_read_b128 v[136:139], v140 offset:2048
	ds_read_b128 v[140:143], v140 offset:3072
	ds_read_b128 v[144:147], v156
	ds_read_b128 v[148:151], v156 offset:1024
	ds_read_b128 v[152:155], v156 offset:2048
	ds_read_b128 v[156:159], v156 offset:3072
	s_add_u32 s54, s54, 0x40000
	s_addc_u32 s55, s55, 0
	s_mov_b32 m0, s67
	v_lshl_add_u64 v[202:203], s[54:55], 0, v[218:219]
	ds_read_b128 v[160:163], v248 offset:32768
	ds_read_b128 v[164:167], v248 offset:33792
	ds_read_b128 v[168:171], v248 offset:34816
	ds_read_b128 v[172:175], v248 offset:35840
	ds_read_b128 v[176:179], v248 offset:36864
	ds_read_b128 v[180:183], v248 offset:37888
	ds_read_b128 v[184:187], v248 offset:38912
	ds_read_b128 v[188:191], v248 offset:39936
	global_load_lds_dwordx4 v[202:203], off
	v_lshl_add_u64 v[202:203], s[54:55], 0, v[214:215]
	s_mov_b32 m0, s90
	s_nop 0
	global_load_lds_dwordx4 v[202:203], off
	s_waitcnt vmcnt(8)
	s_waitcnt lgkmcnt(0)
	s_barrier
	s_setprio 1
	s_waitcnt lgkmcnt(0)
	v_mfma_f32_16x16x32_bf16 v[132:135], v[104:107], v[160:163], v[132:135]
	v_mfma_f32_16x16x32_bf16 v[128:131], v[136:139], v[160:163], v[128:131]
	v_mfma_f32_16x16x32_bf16 v[116:119], v[104:107], v[168:171], v[116:119]
	v_mfma_f32_16x16x32_bf16 v[108:111], v[136:139], v[168:171], v[108:111]
	v_mfma_f32_16x16x32_bf16 v[96:99], v[104:107], v[176:179], v[96:99]
	v_mfma_f32_16x16x32_bf16 v[88:91], v[136:139], v[176:179], v[88:91]
	v_mfma_f32_16x16x32_bf16 v[80:83], v[104:107], v[184:187], v[80:83]
	v_mfma_f32_16x16x32_bf16 v[72:75], v[136:139], v[184:187], v[72:75]
	v_mfma_f32_16x16x32_bf16 v[132:135], v[112:115], v[164:167], v[132:135]
	v_mfma_f32_16x16x32_bf16 v[128:131], v[140:143], v[164:167], v[128:131]
	v_mfma_f32_16x16x32_bf16 v[116:119], v[112:115], v[172:175], v[116:119]
	v_mfma_f32_16x16x32_bf16 v[108:111], v[140:143], v[172:175], v[108:111]
	v_mfma_f32_16x16x32_bf16 v[96:99], v[112:115], v[180:183], v[96:99]
	v_mfma_f32_16x16x32_bf16 v[88:91], v[140:143], v[180:183], v[88:91]
	v_mfma_f32_16x16x32_bf16 v[80:83], v[112:115], v[188:191], v[80:83]
	v_mfma_f32_16x16x32_bf16 v[72:75], v[140:143], v[188:191], v[72:75]
	s_setprio 0
	s_setprio 1
	v_mfma_f32_16x16x32_bf16 v[124:127], v[144:147], v[160:163], v[124:127]
	v_mfma_f32_16x16x32_bf16 v[120:123], v[152:155], v[160:163], v[120:123]
	v_mfma_f32_16x16x32_bf16 v[100:103], v[144:147], v[168:171], v[100:103]
	v_mfma_f32_16x16x32_bf16 v[92:95], v[152:155], v[168:171], v[92:95]
	v_mfma_f32_16x16x32_bf16 v[84:87], v[144:147], v[176:179], v[84:87]
	v_mfma_f32_16x16x32_bf16 v[76:79], v[152:155], v[176:179], v[76:79]
	v_mfma_f32_16x16x32_bf16 v[68:71], v[144:147], v[184:187], v[68:71]
	v_mfma_f32_16x16x32_bf16 v[64:67], v[152:155], v[184:187], v[64:67]
	v_mfma_f32_16x16x32_bf16 v[124:127], v[148:151], v[164:167], v[124:127]
	v_mfma_f32_16x16x32_bf16 v[120:123], v[156:159], v[164:167], v[120:123]
	v_mfma_f32_16x16x32_bf16 v[100:103], v[148:151], v[172:175], v[100:103]
	v_mfma_f32_16x16x32_bf16 v[92:95], v[156:159], v[172:175], v[92:95]
	v_mfma_f32_16x16x32_bf16 v[84:87], v[148:151], v[180:183], v[84:87]
	v_mfma_f32_16x16x32_bf16 v[76:79], v[156:159], v[180:183], v[76:79]
	v_mfma_f32_16x16x32_bf16 v[68:71], v[148:151], v[188:191], v[68:71]
	v_mfma_f32_16x16x32_bf16 v[64:67], v[156:159], v[188:191], v[64:67]
	s_setprio 0
	s_barrier
; #define PG8_STAGE(bufoff, gbase, voff) do { _Pragma("unroll") for (int _i = 0; _i < 2; ++_i) \
;         __builtin_amdgcn_global_load_lds((const unsigned*)((const char*)(gbase) + (voff)[_i]), (LAS unsigned*)(lds + (bufoff) + ldsw + _i * 8192), 16, 0, 0); } while (0)
; #define PG8_LDA(dst, b, h) do { _Pragma("unroll") for (int m = 0; m < 4; ++m) _Pragma("unroll") for (int k = 0; k < 2; ++k) dst[m][k] = *(const LAS bf16x8*)(lds + PG8_SA(b, h) + aoff + m * 2048 + k * 1024); } while (0)
; #define PG8_MMA(ai, bj, At, Bt) do { __builtin_amdgcn_s_setprio(1); _Pragma("unroll") for (int m = 0; m < 4; ++m) _Pragma("unroll") for (int n = 0; n < 2; ++n) _Pragma("unroll") for (int k = 0; k < 2; ++k) \
;         acc[ai][bj][m][n] = __builtin_amdgcn_mfma_f32_16x16x32_bf16(Bt[n][k], At[m][k], acc[ai][bj][m][n], 0, 0, 0); __builtin_amdgcn_s_setprio(0); } while (0)
; #define PG8_WAIT_V(n) asm volatile("s_waitcnt vmcnt(" #n ")" ::: "memory")
; #define PG8_WAIT_L(n) asm volatile("s_waitcnt lgkmcnt(" #n ")" ::: "memory")
; #define PG8_BAR __builtin_amdgcn_s_barrier()
; #define PG8_SCHED __builtin_amdgcn_sched_barrier(0)
; template <class Epi, class Sched, bool ALIGN_EPI>
; __device__ __forceinline__ void gemm_phase(LAS unsigned char* lds, const Gemm g, const Sched& S, const Epi& E) {
;     ...
;         for (int t = 0; t < nt; t += 2) {
;             const bool last = (t == nt - 2);
;             const char* a1 = cA + (size_t)(t + 1) * kstep;
;             const char* a2 = last ? nA : cA + (size_t)(t + 2) * kstep; const char* b2 = last ? nB : cB + (size_t)(t + 2) * kstep;
;     ...
;             PG8_LDA(At, 1, 1); PG8_STAGE(PG8_SB(1, 0), b3, voffB); PG8_STAGE(PG8_SB(1, 1), b3 + hstepB, voffB); PG8_STAGE(PG8_SA(1, 0), a3, voffA);
;             PG8_WAIT_V(8); PG8_WAIT_L(0); PG8_BAR; PG8_MMA(1, 0, At, B0); PG8_MMA(1, 1, At, B1); PG8_BAR; PG8_SCHED;
	s_add_i32 s52, s52, s50
	v_lshl_add_u64 v[194:195], v[194:195], 0, s[12:13]
	s_mov_b32 m0, s52
	ds_read_b128 v[160:163], v248 offset:49152
	ds_read_b128 v[164:167], v248 offset:50176
	ds_read_b128 v[168:171], v248 offset:51200
	ds_read_b128 v[172:175], v248 offset:52224
	ds_read_b128 v[176:179], v248 offset:53248
	ds_read_b128 v[180:183], v248 offset:54272
	ds_read_b128 v[184:187], v248 offset:55296
	ds_read_b128 v[188:191], v248 offset:56320
	global_load_lds_dwordx4 v[194:195], off
	s_add_i32 m0, s52, 0x2000
	s_add_u32 s46, s46, 0x40080
	v_lshl_add_u64 v[194:195], v[196:197], 0, s[12:13]
	s_addc_u32 s47, s47, 0
	s_add_i32 s52, s53, s50
	global_load_lds_dwordx4 v[194:195], off
	v_lshl_add_u64 v[194:195], s[46:47], 0, v[216:217]
	s_mov_b32 m0, s52
	s_nop 0
	global_load_lds_dwordx4 v[194:195], off
	v_lshl_add_u64 v[194:195], s[46:47], 0, v[212:213]
	s_add_i32 m0, s52, 0x2000
	s_nop 0
	global_load_lds_dwordx4 v[194:195], off
	v_lshl_add_u64 v[194:195], v[198:199], 0, s[12:13]
	s_mov_b32 m0, s66
	s_nop 0
	global_load_lds_dwordx4 v[194:195], off
	v_lshl_add_u64 v[194:195], v[200:201], 0, s[12:13]
	s_mov_b32 m0, s86
	s_nop 0
	global_load_lds_dwordx4 v[194:195], off
	s_waitcnt vmcnt(8)
	s_waitcnt lgkmcnt(0)
	s_barrier
	s_setprio 1
	s_waitcnt lgkmcnt(0)
	v_mfma_f32_16x16x32_bf16 v[60:63], v[104:107], v[160:163], v[60:63]
	v_mfma_f32_16x16x32_bf16 v[56:59], v[136:139], v[160:163], v[56:59]
	v_mfma_f32_16x16x32_bf16 v[44:47], v[104:107], v[168:171], v[44:47]
	v_mfma_f32_16x16x32_bf16 v[40:43], v[136:139], v[168:171], v[40:43]
	v_mfma_f32_16x16x32_bf16 v[32:35], v[104:107], v[176:179], v[32:35]
	v_mfma_f32_16x16x32_bf16 v[24:27], v[136:139], v[176:179], v[24:27]
	v_mfma_f32_16x16x32_bf16 v[16:19], v[104:107], v[184:187], v[16:19]
	v_mfma_f32_16x16x32_bf16 v[8:11], v[136:139], v[184:187], v[8:11]
	v_mfma_f32_16x16x32_bf16 v[60:63], v[112:115], v[164:167], v[60:63]
	v_mfma_f32_16x16x32_bf16 v[56:59], v[140:143], v[164:167], v[56:59]
	v_mfma_f32_16x16x32_bf16 v[44:47], v[112:115], v[172:175], v[44:47]
	v_mfma_f32_16x16x32_bf16 v[40:43], v[140:143], v[172:175], v[40:43]
	v_mfma_f32_16x16x32_bf16 v[32:35], v[112:115], v[180:183], v[32:35]
	v_mfma_f32_16x16x32_bf16 v[24:27], v[140:143], v[180:183], v[24:27]
	v_mfma_f32_16x16x32_bf16 v[16:19], v[112:115], v[188:191], v[16:19]
	v_mfma_f32_16x16x32_bf16 v[8:11], v[140:143], v[188:191], v[8:11]
	s_setprio 0
	s_setprio 1
	v_mfma_f32_16x16x32_bf16 v[52:55], v[144:147], v[160:163], v[52:55]
	s_add_i32 s92, s92, 2
	v_mfma_f32_16x16x32_bf16 v[48:51], v[152:155], v[160:163], v[48:51]
	s_add_u32 s44, s44, 0x100
	v_mfma_f32_16x16x32_bf16 v[36:39], v[144:147], v[168:171], v[36:39]
	s_addc_u32 s45, s45, 0
	v_mfma_f32_16x16x32_bf16 v[28:31], v[152:155], v[168:171], v[28:31]
	s_add_u32 s64, s64, 0x100
	v_mfma_f32_16x16x32_bf16 v[20:23], v[144:147], v[176:179], v[20:23]
	s_addc_u32 s65, s65, 0
	v_mfma_f32_16x16x32_bf16 v[12:15], v[152:155], v[176:179], v[12:15]
	s_add_u32 s46, s44, 0xfffc0080
	v_mfma_f32_16x16x32_bf16 v[4:7], v[144:147], v[184:187], v[4:7]
	s_addc_u32 s47, s45, -1
	v_mfma_f32_16x16x32_bf16 v[0:3], v[152:155], v[184:187], v[0:3]
	s_add_i32 s52, 0, 0x10000
	v_mfma_f32_16x16x32_bf16 v[52:55], v[148:151], v[164:167], v[52:55]
	s_cmp_eq_u32 s92, 12
	v_mfma_f32_16x16x32_bf16 v[48:51], v[156:159], v[164:167], v[48:51]
	s_cselect_b32 s55, s56, s47
	v_mfma_f32_16x16x32_bf16 v[36:39], v[148:151], v[172:175], v[36:39]
	s_cselect_b32 s54, s57, s46
	v_mfma_f32_16x16x32_bf16 v[28:31], v[156:159], v[172:175], v[28:31]
	s_cselect_b32 s47, s59, s65
	v_mfma_f32_16x16x32_bf16 v[20:23], v[148:151], v[180:183], v[20:23]
	s_cselect_b32 s46, s63, s64
	v_mfma_f32_16x16x32_bf16 v[12:15], v[156:159], v[180:183], v[12:15]
	s_add_i32 s53, 0, 0x14000
	v_mfma_f32_16x16x32_bf16 v[4:7], v[148:151], v[188:191], v[4:7]
	s_cmp_gt_u32 s92, 13
	v_mfma_f32_16x16x32_bf16 v[0:3], v[156:159], v[188:191], v[0:3]
	s_setprio 0
	s_barrier

; #define LAS __attribute__((address_space(3)))
; #define PG8_STAGE(bufoff, gbase, voff) do { _Pragma("unroll") for (int _i = 0; _i < 2; ++_i) \
;         __builtin_amdgcn_global_load_lds((const unsigned*)((const char*)(gbase) + (voff)[_i]), (LAS unsigned*)(lds + (bufoff) + ldsw + _i * 8192), 16, 0, 0); } while (0)
; #define PG8_LDA(dst, b, h) do { _Pragma("unroll") for (int m = 0; m < 4; ++m) _Pragma("unroll") for (int k = 0; k < 2; ++k) dst[m][k] = *(const LAS bf16x8*)(lds + PG8_SA(b, h) + aoff + m * 2048 + k * 1024); } while (0)
; #define PG8_LDB(dst, b, h) do { _Pragma("unroll") for (int n = 0; n < 2; ++n) _Pragma("unroll") for (int k = 0; k < 2; ++k) dst[n][k] = *(const LAS bf16x8*)(lds + PG8_SB(b, h) + boff + n * 2048 + k * 1024); } while (0)
; #define PG8_SCHED __builtin_amdgcn_sched_barrier(0)
; template <class Epi, class Sched, bool ALIGN_EPI>
; __device__ __forceinline__ void gemm_phase(LAS unsigned char* lds, const Gemm g, const Sched& S, const Epi& E) {
;     ...
;             PG8_LDB(B0, 0, 0); PG8_LDB(B1, 0, 1); PG8_SCHED; PG8_LDA(At, 0, 0); PG8_STAGE(PG8_SA(1, 1), a1 + hstepA, voffA);
;     __device__ __forceinline__ void operator()(const f32x4 (&acc)[2][2][4][2], const Unit& u, int wr, int wc, int fr, int fq) const {
;         const int b = u.pm >> 3, col0 = u.pn * 256 + wc * 32 + 8 * fq;
;         { const int t = (wr * 4 + wc) * 64 + fq * 16 + fr;
;           if (t < 64) ((LAS f32x4*)gl)[t] = *(const f32x4*)(gate + (size_t)b * gate_ld + u.pn * 256 + 4 * t);
;           else if (t < 128 && gmn) ((LAS f32x4*)gl)[t] = *(const f32x4*)(gmn + (size_t)b * DM + u.pn * 256 + 4 * (t - 64));
;           asm volatile("s_waitcnt vmcnt(0) lgkmcnt(0)" ::: "memory"); __builtin_amdgcn_s_barrier(); asm volatile("" ::: "memory"); }
.LBB0_319:
	s_add_u32 vcc_lo, s57, 0x40080
	s_addc_u32 vcc_hi, s56, 0
	v_lshl_add_u64 v[194:195], vcc, 0, v[220:221]
	s_add_i32 m0, s48, 0xc000
	s_nop 0
	global_load_lds_dwordx4 v[194:195], off
	v_lshl_add_u64 v[194:195], vcc, 0, v[222:223]
	s_add_i32 m0, s48, 0xe000
	s_nop 0
	global_load_lds_dwordx4 v[194:195], off
	s_mul_i32 s100, s40, 36
	s_add_i32 s100, s100, 0x24000
	s_cmp_eq_u32 s40, 0x1c0
	s_cselect_b32 s100, 0x20c00, s100
	s_lshl_b32 s101, s40, 4
	s_add_i32 s101, s101, 0x21800
	v_lshrrev_b32_e32 v210, 3, v242
	v_and_b32_e32 v246, 7, v242
	v_mul_u32_u24_e32 v210, 0x90, v210
	v_lshl_add_u32 v210, v246, 4, v210
	v_add_u32_e32 v210, s100, v210
	v_mul_u32_u24_e32 v208, 0x90, v211
	v_lshl_add_u32 v208, v207, 5, v208
	v_add_u32_e32 v208, s100, v208
	v_lshrrev_b32_e32 v252, 3, v242
	v_sub_u32_e32 v252, v252, v211
	v_lshlrev_b32_e32 v252, 12, v252
	v_lshl_add_u32 v246, v246, 4, v252
	v_lshlrev_b32_e32 v252, 5, v207
	v_sub_u32_e32 v246, v246, v252
	v_lshl_add_u32 v252, v242, 2, s101
	ds_write_b32 v252, v216
	ds_write_b32 v252, v218 offset:256
	ds_write_b32 v252, v220 offset:512
	ds_write_b32 v252, v222 offset:768
	s_add_u32 s100, s6, 0x8000
	s_addc_u32 s101, s7, 0
	v_and_b32_e32 v206, 3, v242
	v_lshrrev_b32_e32 v204, 2, v242
	v_lshl_add_u32 v205, v206, 4, v204
	v_sub_u32_e32 v204, v204, v211
	v_sub_u32_e32 v206, v206, v207
	v_lshlrev_b32_e32 v204, 11, v204
	v_lshl_add_u32 v204, v206, 4, v204
	v_lshlrev_b32_e32 v206, 2, v205
	v_ashrrev_i32_e32 v205, 31, v204
	v_mov_b32_e32 v106, v211
	v_mov_b32_e32 v250, v207
	s_ashr_i32 s46, s77, 3
	v_lshlrev_b32_e32 v104, 4, v250
	v_add3_u32 v107, s40, v106, v104
	s_lshl_b32 s44, s76, 8
	v_cmp_lt_i32_e32 vcc, 63, v107
	s_mov_b64 s[56:57], 0
	s_and_saveexec_b64 s[54:55], vcc
	s_xor_b64 s[54:55], exec, s[54:55]
	s_movk_i32 s63, 0x5ff
	s_cbranch_execnz .LBB0_368
	s_andn2_saveexec_b64 s[54:55], s[54:55]
	s_cbranch_execnz .LBB0_371

; __global__ void __launch_bounds__(512, 2) fwd_kernel(Args args) {
;     ...
;     for (int ph = lo; ph < hi; ++ph) {
.Ltramp_8:
	s_branch .LBB0_8
.Ltramp_661:
	s_branch .LBB0_661
